# DPP/permlane16+32_swap wave reductions replace ds_bpermute xor-butterflies (bit-exact) in epilogues, samp_fin, gla_norm, final
# speedup vs baseline: 1.0034x; 1.0034x over previous
; __device__ __forceinline__ void rows_rstd(const float* SS, const Unit& u, int wr, int fr, int fq, float (&rs)[2][4]) {
;     if (u.pm < 32) { const float* RSTD = (const float*)((const char*)SS + SS_TO_RSTD);
; #pragma unroll
;         for (int ai = 0; ai < 2; ++ai)
; #pragma unroll
;             for (int m = 0; m < 4; ++m) rs[ai][m] = RSTD[u.pm * BM + ai * HALF + wr * 64 + m * 16 + fr];
;     } else {
; #pragma unroll
;         for (int ai = 0; ai < 2; ++ai)
; #pragma unroll
;             for (int m = 0; m < 4; ++m) {
;                 const int row = u.pm * BM + ai * HALF + wr * 64 + m * 16 + fr; float s = 0.f;
; #pragma unroll
;                 for (int j = 0; j < 8; ++j) s += SS[(size_t)(fq * 8 + j) * MPAD + row];
;                 s += __shfl_xor(s, 16); s += __shfl_xor(s, 32);
;                 rs[ai][m] = 1.0f / sqrtf(s * (1.0f / 2048.0f) + RMS_EPS);
;             }
.LBB0_234:
	s_lshl_b32 s6, s76, 8
	v_mov_b32_e32 v140, v159
	v_mov_b32_e32 v141, v161
	s_add_i32 s6, s6, s70
	s_cmp_lt_i32 s76, 32
	v_add_u32_e32 v156, s6, v141
	v_lshlrev_b32_e32 v154, 3, v140
	v_add_u32_e32 v152, 16, v156
	v_add_u32_e32 v150, 32, v156
	v_add_u32_e32 v148, 48, v156
	v_add_u32_e32 v146, 0x80, v156
	v_add_u32_e32 v144, 0x90, v156
	v_add_u32_e32 v142, 0xa0, v156
	s_mov_b64 s[6:7], -1
	v_ashrrev_i32_e32 v157, 31, v156
	v_ashrrev_i32_e32 v155, 31, v154
	v_ashrrev_i32_e32 v153, 31, v152
	v_ashrrev_i32_e32 v151, 31, v150
	v_ashrrev_i32_e32 v149, 31, v148
	v_ashrrev_i32_e32 v147, 31, v146
	v_ashrrev_i32_e32 v145, 31, v144
	v_ashrrev_i32_e32 v143, 31, v142
	v_add_u32_e32 v140, 0xb0, v156
	s_cbranch_scc1 .LBB0_236
	v_and_b32_e32 v158, 64, v219
	v_xor_b32_e32 v141, 16, v219
	v_add_u32_e32 v158, 64, v158
	v_cmp_lt_i32_e32 vcc, v141, v158
	v_lshl_add_u64 v[194:195], v[156:157], 2, s[14:15]
	v_mad_i64_i32 v[170:171], s[6:7], v154, s46, v[194:195]
	v_cndmask_b32_e32 v141, v219, v141, vcc
	v_lshlrev_b32_e32 v169, 2, v141
	v_xor_b32_e32 v141, 32, v219
	v_cmp_lt_i32_e32 vcc, v141, v158
	s_nop 1
	v_cndmask_b32_e32 v141, v219, v141, vcc
	v_lshlrev_b32_e32 v167, 2, v141
	global_load_dword v208, v[170:171], off
	v_or_b32_e32 v171, 1, v154
	v_mad_i64_i32 v[172:173], s[6:7], v171, s46, v[194:195]
	global_load_dword v209, v[172:173], off
	v_or_b32_e32 v172, 2, v154
	v_mad_i64_i32 v[174:175], s[6:7], v172, s46, v[194:195]
	v_or_b32_e32 v173, 3, v154
	global_load_dword v210, v[174:175], off
	v_mad_i64_i32 v[174:175], s[6:7], v173, s46, v[194:195]
	global_load_dword v211, v[174:175], off
	v_or_b32_e32 v174, 4, v154
	v_mad_i64_i32 v[176:177], s[6:7], v174, s46, v[194:195]
	v_or_b32_e32 v175, 5, v154
	global_load_dword v212, v[176:177], off
	v_mad_i64_i32 v[176:177], s[6:7], v175, s46, v[194:195]
	global_load_dword v213, v[176:177], off
	v_or_b32_e32 v176, 6, v154
	v_mad_i64_i32 v[196:197], s[6:7], v176, s46, v[194:195]
	v_or_b32_e32 v177, 7, v154
	v_mad_i64_i32 v[194:195], s[6:7], v177, s46, v[194:195]
	global_load_dword v214, v[196:197], off
	global_load_dword v215, v[194:195], off
	v_lshl_add_u64 v[194:195], v[152:153], 2, s[14:15]
	s_waitcnt vmcnt(0)
	v_add_f32_e32 v141, 0, v208
	v_add_f32_e32 v141, v141, v209
	v_add_f32_e32 v141, v141, v210
	v_add_f32_e32 v141, v141, v211
	v_add_f32_e32 v141, v141, v212
	v_add_f32_e32 v141, v141, v213
	v_add_f32_e32 v141, v141, v214
	v_add_f32_e32 v141, v141, v215
	v_mov_b32_e32 v158, v141
	v_mov_b32_e32 v216, v141
	s_nop 1
	v_permlane16_swap_b32_e32 v158, v216
	s_waitcnt lgkmcnt(0)
	v_add_f32_e32 v141, v158, v216
	v_mov_b32_e32 v158, v141
	v_mov_b32_e32 v216, v141
	s_nop 1
	v_permlane32_swap_b32_e32 v158, v216
	s_waitcnt lgkmcnt(0)
	v_add_f32_e32 v141, v158, v216
	v_fmamk_f32 v141, v141, 0x3a000000, v220
	v_cmp_gt_f32_e32 vcc, s43, v141
	v_mul_f32_e32 v158, 0x4f800000, v141
	s_nop 0
	v_cndmask_b32_e32 v141, v141, v158, vcc
	v_sqrt_f32_e32 v158, v141
	s_nop 0
	v_add_u32_e32 v160, -1, v158
	v_fma_f32 v162, -v160, v158, v141
	v_cmp_ge_f32_e64 s[6:7], 0, v162
	v_add_u32_e32 v162, 1, v158
	s_nop 0
	v_cndmask_b32_e64 v160, v158, v160, s[6:7]
	v_fma_f32 v158, -v162, v158, v141
	v_cmp_lt_f32_e64 s[6:7], 0, v158
	s_nop 1
	v_cndmask_b32_e64 v158, v160, v162, s[6:7]
	v_mul_f32_e32 v160, 0x37800000, v158
	v_cndmask_b32_e32 v158, v158, v160, vcc
	v_cmp_class_f32_e32 vcc, v141, v221
	v_mad_i64_i32 v[196:197], s[6:7], v154, s46, v[194:195]
	s_nop 0
	v_cndmask_b32_e32 v141, v158, v141, vcc
	v_div_scale_f32 v158, s[6:7], v141, v141, 1.0
	v_rcp_f32_e32 v160, v158
	s_nop 0
	v_fma_f32 v162, -v158, v160, 1.0
	v_fmac_f32_e32 v160, v162, v160
	v_div_scale_f32 v162, vcc, 1.0, v141, 1.0
	v_mul_f32_e32 v164, v162, v160
	v_fma_f32 v166, -v158, v164, v162
	v_fmac_f32_e32 v164, v166, v160
	v_fma_f32 v158, -v158, v164, v162
	v_div_fmas_f32 v158, v158, v160, v164
	v_div_fixup_f32 v158, v158, v141, 1.0
	global_load_dword v208, v[196:197], off
	v_mad_i64_i32 v[196:197], s[6:7], v171, s46, v[194:195]
	global_load_dword v209, v[196:197], off
	v_mad_i64_i32 v[196:197], s[6:7], v172, s46, v[194:195]
	global_load_dword v210, v[196:197], off
	v_mad_i64_i32 v[196:197], s[6:7], v173, s46, v[194:195]
	global_load_dword v211, v[196:197], off
	v_mad_i64_i32 v[196:197], s[6:7], v174, s46, v[194:195]
	global_load_dword v212, v[196:197], off
	v_mad_i64_i32 v[196:197], s[6:7], v175, s46, v[194:195]
	global_load_dword v213, v[196:197], off
	v_mad_i64_i32 v[196:197], s[6:7], v176, s46, v[194:195]
	v_mad_i64_i32 v[194:195], s[6:7], v177, s46, v[194:195]
	global_load_dword v214, v[196:197], off
	global_load_dword v215, v[194:195], off
	v_lshl_add_u64 v[194:195], v[150:151], 2, s[14:15]
	s_waitcnt vmcnt(0)
	v_add_f32_e32 v141, 0, v208
	v_add_f32_e32 v141, v141, v209
	v_add_f32_e32 v141, v141, v210
	v_add_f32_e32 v141, v141, v211
	v_add_f32_e32 v141, v141, v212
	v_add_f32_e32 v141, v141, v213
	v_add_f32_e32 v141, v141, v214
	v_add_f32_e32 v141, v141, v215
	v_mov_b32_e32 v160, v141
	v_mov_b32_e32 v216, v141
	s_nop 1
	v_permlane16_swap_b32_e32 v160, v216
	s_waitcnt lgkmcnt(0)
	v_add_f32_e32 v141, v160, v216
	v_mov_b32_e32 v160, v141
	v_mov_b32_e32 v216, v141
	s_nop 1
	v_permlane32_swap_b32_e32 v160, v216
	s_waitcnt lgkmcnt(0)
; __device__ __forceinline__ void rows_rstd(const float* SS, const Unit& u, int wr, int fr, int fq, float (&rs)[2][4]) {
;     ...
;             for (int m = 0; m < 4; ++m) {
;                 const int row = u.pm * BM + ai * HALF + wr * 64 + m * 16 + fr; float s = 0.f;
; #pragma unroll
;                 for (int j = 0; j < 8; ++j) s += SS[(size_t)(fq * 8 + j) * MPAD + row];
;                 s += __shfl_xor(s, 16); s += __shfl_xor(s, 32);
;                 rs[ai][m] = 1.0f / sqrtf(s * (1.0f / 2048.0f) + RMS_EPS);
	v_add_f32_e32 v141, v160, v216
	v_fmamk_f32 v141, v141, 0x3a000000, v220
	v_cmp_gt_f32_e32 vcc, s43, v141
	v_mul_f32_e32 v160, 0x4f800000, v141
	s_nop 0
	v_cndmask_b32_e32 v141, v141, v160, vcc
	v_sqrt_f32_e32 v160, v141
	s_nop 0
	v_add_u32_e32 v162, -1, v160
	v_fma_f32 v164, -v162, v160, v141
	v_cmp_ge_f32_e64 s[6:7], 0, v164
	v_add_u32_e32 v164, 1, v160
	s_nop 0
	v_cndmask_b32_e64 v162, v160, v162, s[6:7]
	v_fma_f32 v160, -v164, v160, v141
	v_cmp_lt_f32_e64 s[6:7], 0, v160
	s_nop 1
	v_cndmask_b32_e64 v160, v162, v164, s[6:7]
	v_mul_f32_e32 v162, 0x37800000, v160
	v_cndmask_b32_e32 v160, v160, v162, vcc
	v_cmp_class_f32_e32 vcc, v141, v221
	v_mad_i64_i32 v[196:197], s[6:7], v154, s46, v[194:195]
	s_nop 0
	v_cndmask_b32_e32 v141, v160, v141, vcc
	v_div_scale_f32 v160, s[6:7], v141, v141, 1.0
	v_rcp_f32_e32 v162, v160
	s_nop 0
	v_fma_f32 v164, -v160, v162, 1.0
	v_fmac_f32_e32 v162, v164, v162
	v_div_scale_f32 v164, vcc, 1.0, v141, 1.0
	v_mul_f32_e32 v166, v164, v162
	v_fma_f32 v168, -v160, v166, v164
	v_fmac_f32_e32 v166, v168, v162
	v_fma_f32 v160, -v160, v166, v164
	v_div_fmas_f32 v160, v160, v162, v166
	v_div_fixup_f32 v160, v160, v141, 1.0
	global_load_dword v208, v[196:197], off
	v_mad_i64_i32 v[196:197], s[6:7], v171, s46, v[194:195]
	global_load_dword v209, v[196:197], off
	v_mad_i64_i32 v[196:197], s[6:7], v172, s46, v[194:195]
	global_load_dword v210, v[196:197], off
	v_mad_i64_i32 v[196:197], s[6:7], v173, s46, v[194:195]
	global_load_dword v211, v[196:197], off
	v_mad_i64_i32 v[196:197], s[6:7], v174, s46, v[194:195]
	global_load_dword v212, v[196:197], off
	v_mad_i64_i32 v[196:197], s[6:7], v175, s46, v[194:195]
	global_load_dword v213, v[196:197], off
	v_mad_i64_i32 v[196:197], s[6:7], v176, s46, v[194:195]
	v_mad_i64_i32 v[194:195], s[6:7], v177, s46, v[194:195]
	global_load_dword v214, v[196:197], off
	global_load_dword v215, v[194:195], off
	v_lshl_add_u64 v[194:195], v[148:149], 2, s[14:15]
	s_waitcnt vmcnt(0)
	v_add_f32_e32 v141, 0, v208
	v_add_f32_e32 v141, v141, v209
	v_add_f32_e32 v141, v141, v210
	v_add_f32_e32 v141, v141, v211
	v_add_f32_e32 v141, v141, v212
	v_add_f32_e32 v141, v141, v213
	v_add_f32_e32 v141, v141, v214
	v_add_f32_e32 v141, v141, v215
	v_mov_b32_e32 v162, v141
	v_mov_b32_e32 v216, v141
	s_nop 1
	v_permlane16_swap_b32_e32 v162, v216
	s_waitcnt lgkmcnt(0)
	v_add_f32_e32 v141, v162, v216
	v_mov_b32_e32 v162, v141
	v_mov_b32_e32 v216, v141
	s_nop 1
	v_permlane32_swap_b32_e32 v162, v216
	s_waitcnt lgkmcnt(0)
	v_add_f32_e32 v141, v162, v216
	v_fmamk_f32 v141, v141, 0x3a000000, v220
	v_cmp_gt_f32_e32 vcc, s43, v141
	v_mul_f32_e32 v162, 0x4f800000, v141
	s_nop 0
	v_cndmask_b32_e32 v141, v141, v162, vcc
	v_sqrt_f32_e32 v162, v141
	s_nop 0
	v_add_u32_e32 v164, -1, v162
	v_fma_f32 v166, -v164, v162, v141
	v_cmp_ge_f32_e64 s[6:7], 0, v166
	v_add_u32_e32 v166, 1, v162
	s_nop 0
	v_cndmask_b32_e64 v164, v162, v164, s[6:7]
	v_fma_f32 v162, -v166, v162, v141
	v_cmp_lt_f32_e64 s[6:7], 0, v162
	s_nop 1
	v_cndmask_b32_e64 v162, v164, v166, s[6:7]
	v_mul_f32_e32 v164, 0x37800000, v162
	v_cndmask_b32_e32 v162, v162, v164, vcc
	v_cmp_class_f32_e32 vcc, v141, v221
	v_mad_i64_i32 v[196:197], s[6:7], v154, s46, v[194:195]
	s_nop 0
	v_cndmask_b32_e32 v141, v162, v141, vcc
	v_div_scale_f32 v162, s[6:7], v141, v141, 1.0
	v_rcp_f32_e32 v164, v162
	s_nop 0
	v_fma_f32 v166, -v162, v164, 1.0
	v_fmac_f32_e32 v164, v166, v164
	v_div_scale_f32 v166, vcc, 1.0, v141, 1.0
	v_mul_f32_e32 v168, v166, v164
	v_fma_f32 v170, -v162, v168, v166
	v_fmac_f32_e32 v168, v170, v164
	v_fma_f32 v162, -v162, v168, v166
	v_div_fmas_f32 v162, v162, v164, v168
	v_div_fixup_f32 v162, v162, v141, 1.0
	global_load_dword v208, v[196:197], off
	v_mad_i64_i32 v[196:197], s[6:7], v171, s46, v[194:195]
	global_load_dword v209, v[196:197], off
	v_mad_i64_i32 v[196:197], s[6:7], v172, s46, v[194:195]
	global_load_dword v210, v[196:197], off
	v_mad_i64_i32 v[196:197], s[6:7], v173, s46, v[194:195]
	global_load_dword v211, v[196:197], off
	v_mad_i64_i32 v[196:197], s[6:7], v174, s46, v[194:195]
	global_load_dword v212, v[196:197], off
	v_mad_i64_i32 v[196:197], s[6:7], v175, s46, v[194:195]
	global_load_dword v213, v[196:197], off
	v_mad_i64_i32 v[196:197], s[6:7], v176, s46, v[194:195]
	v_mad_i64_i32 v[194:195], s[6:7], v177, s46, v[194:195]
	global_load_dword v214, v[196:197], off
	global_load_dword v215, v[194:195], off
	v_lshl_add_u64 v[194:195], v[146:147], 2, s[14:15]
	s_waitcnt vmcnt(0)
	v_add_f32_e32 v141, 0, v208
	v_add_f32_e32 v141, v141, v209
	v_add_f32_e32 v141, v141, v210
	v_add_f32_e32 v141, v141, v211
	v_add_f32_e32 v141, v141, v212
	v_add_f32_e32 v141, v141, v213
	v_add_f32_e32 v141, v141, v214
	v_add_f32_e32 v141, v141, v215
	v_mov_b32_e32 v164, v141
	v_mov_b32_e32 v216, v141
	s_nop 1
	v_permlane16_swap_b32_e32 v164, v216
	s_waitcnt lgkmcnt(0)
	v_add_f32_e32 v141, v164, v216
	v_mov_b32_e32 v164, v141
	v_mov_b32_e32 v216, v141
	s_nop 1
	v_permlane32_swap_b32_e32 v164, v216
	s_waitcnt lgkmcnt(0)
; __device__ __forceinline__ void rows_rstd(const float* SS, const Unit& u, int wr, int fr, int fq, float (&rs)[2][4]) {
;     ...
;             for (int m = 0; m < 4; ++m) {
;                 const int row = u.pm * BM + ai * HALF + wr * 64 + m * 16 + fr; float s = 0.f;
; #pragma unroll
;                 for (int j = 0; j < 8; ++j) s += SS[(size_t)(fq * 8 + j) * MPAD + row];
;                 s += __shfl_xor(s, 16); s += __shfl_xor(s, 32);
;                 rs[ai][m] = 1.0f / sqrtf(s * (1.0f / 2048.0f) + RMS_EPS);
	v_add_f32_e32 v141, v164, v216
	v_fmamk_f32 v141, v141, 0x3a000000, v220
	v_cmp_gt_f32_e32 vcc, s43, v141
	v_mul_f32_e32 v164, 0x4f800000, v141
	s_nop 0
	v_cndmask_b32_e32 v141, v141, v164, vcc
	v_sqrt_f32_e32 v164, v141
	s_nop 0
	v_add_u32_e32 v166, -1, v164
	v_fma_f32 v168, -v166, v164, v141
	v_cmp_ge_f32_e64 s[6:7], 0, v168
	v_add_u32_e32 v168, 1, v164
	s_nop 0
	v_cndmask_b32_e64 v166, v164, v166, s[6:7]
	v_fma_f32 v164, -v168, v164, v141
	v_cmp_lt_f32_e64 s[6:7], 0, v164
	s_nop 1
	v_cndmask_b32_e64 v164, v166, v168, s[6:7]
	v_mul_f32_e32 v166, 0x37800000, v164
	v_cndmask_b32_e32 v164, v164, v166, vcc
	v_cmp_class_f32_e32 vcc, v141, v221
	v_mad_i64_i32 v[196:197], s[6:7], v154, s46, v[194:195]
	s_nop 0
	v_cndmask_b32_e32 v141, v164, v141, vcc
	v_div_scale_f32 v164, s[6:7], v141, v141, 1.0
	v_rcp_f32_e32 v166, v164
	s_nop 0
	v_fma_f32 v168, -v164, v166, 1.0
	v_fmac_f32_e32 v166, v168, v166
	v_div_scale_f32 v168, vcc, 1.0, v141, 1.0
	v_mul_f32_e32 v170, v168, v166
	v_fma_f32 v189, -v164, v170, v168
	v_fmac_f32_e32 v170, v189, v166
	v_fma_f32 v164, -v164, v170, v168
	v_div_fmas_f32 v164, v164, v166, v170
	v_div_fixup_f32 v164, v164, v141, 1.0
	global_load_dword v208, v[196:197], off
	v_mad_i64_i32 v[196:197], s[6:7], v171, s46, v[194:195]
	global_load_dword v209, v[196:197], off
	v_mad_i64_i32 v[196:197], s[6:7], v172, s46, v[194:195]
	global_load_dword v210, v[196:197], off
	v_mad_i64_i32 v[196:197], s[6:7], v173, s46, v[194:195]
	global_load_dword v211, v[196:197], off
	v_mad_i64_i32 v[196:197], s[6:7], v174, s46, v[194:195]
	global_load_dword v212, v[196:197], off
	v_mad_i64_i32 v[196:197], s[6:7], v175, s46, v[194:195]
	global_load_dword v213, v[196:197], off
	v_mad_i64_i32 v[196:197], s[6:7], v176, s46, v[194:195]
	v_mad_i64_i32 v[194:195], s[6:7], v177, s46, v[194:195]
	global_load_dword v214, v[196:197], off
	global_load_dword v215, v[194:195], off
	s_waitcnt vmcnt(0)
	v_add_f32_e32 v141, 0, v208
	v_add_f32_e32 v141, v141, v209
	v_add_f32_e32 v141, v141, v210
	v_add_f32_e32 v141, v141, v211
	v_add_f32_e32 v141, v141, v212
	v_add_f32_e32 v141, v141, v213
	v_add_f32_e32 v141, v141, v214
	v_add_f32_e32 v141, v141, v215
	v_mov_b32_e32 v166, v141
	v_mov_b32_e32 v216, v141
	s_nop 1
	v_permlane16_swap_b32_e32 v166, v216
	s_waitcnt lgkmcnt(0)
	v_add_f32_e32 v141, v166, v216
	v_mov_b32_e32 v166, v141
	v_mov_b32_e32 v216, v141
	s_nop 1
	v_permlane32_swap_b32_e32 v166, v216
	s_waitcnt lgkmcnt(0)
	v_add_f32_e32 v141, v166, v216
	v_fmamk_f32 v141, v141, 0x3a000000, v220
	v_cmp_gt_f32_e32 vcc, s43, v141
	v_mul_f32_e32 v166, 0x4f800000, v141
	s_nop 0
	v_cndmask_b32_e32 v141, v141, v166, vcc
	v_sqrt_f32_e32 v166, v141
	s_nop 0
	v_add_u32_e32 v168, -1, v166
	v_fma_f32 v170, -v168, v166, v141
	v_cmp_ge_f32_e64 s[6:7], 0, v170
	v_add_u32_e32 v170, 1, v166
	s_nop 0
	v_cndmask_b32_e64 v168, v166, v168, s[6:7]
	v_fma_f32 v166, -v170, v166, v141
	v_cmp_lt_f32_e64 s[6:7], 0, v166
	s_nop 1
	v_cndmask_b32_e64 v166, v168, v170, s[6:7]
	v_mul_f32_e32 v168, 0x37800000, v166
	v_cndmask_b32_e32 v166, v166, v168, vcc
	v_cmp_class_f32_e32 vcc, v141, v221
	s_nop 1
	v_cndmask_b32_e32 v141, v166, v141, vcc
	v_div_scale_f32 v166, s[6:7], v141, v141, 1.0
	v_rcp_f32_e32 v168, v166
	s_nop 0
	v_fma_f32 v170, -v166, v168, 1.0
	v_fmac_f32_e32 v168, v170, v168
	v_div_scale_f32 v170, vcc, 1.0, v141, 1.0
	v_mul_f32_e32 v189, v170, v168
	v_fma_f32 v194, -v166, v189, v170
	v_fmac_f32_e32 v189, v194, v168
	v_fma_f32 v166, -v166, v189, v170
	v_lshl_add_u64 v[194:195], v[144:145], 2, s[14:15]
	v_div_fmas_f32 v166, v166, v168, v189
	v_mad_i64_i32 v[196:197], s[6:7], v154, s46, v[194:195]
	v_div_fixup_f32 v166, v166, v141, 1.0
	global_load_dword v208, v[196:197], off
	v_mad_i64_i32 v[196:197], s[6:7], v171, s46, v[194:195]
	global_load_dword v209, v[196:197], off
	v_mad_i64_i32 v[196:197], s[6:7], v172, s46, v[194:195]
	global_load_dword v210, v[196:197], off
	v_mad_i64_i32 v[196:197], s[6:7], v173, s46, v[194:195]
	global_load_dword v211, v[196:197], off
	v_mad_i64_i32 v[196:197], s[6:7], v174, s46, v[194:195]
	global_load_dword v212, v[196:197], off
	v_mad_i64_i32 v[196:197], s[6:7], v175, s46, v[194:195]
	global_load_dword v213, v[196:197], off
	v_mad_i64_i32 v[196:197], s[6:7], v176, s46, v[194:195]
	v_mad_i64_i32 v[194:195], s[6:7], v177, s46, v[194:195]
	global_load_dword v214, v[196:197], off
	global_load_dword v215, v[194:195], off
	s_waitcnt vmcnt(0)
	v_add_f32_e32 v141, 0, v208
	v_add_f32_e32 v141, v141, v209
	v_add_f32_e32 v141, v141, v210
	v_add_f32_e32 v141, v141, v211
	v_add_f32_e32 v141, v141, v212
	v_add_f32_e32 v141, v141, v213
	v_add_f32_e32 v141, v141, v214
	v_add_f32_e32 v141, v141, v215
	v_mov_b32_e32 v168, v141
	v_mov_b32_e32 v216, v141
	s_nop 1
	v_permlane16_swap_b32_e32 v168, v216
	s_waitcnt lgkmcnt(0)
	v_add_f32_e32 v141, v168, v216
	v_mov_b32_e32 v168, v141
	v_mov_b32_e32 v216, v141
	s_nop 1
	v_permlane32_swap_b32_e32 v168, v216
	s_waitcnt lgkmcnt(0)
; __device__ __forceinline__ void rows_rstd(const float* SS, const Unit& u, int wr, int fr, int fq, float (&rs)[2][4]) {
;     ...
;             for (int m = 0; m < 4; ++m) {
;                 const int row = u.pm * BM + ai * HALF + wr * 64 + m * 16 + fr; float s = 0.f;
; #pragma unroll
;                 for (int j = 0; j < 8; ++j) s += SS[(size_t)(fq * 8 + j) * MPAD + row];
;                 s += __shfl_xor(s, 16); s += __shfl_xor(s, 32);
;                 rs[ai][m] = 1.0f / sqrtf(s * (1.0f / 2048.0f) + RMS_EPS);
	v_add_f32_e32 v141, v168, v216
	v_fmamk_f32 v141, v141, 0x3a000000, v220
	v_cmp_gt_f32_e32 vcc, s43, v141
	v_mul_f32_e32 v168, 0x4f800000, v141
	s_nop 0
	v_cndmask_b32_e32 v141, v141, v168, vcc
	v_sqrt_f32_e32 v168, v141
	s_nop 0
	v_add_u32_e32 v170, -1, v168
	v_fma_f32 v189, -v170, v168, v141
	v_cmp_ge_f32_e64 s[6:7], 0, v189
	v_add_u32_e32 v189, 1, v168
	s_nop 0
	v_cndmask_b32_e64 v170, v168, v170, s[6:7]
	v_fma_f32 v168, -v189, v168, v141
	v_cmp_lt_f32_e64 s[6:7], 0, v168
	s_nop 1
	v_cndmask_b32_e64 v168, v170, v189, s[6:7]
	v_mul_f32_e32 v170, 0x37800000, v168
	v_cndmask_b32_e32 v168, v168, v170, vcc
	v_cmp_class_f32_e32 vcc, v141, v221
	s_nop 1
	v_cndmask_b32_e32 v141, v168, v141, vcc
	v_div_scale_f32 v168, s[6:7], v141, v141, 1.0
	v_rcp_f32_e32 v170, v168
	s_nop 0
	v_fma_f32 v189, -v168, v170, 1.0
	v_fmac_f32_e32 v170, v189, v170
	v_div_scale_f32 v189, vcc, 1.0, v141, 1.0
	v_mul_f32_e32 v194, v189, v170
	v_fma_f32 v195, -v168, v194, v189
	v_fmac_f32_e32 v194, v195, v170
	v_fma_f32 v168, -v168, v194, v189
	v_div_fmas_f32 v168, v168, v170, v194
	v_lshl_add_u64 v[194:195], v[142:143], 2, s[14:15]
	v_mad_i64_i32 v[196:197], s[6:7], v154, s46, v[194:195]
	v_div_fixup_f32 v168, v168, v141, 1.0
	global_load_dword v208, v[196:197], off
	v_mad_i64_i32 v[196:197], s[6:7], v171, s46, v[194:195]
	global_load_dword v209, v[196:197], off
	v_mad_i64_i32 v[196:197], s[6:7], v172, s46, v[194:195]
	global_load_dword v210, v[196:197], off
	v_mad_i64_i32 v[196:197], s[6:7], v173, s46, v[194:195]
	global_load_dword v211, v[196:197], off
	v_mad_i64_i32 v[196:197], s[6:7], v174, s46, v[194:195]
	global_load_dword v212, v[196:197], off
	v_mad_i64_i32 v[196:197], s[6:7], v175, s46, v[194:195]
	global_load_dword v213, v[196:197], off
	v_mad_i64_i32 v[196:197], s[6:7], v176, s46, v[194:195]
	v_mad_i64_i32 v[194:195], s[6:7], v177, s46, v[194:195]
	global_load_dword v214, v[196:197], off
	global_load_dword v215, v[194:195], off
	s_waitcnt vmcnt(0)
	v_add_f32_e32 v141, 0, v208
	v_add_f32_e32 v141, v141, v209
	v_add_f32_e32 v141, v141, v210
	v_add_f32_e32 v141, v141, v211
	v_add_f32_e32 v141, v141, v212
	v_add_f32_e32 v141, v141, v213
	v_add_f32_e32 v141, v141, v214
	v_add_f32_e32 v141, v141, v215
	v_mov_b32_e32 v170, v141
	v_mov_b32_e32 v216, v141
	s_nop 1
	v_permlane16_swap_b32_e32 v170, v216
	s_waitcnt lgkmcnt(0)
	v_add_f32_e32 v141, v170, v216
	v_mov_b32_e32 v170, v141
	v_mov_b32_e32 v216, v141
	s_nop 1
	v_permlane32_swap_b32_e32 v170, v216
	s_waitcnt lgkmcnt(0)
	v_add_f32_e32 v141, v170, v216
	v_fmamk_f32 v141, v141, 0x3a000000, v220
	v_cmp_gt_f32_e32 vcc, s43, v141
	v_mul_f32_e32 v170, 0x4f800000, v141
	s_nop 0
	v_cndmask_b32_e32 v141, v141, v170, vcc
	v_sqrt_f32_e32 v170, v141
	s_nop 0
	v_add_u32_e32 v189, -1, v170
	v_fma_f32 v194, -v189, v170, v141
	v_cmp_ge_f32_e64 s[6:7], 0, v194
	v_add_u32_e32 v194, 1, v170
	s_nop 0
	v_cndmask_b32_e64 v189, v170, v189, s[6:7]
	v_fma_f32 v170, -v194, v170, v141
	v_cmp_lt_f32_e64 s[6:7], 0, v170
	s_nop 1
	v_cndmask_b32_e64 v170, v189, v194, s[6:7]
	v_mul_f32_e32 v189, 0x37800000, v170
	v_cndmask_b32_e32 v170, v170, v189, vcc
	v_cmp_class_f32_e32 vcc, v141, v221
	s_nop 1
	v_cndmask_b32_e32 v141, v170, v141, vcc
	v_div_scale_f32 v170, s[6:7], v141, v141, 1.0
	v_rcp_f32_e32 v189, v170
	s_nop 0
	v_fma_f32 v194, -v170, v189, 1.0
	v_fmac_f32_e32 v189, v194, v189
	v_div_scale_f32 v194, vcc, 1.0, v141, 1.0
	v_mul_f32_e32 v195, v194, v189
	v_fma_f32 v196, -v170, v195, v194
	v_fmac_f32_e32 v195, v196, v189
	v_fma_f32 v170, -v170, v195, v194
	v_div_fmas_f32 v170, v170, v189, v195
	v_div_fixup_f32 v170, v170, v141, 1.0
	v_ashrrev_i32_e32 v141, 31, v140
	v_lshl_add_u64 v[194:195], v[140:141], 2, s[14:15]
	v_mad_i64_i32 v[196:197], s[6:7], v154, s46, v[194:195]
	global_load_dword v208, v[196:197], off
	v_mad_i64_i32 v[196:197], s[6:7], v171, s46, v[194:195]
	global_load_dword v209, v[196:197], off
	v_mad_i64_i32 v[196:197], s[6:7], v172, s46, v[194:195]
	global_load_dword v210, v[196:197], off
	v_mad_i64_i32 v[172:173], s[6:7], v173, s46, v[194:195]
	global_load_dword v211, v[172:173], off
	v_mad_i64_i32 v[172:173], s[6:7], v174, s46, v[194:195]
	global_load_dword v212, v[172:173], off
	v_mad_i64_i32 v[172:173], s[6:7], v175, s46, v[194:195]
	global_load_dword v213, v[172:173], off
	v_mad_i64_i32 v[172:173], s[6:7], v176, s46, v[194:195]
	global_load_dword v214, v[172:173], off
	v_mad_i64_i32 v[172:173], s[6:7], v177, s46, v[194:195]
	global_load_dword v215, v[172:173], off
	s_waitcnt vmcnt(0)
	v_add_f32_e32 v189, 0, v208
	v_add_f32_e32 v171, v189, v209
	v_add_f32_e32 v171, v171, v210
	v_add_f32_e32 v171, v171, v211
	v_add_f32_e32 v171, v171, v212
	v_add_f32_e32 v171, v171, v213
	v_add_f32_e32 v171, v171, v214
	v_add_f32_e32 v171, v171, v215
	v_mov_b32_e32 v169, v171
	v_mov_b32_e32 v216, v171
	s_nop 1
	v_permlane16_swap_b32_e32 v169, v216
	s_waitcnt lgkmcnt(0)
	v_add_f32_e32 v169, v169, v216
	v_mov_b32_e32 v167, v169
	v_mov_b32_e32 v216, v169
	s_nop 1
	v_permlane32_swap_b32_e32 v167, v216
	s_waitcnt lgkmcnt(0)
	v_add_f32_e32 v167, v167, v216
	v_fmamk_f32 v167, v167, 0x3a000000, v220
	v_cmp_gt_f32_e32 vcc, s43, v167
	v_mul_f32_e32 v169, 0x4f800000, v167
	s_nop 0
	v_cndmask_b32_e32 v167, v167, v169, vcc
	v_sqrt_f32_e32 v169, v167
	s_nop 0
	v_add_u32_e32 v171, -1, v169
	v_fma_f32 v172, -v171, v169, v167
	v_cmp_ge_f32_e64 s[6:7], 0, v172
	v_add_u32_e32 v172, 1, v169
	s_nop 0
	v_cndmask_b32_e64 v171, v169, v171, s[6:7]
	v_fma_f32 v169, -v172, v169, v167
	v_cmp_lt_f32_e64 s[6:7], 0, v169
	s_nop 1
	v_cndmask_b32_e64 v169, v171, v172, s[6:7]
	v_mul_f32_e32 v171, 0x37800000, v169
	v_cndmask_b32_e32 v169, v169, v171, vcc
	v_cmp_class_f32_e32 vcc, v167, v221
	s_nop 1
	v_cndmask_b32_e32 v167, v169, v167, vcc
	v_div_scale_f32 v169, s[6:7], v167, v167, 1.0
	v_rcp_f32_e32 v171, v169
	s_mov_b64 s[6:7], 0
	v_fma_f32 v172, -v169, v171, 1.0
	v_fmac_f32_e32 v171, v172, v171
	v_div_scale_f32 v172, vcc, 1.0, v167, 1.0
	v_mul_f32_e32 v173, v172, v171
	v_fma_f32 v174, -v169, v173, v172
	v_fmac_f32_e32 v173, v174, v171
	v_fma_f32 v169, -v169, v173, v172
	v_div_fmas_f32 v169, v169, v171, v173
	v_div_fixup_f32 v172, v169, v167, 1.0

; __device__ __forceinline__ u32x4 pack8(const f32x4 a, const f32x4 b) { u32x4 w; w.x = cvt_pk_bf16(a[0], a[1]); w.y = cvt_pk_bf16(a[2], a[3]); w.z = cvt_pk_bf16(b[0], b[1]); w.w = cvt_pk_bf16(b[2], b[3]); return w; }
;     __device__ __forceinline__ void operator()(const f32x4 (&acc)[2][2][4][2], const Unit& u, int wr, int wc, int fr, int fq) const {
;     ...
;                 for (int bj = 0; bj < 2; ++bj) { const float* p = Xin + (size_t)(u.pm * BM + ai * HALF + wr * 64 + m * 16 + fr) * DM + u.pn * BM + bj * HALF + wc * 32 + 8 * fq;
;                     xa[m][bj][0] = *(const f32x4*)p; xa[m][bj][1] = *(const f32x4*)(p + 4); }
; #pragma unroll
;             for (int m = 0; m < 4; ++m) {
;                 const int row = u.pm * BM + ai * HALF + wr * 64 + m * 16 + fr; float ss = 0.f;
; #pragma unroll
;                 for (int bj = 0; bj < 2; ++bj) {
;                     const size_t off = (size_t)row * DM + u.pn * BM + bj * HALF + wc * 32 + 8 * fq;
;                     const f32x4 a0 = xa[m][bj][0] + acc[ai][bj][m][0] * scale, a1 = xa[m][bj][1] + acc[ai][bj][m][1] * scale;
;                     *(f32x4*)(X + off) = a0; *(f32x4*)(X + off + 4) = a1;
;                     ss += (a0[0] * a0[0] + a0[1] * a0[1]) + (a0[2] * a0[2] + a0[3] * a0[3]) + (a1[0] * a1[0] + a1[1] * a1[1]) + (a1[2] * a1[2] + a1[3] * a1[3]);
;                     *(u32x4*)(XB + off) = pack8(a0, a1);
;                 }
;                 ss += __shfl_xor(ss, 16); ss += __shfl_xor(ss, 32);
;                 if (fq == 0) SSo[(size_t)(u.pn * 4 + wc) * MPAD + row] = ss;
.LBB0_346:
	s_lshl_b32 s6, s86, 8
	v_mov_b32_e32 v2, v233
	v_mov_b32_e32 v4, v189
	s_add_i32 s6, s6, s73
	s_nop 0
	v_add_u32_e32 v198, s6, v2
	s_lshl_b32 s6, s76, 8
	s_ashr_i32 s7, s6, 31
	v_lshlrev_b32_e32 v2, 3, v4
	s_waitcnt lgkmcnt(0)
	v_ashrrev_i32_e32 v3, 31, v2
	s_or_b64 s[30:31], s[6:7], s[48:49]
	v_lshl_add_u64 v[106:107], s[30:31], 0, v[2:3]
	s_lshl_b32 s30, s76, 2
	s_or_b32 s31, s30, s70
	s_lshl_b64 s[6:7], s[6:7], 2
	s_add_u32 s6, s81, s6
	s_addc_u32 s7, s82, s7
	v_ashrrev_i32_e32 v199, 31, v198
	v_lshl_add_u64 v[200:201], v[2:3], 2, s[6:7]
	v_lshlrev_b64 v[2:3], 13, v[198:199]
	v_lshl_add_u64 v[2:3], v[200:201], 0, v[2:3]
	global_load_dwordx4 v[236:239], v[2:3], off offset:16
	global_load_dwordx4 v[240:243], v[2:3], off
	global_load_dwordx4 v[244:247], v[2:3], off offset:528
	global_load_dwordx4 v[248:251], v[2:3], off offset:512
	v_add_u32_e32 v54, 16, v198
	v_ashrrev_i32_e32 v55, 31, v54
	v_lshlrev_b64 v[2:3], 13, v[54:55]
	v_add_u32_e32 v52, 32, v198
	v_lshl_add_u64 v[2:3], v[200:201], 0, v[2:3]
	v_ashrrev_i32_e32 v53, 31, v52
	global_load_dwordx4 v[42:45], v[2:3], off offset:16
	global_load_dwordx4 v[46:49], v[2:3], off
	global_load_dwordx4 v[34:37], v[2:3], off offset:528
	global_load_dwordx4 v[38:41], v[2:3], off offset:512
	v_lshlrev_b64 v[2:3], 13, v[52:53]
	v_add_u32_e32 v50, 48, v198
	v_lshl_add_u64 v[2:3], v[200:201], 0, v[2:3]
	v_ashrrev_i32_e32 v51, 31, v50
	global_load_dwordx4 v[26:29], v[2:3], off offset:16
	global_load_dwordx4 v[30:33], v[2:3], off
	global_load_dwordx4 v[10:13], v[2:3], off offset:528
	global_load_dwordx4 v[18:21], v[2:3], off offset:512
	v_lshlrev_b64 v[2:3], 13, v[50:51]
	v_lshl_add_u64 v[6:7], v[200:201], 0, v[2:3]
	v_cmp_eq_u32_e32 vcc, 0, v4
	global_load_dwordx4 v[14:17], v[6:7], off offset:16
	global_load_dwordx4 v[22:25], v[6:7], off
	global_load_dwordx4 v[2:5], v[6:7], off offset:528
	s_nop 0
	global_load_dwordx4 v[6:9], v[6:7], off offset:512
	v_lshlrev_b64 v[56:57], 11, v[198:199]
	v_lshl_add_u64 v[56:57], v[106:107], 0, v[56:57]
	v_lshl_add_u64 v[222:223], v[56:57], 2, s[14:15]
	v_lshl_add_u64 v[56:57], v[56:57], 1, s[16:17]
	s_mul_hi_i32 s30, s31, 0x8400
	s_mul_i32 s31, s31, 0x8400
	s_waitcnt vmcnt(0)
	v_pk_add_f32 v[242:243], v[202:203], v[242:243]
	v_pk_add_f32 v[240:241], v[204:205], v[240:241]
	v_pk_add_f32 v[204:205], v[206:207], v[238:239]
	v_mul_f32_e32 v206, v241, v241
	v_mul_f32_e32 v207, v243, v243
	v_pk_add_f32 v[202:203], v[208:209], v[236:237]
	v_fmac_f32_e32 v206, v240, v240
	v_fmac_f32_e32 v207, v242, v242
	v_add_f32_e32 v206, v206, v207
	v_mul_f32_e32 v207, v203, v203
	v_fmac_f32_e32 v207, v202, v202
	v_add_f32_e32 v206, v207, v206
	v_mul_f32_e32 v207, v205, v205
	v_fmac_f32_e32 v207, v204, v204
	global_store_dwordx4 v[222:223], v[240:243], off
	global_store_dwordx4 v[222:223], v[202:205], off offset:16
	v_add_f32_e32 v232, v207, v206
	v_cvt_pk_bf16_f32 v206, v240, v241
	v_cvt_pk_bf16_f32 v207, v242, v243
	v_cvt_pk_bf16_f32 v208, v202, v203
	v_cvt_pk_bf16_f32 v209, v204, v205
	s_nop 0
	v_pk_add_f32 v[204:205], v[210:211], v[250:251]
	v_pk_add_f32 v[202:203], v[212:213], v[248:249]
	v_mul_f32_e32 v211, v205, v205
	v_mul_f32_e32 v210, v203, v203
	global_store_dwordx4 v[56:57], v[206:209], off
	v_fmac_f32_e32 v210, v202, v202
	v_fmac_f32_e32 v211, v204, v204
	v_pk_add_f32 v[206:207], v[216:217], v[244:245]
	v_add_f32_e32 v210, v210, v211
	v_mul_f32_e32 v211, v207, v207
	v_pk_add_f32 v[208:209], v[214:215], v[246:247]
	global_store_dwordx4 v[222:223], v[202:205], off offset:512
	global_store_dwordx4 v[222:223], v[206:209], off offset:528
	v_fmac_f32_e32 v211, v206, v206
	v_cvt_pk_bf16_f32 v202, v202, v203
	v_cvt_pk_bf16_f32 v203, v204, v205
	v_cvt_pk_bf16_f32 v204, v206, v207
	v_cvt_pk_bf16_f32 v205, v208, v209
	global_store_dwordx4 v[56:57], v[202:205], off offset:256
	v_and_b32_e32 v57, 64, v219
	v_add_f32_e32 v210, v211, v210
	v_mul_f32_e32 v211, v209, v209
	v_xor_b32_e32 v56, 16, v219
	v_add_u32_e32 v57, 64, v57
	v_fmac_f32_e32 v211, v208, v208
	v_cmp_lt_i32_e64 s[6:7], v56, v57
	v_add_f32_e32 v210, v211, v210
	v_add_f32_e32 v210, v232, v210
	v_cndmask_b32_e64 v56, v219, v56, s[6:7]
	v_lshlrev_b32_e32 v202, 2, v56
	v_mov_b32_e32 v56, v210
	v_mov_b32_e32 v252, v210
	s_nop 1
	v_permlane16_swap_b32_e32 v56, v252
	v_xor_b32_e32 v203, 32, v219
	v_cmp_lt_i32_e64 s[6:7], v203, v57
	s_waitcnt lgkmcnt(0)
	v_add_f32_e32 v56, v56, v252
	v_cndmask_b32_e64 v57, v219, v203, s[6:7]
	v_lshlrev_b32_e32 v203, 2, v57
	v_mov_b32_e32 v57, v56
	v_mov_b32_e32 v252, v56
	s_nop 1
	v_permlane32_swap_b32_e32 v57, v252
	s_and_saveexec_b64 s[6:7], vcc
	s_cbranch_execz .LBB0_348
	s_add_u32 s54, s66, s31
	s_addc_u32 s55, s67, s30
	v_lshl_add_u64 v[204:205], v[198:199], 2, s[54:55]
	s_waitcnt lgkmcnt(0)
	v_add_f32_e32 v56, v57, v252
	global_store_dword v[204:205], v56, off
; __device__ __forceinline__ u32x4 pack8(const f32x4 a, const f32x4 b) { u32x4 w; w.x = cvt_pk_bf16(a[0], a[1]); w.y = cvt_pk_bf16(a[2], a[3]); w.z = cvt_pk_bf16(b[0], b[1]); w.w = cvt_pk_bf16(b[2], b[3]); return w; }
;     __device__ __forceinline__ void operator()(const f32x4 (&acc)[2][2][4][2], const Unit& u, int wr, int wc, int fr, int fq) const {
;     ...
;             for (int m = 0; m < 4; ++m) {
;                 const int row = u.pm * BM + ai * HALF + wr * 64 + m * 16 + fr; float ss = 0.f;
; #pragma unroll
;                 for (int bj = 0; bj < 2; ++bj) {
;                     const size_t off = (size_t)row * DM + u.pn * BM + bj * HALF + wc * 32 + 8 * fq;
;                     const f32x4 a0 = xa[m][bj][0] + acc[ai][bj][m][0] * scale, a1 = xa[m][bj][1] + acc[ai][bj][m][1] * scale;
;                     *(f32x4*)(X + off) = a0; *(f32x4*)(X + off + 4) = a1;
;                     ss += (a0[0] * a0[0] + a0[1] * a0[1]) + (a0[2] * a0[2] + a0[3] * a0[3]) + (a1[0] * a1[0] + a1[1] * a1[1]) + (a1[2] * a1[2] + a1[3] * a1[3]);
;                     *(u32x4*)(XB + off) = pack8(a0, a1);
;                 }
;                 ss += __shfl_xor(ss, 16); ss += __shfl_xor(ss, 32);
;                 if (fq == 0) SSo[(size_t)(u.pn * 4 + wc) * MPAD + row] = ss;
.LBB0_348:
	s_or_b64 exec, exec, s[6:7]
	v_pk_add_f32 v[48:49], v[196:197], v[48:49]
	v_pk_add_f32 v[46:47], v[194:195], v[46:47]
	s_waitcnt lgkmcnt(0)
	v_lshlrev_b64 v[56:57], 11, v[54:55]
	v_pk_add_f32 v[44:45], v[176:177], v[44:45]
	v_mul_f32_e32 v176, v47, v47
	v_mul_f32_e32 v177, v49, v49
	v_lshl_add_u64 v[56:57], v[56:57], 0, v[106:107]
	v_pk_add_f32 v[42:43], v[174:175], v[42:43]
	v_fmac_f32_e32 v176, v46, v46
	v_fmac_f32_e32 v177, v48, v48
	v_lshl_add_u64 v[174:175], v[56:57], 2, s[14:15]
	v_add_f32_e32 v176, v176, v177
	v_mul_f32_e32 v177, v43, v43
	v_pk_add_f32 v[40:41], v[172:173], v[40:41]
	v_pk_add_f32 v[38:39], v[170:171], v[38:39]
	global_store_dwordx4 v[174:175], v[46:49], off
	global_store_dwordx4 v[174:175], v[42:45], off offset:16
	v_fmac_f32_e32 v177, v42, v42
	v_cvt_pk_bf16_f32 v46, v46, v47
	v_cvt_pk_bf16_f32 v47, v48, v49
	v_cvt_pk_bf16_f32 v48, v42, v43
	v_add_f32_e32 v176, v177, v176
	v_pk_add_f32 v[42:43], v[166:167], v[34:35]
	v_mul_f32_e32 v34, v39, v39
	v_mul_f32_e32 v35, v41, v41
	v_fmac_f32_e32 v34, v38, v38
	v_fmac_f32_e32 v35, v40, v40
	v_mul_f32_e32 v177, v45, v45
	v_add_f32_e32 v34, v34, v35
	v_mul_f32_e32 v35, v43, v43
	v_fmac_f32_e32 v177, v44, v44
	v_cvt_pk_bf16_f32 v49, v44, v45
	v_pk_add_f32 v[44:45], v[168:169], v[36:37]
	v_fmac_f32_e32 v35, v42, v42
	v_add_f32_e32 v34, v35, v34
	v_mul_f32_e32 v35, v45, v45
	v_fmac_f32_e32 v35, v44, v44
	v_add_f32_e32 v176, v177, v176
	v_add_f32_e32 v34, v35, v34
	v_add_f32_e32 v34, v176, v34
	v_mov_b32_e32 v35, v34
	v_mov_b32_e32 v252, v34
	s_nop 1
	v_permlane16_swap_b32_e32 v35, v252
	v_lshl_add_u64 v[56:57], v[56:57], 1, s[16:17]
	global_store_dwordx4 v[56:57], v[46:49], off
	global_store_dwordx4 v[174:175], v[38:41], off offset:512
	global_store_dwordx4 v[174:175], v[42:45], off offset:528
	v_cvt_pk_bf16_f32 v36, v38, v39
	v_cvt_pk_bf16_f32 v37, v40, v41
	s_waitcnt lgkmcnt(0)
	v_add_f32_e32 v34, v35, v252
	v_mov_b32_e32 v35, v34
	v_mov_b32_e32 v252, v34
	s_nop 1
	v_permlane32_swap_b32_e32 v35, v252
	v_cvt_pk_bf16_f32 v38, v42, v43
	v_cvt_pk_bf16_f32 v39, v44, v45
	global_store_dwordx4 v[56:57], v[36:39], off offset:256
	s_and_saveexec_b64 s[6:7], vcc
	s_cbranch_execz .LBB0_350
	s_add_u32 s54, s66, s31
	s_addc_u32 s55, s67, s30
	v_lshl_add_u64 v[36:37], v[54:55], 2, s[54:55]
	s_waitcnt lgkmcnt(0)
	v_add_f32_e32 v34, v35, v252
	global_store_dword v[36:37], v34, off
.LBB0_350:
	s_or_b64 exec, exec, s[6:7]
	v_pk_add_f32 v[32:33], v[164:165], v[32:33]
	v_pk_add_f32 v[30:31], v[162:163], v[30:31]
	s_waitcnt lgkmcnt(0)
	v_lshlrev_b64 v[34:35], 11, v[52:53]
	v_mul_f32_e32 v38, v31, v31
	v_mul_f32_e32 v39, v33, v33
	v_lshl_add_u64 v[34:35], v[34:35], 0, v[106:107]
	v_pk_add_f32 v[26:27], v[158:159], v[26:27]
	v_fmac_f32_e32 v38, v30, v30
	v_fmac_f32_e32 v39, v32, v32
	v_lshl_add_u64 v[36:37], v[34:35], 2, s[14:15]
	v_add_f32_e32 v38, v38, v39
	v_mul_f32_e32 v39, v27, v27
	v_pk_add_f32 v[20:21], v[156:157], v[20:21]
	v_pk_add_f32 v[18:19], v[154:155], v[18:19]
	v_pk_add_f32 v[28:29], v[160:161], v[28:29]
	global_store_dwordx4 v[36:37], v[30:33], off
	global_store_dwordx4 v[36:37], v[26:29], off offset:16
	v_fmac_f32_e32 v39, v26, v26
	v_cvt_pk_bf16_f32 v30, v30, v31
	v_cvt_pk_bf16_f32 v31, v32, v33
	v_cvt_pk_bf16_f32 v32, v26, v27
	v_add_f32_e32 v38, v39, v38
	v_pk_add_f32 v[26:27], v[150:151], v[10:11]
	v_mul_f32_e32 v10, v19, v19
	v_mul_f32_e32 v11, v21, v21
	v_fmac_f32_e32 v10, v18, v18
	v_fmac_f32_e32 v11, v20, v20
	v_mul_f32_e32 v39, v29, v29
	v_add_f32_e32 v10, v10, v11
	v_mul_f32_e32 v11, v27, v27
	v_fmac_f32_e32 v39, v28, v28
	v_cvt_pk_bf16_f32 v33, v28, v29
	v_pk_add_f32 v[28:29], v[152:153], v[12:13]
	v_fmac_f32_e32 v11, v26, v26
	v_add_f32_e32 v10, v11, v10
	v_mul_f32_e32 v11, v29, v29
	v_fmac_f32_e32 v11, v28, v28
	v_add_f32_e32 v38, v39, v38
	v_add_f32_e32 v10, v11, v10
	v_add_f32_e32 v10, v38, v10
	v_mov_b32_e32 v11, v10
	v_mov_b32_e32 v252, v10
	s_nop 1
	v_permlane16_swap_b32_e32 v11, v252
	v_lshl_add_u64 v[34:35], v[34:35], 1, s[16:17]
	global_store_dwordx4 v[34:35], v[30:33], off
	global_store_dwordx4 v[36:37], v[18:21], off offset:512
	global_store_dwordx4 v[36:37], v[26:29], off offset:528
	s_waitcnt lgkmcnt(0)
	v_add_f32_e32 v10, v11, v252
	v_mov_b32_e32 v11, v10
	v_mov_b32_e32 v252, v10
	s_nop 1
	v_permlane32_swap_b32_e32 v11, v252
	v_cvt_pk_bf16_f32 v18, v18, v19
	v_cvt_pk_bf16_f32 v19, v20, v21
	v_cvt_pk_bf16_f32 v20, v26, v27
	v_cvt_pk_bf16_f32 v21, v28, v29
	global_store_dwordx4 v[34:35], v[18:21], off offset:256
	s_and_saveexec_b64 s[6:7], vcc
	s_cbranch_execz .LBB0_352
	s_add_u32 s54, s66, s31
	s_addc_u32 s55, s67, s30
	v_lshl_add_u64 v[12:13], v[52:53], 2, s[54:55]
	s_waitcnt lgkmcnt(0)
	v_add_f32_e32 v10, v11, v252
	global_store_dword v[12:13], v10, off
; __device__ __forceinline__ u32x4 pack8(const f32x4 a, const f32x4 b) { u32x4 w; w.x = cvt_pk_bf16(a[0], a[1]); w.y = cvt_pk_bf16(a[2], a[3]); w.z = cvt_pk_bf16(b[0], b[1]); w.w = cvt_pk_bf16(b[2], b[3]); return w; }
;     __device__ __forceinline__ void operator()(const f32x4 (&acc)[2][2][4][2], const Unit& u, int wr, int wc, int fr, int fq) const {
;     ...
;             f32x4 xa[4][2][2];
; #pragma unroll
;             for (int m = 0; m < 4; ++m)
; #pragma unroll
;                 for (int bj = 0; bj < 2; ++bj) { const float* p = Xin + (size_t)(u.pm * BM + ai * HALF + wr * 64 + m * 16 + fr) * DM + u.pn * BM + bj * HALF + wc * 32 + 8 * fq;
;                     xa[m][bj][0] = *(const f32x4*)p; xa[m][bj][1] = *(const f32x4*)(p + 4); }
; #pragma unroll
;             for (int m = 0; m < 4; ++m) {
;                 const int row = u.pm * BM + ai * HALF + wr * 64 + m * 16 + fr; float ss = 0.f;
; #pragma unroll
;                 for (int bj = 0; bj < 2; ++bj) {
;                     const size_t off = (size_t)row * DM + u.pn * BM + bj * HALF + wc * 32 + 8 * fq;
;                     const f32x4 a0 = xa[m][bj][0] + acc[ai][bj][m][0] * scale, a1 = xa[m][bj][1] + acc[ai][bj][m][1] * scale;
;                     *(f32x4*)(X + off) = a0; *(f32x4*)(X + off + 4) = a1;
;                     ss += (a0[0] * a0[0] + a0[1] * a0[1]) + (a0[2] * a0[2] + a0[3] * a0[3]) + (a1[0] * a1[0] + a1[1] * a1[1]) + (a1[2] * a1[2] + a1[3] * a1[3]);
;                     *(u32x4*)(XB + off) = pack8(a0, a1);
;                 }
;                 ss += __shfl_xor(ss, 16); ss += __shfl_xor(ss, 32);
;                 if (fq == 0) SSo[(size_t)(u.pn * 4 + wc) * MPAD + row] = ss;
.LBB0_352:
	s_or_b64 exec, exec, s[6:7]
	s_waitcnt lgkmcnt(0)
	v_lshlrev_b64 v[10:11], 11, v[50:51]
	v_lshl_add_u64 v[18:19], v[10:11], 0, v[106:107]
	v_pk_add_f32 v[12:13], v[148:149], v[24:25]
	v_pk_add_f32 v[10:11], v[146:147], v[22:23]
	v_mul_f32_e32 v23, v13, v13
	v_mul_f32_e32 v22, v11, v11
	v_pk_add_f32 v[14:15], v[142:143], v[14:15]
	v_fmac_f32_e32 v22, v10, v10
	v_fmac_f32_e32 v23, v12, v12
	v_lshl_add_u64 v[20:21], v[18:19], 2, s[14:15]
	v_add_f32_e32 v22, v22, v23
	v_mul_f32_e32 v23, v15, v15
	v_pk_add_f32 v[8:9], v[140:141], v[8:9]
	v_pk_add_f32 v[6:7], v[128:129], v[6:7]
	v_pk_add_f32 v[16:17], v[144:145], v[16:17]
	global_store_dwordx4 v[20:21], v[10:13], off
	global_store_dwordx4 v[20:21], v[14:17], off offset:16
	v_fmac_f32_e32 v23, v14, v14
	v_cvt_pk_bf16_f32 v10, v10, v11
	v_cvt_pk_bf16_f32 v11, v12, v13
	v_cvt_pk_bf16_f32 v12, v14, v15
	v_add_f32_e32 v22, v23, v22
	v_pk_add_f32 v[14:15], v[124:125], v[2:3]
	v_mul_f32_e32 v2, v7, v7
	v_mul_f32_e32 v3, v9, v9
	v_fmac_f32_e32 v2, v6, v6
	v_fmac_f32_e32 v3, v8, v8
	v_mul_f32_e32 v23, v17, v17
	v_add_f32_e32 v2, v2, v3
	v_mul_f32_e32 v3, v15, v15
	v_fmac_f32_e32 v23, v16, v16
	v_cvt_pk_bf16_f32 v13, v16, v17
	v_pk_add_f32 v[16:17], v[126:127], v[4:5]
	v_fmac_f32_e32 v3, v14, v14
	v_add_f32_e32 v2, v3, v2
	v_mul_f32_e32 v3, v17, v17
	v_fmac_f32_e32 v3, v16, v16
	v_add_f32_e32 v22, v23, v22
	v_add_f32_e32 v2, v3, v2
	v_add_f32_e32 v2, v22, v2
	v_mov_b32_e32 v3, v2
	v_mov_b32_e32 v252, v2
	s_nop 1
	v_permlane16_swap_b32_e32 v3, v252
	v_lshl_add_u64 v[18:19], v[18:19], 1, s[16:17]
	global_store_dwordx4 v[18:19], v[10:13], off
	global_store_dwordx4 v[20:21], v[6:9], off offset:512
	global_store_dwordx4 v[20:21], v[14:17], off offset:528
	v_cvt_pk_bf16_f32 v4, v6, v7
	v_cvt_pk_bf16_f32 v5, v8, v9
	s_waitcnt lgkmcnt(0)
	v_add_f32_e32 v2, v3, v252
	v_mov_b32_e32 v3, v2
	v_mov_b32_e32 v252, v2
	s_nop 1
	v_permlane32_swap_b32_e32 v3, v252
	v_cvt_pk_bf16_f32 v6, v14, v15
	v_cvt_pk_bf16_f32 v7, v16, v17
	global_store_dwordx4 v[18:19], v[4:7], off offset:256
	s_and_saveexec_b64 s[6:7], vcc
	s_cbranch_execz .LBB0_354
	s_add_u32 s54, s66, s31
	s_addc_u32 s55, s67, s30
	v_lshl_add_u64 v[4:5], v[50:51], 2, s[54:55]
	s_waitcnt lgkmcnt(0)
	v_add_f32_e32 v2, v3, v252
	global_store_dword v[4:5], v2, off
.LBB0_354:
	s_or_b64 exec, exec, s[6:7]
	v_add_u32_e32 v140, 0x80, v198
	v_ashrrev_i32_e32 v141, 31, v140
	s_waitcnt lgkmcnt(0)
	v_lshlrev_b64 v[2:3], 13, v[140:141]
	v_lshl_add_u64 v[2:3], v[200:201], 0, v[2:3]
	global_load_dwordx4 v[142:145], v[2:3], off offset:16
	global_load_dwordx4 v[146:149], v[2:3], off
	global_load_dwordx4 v[50:53], v[2:3], off offset:528
	global_load_dwordx4 v[54:57], v[2:3], off offset:512
	v_add_u32_e32 v128, 0x90, v198
	v_ashrrev_i32_e32 v129, 31, v128
	v_lshlrev_b64 v[2:3], 13, v[128:129]
	v_add_u32_e32 v126, 0xa0, v198
	v_lshl_add_u64 v[2:3], v[200:201], 0, v[2:3]
	v_ashrrev_i32_e32 v127, 31, v126
	global_load_dwordx4 v[42:45], v[2:3], off offset:16
	global_load_dwordx4 v[46:49], v[2:3], off
	global_load_dwordx4 v[34:37], v[2:3], off offset:528
	global_load_dwordx4 v[38:41], v[2:3], off offset:512
	v_lshlrev_b64 v[2:3], 13, v[126:127]
	v_add_u32_e32 v124, 0xb0, v198
	v_lshl_add_u64 v[2:3], v[200:201], 0, v[2:3]
	v_ashrrev_i32_e32 v125, 31, v124
	global_load_dwordx4 v[26:29], v[2:3], off offset:16
	global_load_dwordx4 v[30:33], v[2:3], off
	global_load_dwordx4 v[10:13], v[2:3], off offset:528
	global_load_dwordx4 v[18:21], v[2:3], off offset:512
	v_lshlrev_b64 v[2:3], 13, v[124:125]
	v_lshl_add_u64 v[6:7], v[200:201], 0, v[2:3]
	global_load_dwordx4 v[14:17], v[6:7], off offset:16
	global_load_dwordx4 v[22:25], v[6:7], off
	global_load_dwordx4 v[2:5], v[6:7], off offset:528
	s_nop 0
	global_load_dwordx4 v[6:9], v[6:7], off offset:512
	v_lshlrev_b64 v[150:151], 11, v[140:141]
	v_lshl_add_u64 v[150:151], v[150:151], 0, v[106:107]
	s_waitcnt vmcnt(14)
	v_pk_add_f32 v[148:149], v[116:117], v[148:149]
	v_pk_add_f32 v[146:147], v[118:119], v[146:147]
	s_waitcnt vmcnt(12)
	v_pk_add_f32 v[56:57], v[114:115], v[56:57]
	v_pk_add_f32 v[54:55], v[112:113], v[54:55]
	v_pk_add_f32 v[118:119], v[120:121], v[144:145]
	v_mul_f32_e32 v120, v147, v147
	v_mul_f32_e32 v121, v149, v149
	v_pk_add_f32 v[50:51], v[108:109], v[50:51]
	v_mul_f32_e32 v108, v55, v55
	v_mul_f32_e32 v109, v57, v57
	v_pk_add_f32 v[116:117], v[122:123], v[142:143]
	v_fmac_f32_e32 v120, v146, v146
	v_fmac_f32_e32 v121, v148, v148
	v_fmac_f32_e32 v108, v54, v54
	v_fmac_f32_e32 v109, v56, v56
	v_add_f32_e32 v120, v120, v121
	v_mul_f32_e32 v121, v117, v117
	v_add_f32_e32 v108, v108, v109
	v_mul_f32_e32 v109, v51, v51
	v_fmac_f32_e32 v121, v116, v116
	v_pk_add_f32 v[52:53], v[110:111], v[52:53]
	v_fmac_f32_e32 v109, v50, v50
	v_add_f32_e32 v120, v121, v120
	v_mul_f32_e32 v121, v119, v119
	v_add_f32_e32 v108, v109, v108
	v_mul_f32_e32 v109, v53, v53
	v_fmac_f32_e32 v121, v118, v118
	v_fmac_f32_e32 v109, v52, v52
	v_lshl_add_u64 v[142:143], v[150:151], 2, s[14:15]
	v_add_f32_e32 v144, v121, v120
	v_add_f32_e32 v108, v109, v108
	global_store_dwordx4 v[142:143], v[146:149], off
	global_store_dwordx4 v[142:143], v[116:119], off offset:16
	v_cvt_pk_bf16_f32 v120, v146, v147
	v_cvt_pk_bf16_f32 v121, v148, v149
	v_cvt_pk_bf16_f32 v122, v116, v117
	v_add_f32_e32 v108, v144, v108
	v_cvt_pk_bf16_f32 v123, v118, v119
	s_nop 0
	v_lshl_add_u64 v[116:117], v[150:151], 1, s[16:17]
	global_store_dwordx4 v[116:117], v[120:123], off
	global_store_dwordx4 v[142:143], v[54:57], off offset:512
	global_store_dwordx4 v[142:143], v[50:53], off offset:528
	s_nop 0
	v_cvt_pk_bf16_f32 v54, v54, v55
	v_cvt_pk_bf16_f32 v55, v56, v57
	v_cvt_pk_bf16_f32 v56, v50, v51
	v_mov_b32_e32 v50, v108
	v_mov_b32_e32 v252, v108
	s_nop 1
	v_permlane16_swap_b32_e32 v50, v252
	v_cvt_pk_bf16_f32 v57, v52, v53
	global_store_dwordx4 v[116:117], v[54:57], off offset:256
	s_waitcnt lgkmcnt(0)
	v_add_f32_e32 v50, v50, v252
	v_mov_b32_e32 v51, v50
	v_mov_b32_e32 v252, v50
	s_nop 1
	v_permlane32_swap_b32_e32 v51, v252
	s_and_saveexec_b64 s[6:7], vcc
	s_cbranch_execz .LBB0_356
	s_add_u32 s54, s66, s31
	s_addc_u32 s55, s67, s30
	v_lshl_add_u64 v[52:53], v[140:141], 2, s[54:55]
	s_waitcnt lgkmcnt(0)
	v_add_f32_e32 v50, v51, v252
	global_store_dword v[52:53], v50, off
; __device__ __forceinline__ u32x4 pack8(const f32x4 a, const f32x4 b) { u32x4 w; w.x = cvt_pk_bf16(a[0], a[1]); w.y = cvt_pk_bf16(a[2], a[3]); w.z = cvt_pk_bf16(b[0], b[1]); w.w = cvt_pk_bf16(b[2], b[3]); return w; }
;     __device__ __forceinline__ void operator()(const f32x4 (&acc)[2][2][4][2], const Unit& u, int wr, int wc, int fr, int fq) const {
;     ...
;             for (int m = 0; m < 4; ++m) {
;                 const int row = u.pm * BM + ai * HALF + wr * 64 + m * 16 + fr; float ss = 0.f;
; #pragma unroll
;                 for (int bj = 0; bj < 2; ++bj) {
;                     const size_t off = (size_t)row * DM + u.pn * BM + bj * HALF + wc * 32 + 8 * fq;
;                     const f32x4 a0 = xa[m][bj][0] + acc[ai][bj][m][0] * scale, a1 = xa[m][bj][1] + acc[ai][bj][m][1] * scale;
;                     *(f32x4*)(X + off) = a0; *(f32x4*)(X + off + 4) = a1;
;                     ss += (a0[0] * a0[0] + a0[1] * a0[1]) + (a0[2] * a0[2] + a0[3] * a0[3]) + (a1[0] * a1[0] + a1[1] * a1[1]) + (a1[2] * a1[2] + a1[3] * a1[3]);
;                     *(u32x4*)(XB + off) = pack8(a0, a1);
;                 }
;                 ss += __shfl_xor(ss, 16); ss += __shfl_xor(ss, 32);
;                 if (fq == 0) SSo[(size_t)(u.pn * 4 + wc) * MPAD + row] = ss;
.LBB0_356:
	s_or_b64 exec, exec, s[6:7]
	s_waitcnt vmcnt(16)
	v_pk_add_f32 v[48:49], v[104:105], v[48:49]
	v_pk_add_f32 v[46:47], v[102:103], v[46:47]
	s_waitcnt lgkmcnt(0)
	v_lshlrev_b64 v[50:51], 11, v[128:129]
	v_mul_f32_e32 v54, v47, v47
	v_mul_f32_e32 v55, v49, v49
	v_lshl_add_u64 v[50:51], v[50:51], 0, v[106:107]
	v_pk_add_f32 v[42:43], v[98:99], v[42:43]
	v_fmac_f32_e32 v54, v46, v46
	v_fmac_f32_e32 v55, v48, v48
	v_lshl_add_u64 v[52:53], v[50:51], 2, s[14:15]
	v_add_f32_e32 v54, v54, v55
	v_mul_f32_e32 v55, v43, v43
	s_waitcnt vmcnt(14)
	v_pk_add_f32 v[40:41], v[96:97], v[40:41]
	v_pk_add_f32 v[38:39], v[94:95], v[38:39]
	v_pk_add_f32 v[44:45], v[100:101], v[44:45]
	global_store_dwordx4 v[52:53], v[46:49], off
	global_store_dwordx4 v[52:53], v[42:45], off offset:16
	v_fmac_f32_e32 v55, v42, v42
	v_cvt_pk_bf16_f32 v46, v46, v47
	v_cvt_pk_bf16_f32 v47, v48, v49
	v_cvt_pk_bf16_f32 v48, v42, v43
	v_add_f32_e32 v54, v55, v54
	v_pk_add_f32 v[42:43], v[90:91], v[34:35]
	v_mul_f32_e32 v34, v39, v39
	v_mul_f32_e32 v35, v41, v41
	v_fmac_f32_e32 v34, v38, v38
	v_fmac_f32_e32 v35, v40, v40
	v_mul_f32_e32 v55, v45, v45
	v_add_f32_e32 v34, v34, v35
	v_mul_f32_e32 v35, v43, v43
	v_fmac_f32_e32 v55, v44, v44
	v_cvt_pk_bf16_f32 v49, v44, v45
	v_pk_add_f32 v[44:45], v[92:93], v[36:37]
	v_fmac_f32_e32 v35, v42, v42
	v_add_f32_e32 v34, v35, v34
	v_mul_f32_e32 v35, v45, v45
	v_fmac_f32_e32 v35, v44, v44
	v_add_f32_e32 v54, v55, v54
	v_add_f32_e32 v34, v35, v34
	v_add_f32_e32 v34, v54, v34
	v_mov_b32_e32 v35, v34
	v_mov_b32_e32 v252, v34
	s_nop 1
	v_permlane16_swap_b32_e32 v35, v252
	v_lshl_add_u64 v[50:51], v[50:51], 1, s[16:17]
	global_store_dwordx4 v[50:51], v[46:49], off
	global_store_dwordx4 v[52:53], v[38:41], off offset:512
	global_store_dwordx4 v[52:53], v[42:45], off offset:528
	v_cvt_pk_bf16_f32 v36, v38, v39
	v_cvt_pk_bf16_f32 v37, v40, v41
	s_waitcnt lgkmcnt(0)
	v_add_f32_e32 v34, v35, v252
	v_mov_b32_e32 v35, v34
	v_mov_b32_e32 v252, v34
	s_nop 1
	v_permlane32_swap_b32_e32 v35, v252
	v_cvt_pk_bf16_f32 v38, v42, v43
	v_cvt_pk_bf16_f32 v39, v44, v45
	global_store_dwordx4 v[50:51], v[36:39], off offset:256
	s_and_saveexec_b64 s[6:7], vcc
	s_cbranch_execz .LBB0_358
	s_add_u32 s54, s66, s31
	s_addc_u32 s55, s67, s30
	v_lshl_add_u64 v[36:37], v[128:129], 2, s[54:55]
	s_waitcnt lgkmcnt(0)
	v_add_f32_e32 v34, v35, v252
	global_store_dword v[36:37], v34, off
; __device__ __forceinline__ u32x4 pack8(const f32x4 a, const f32x4 b) { u32x4 w; w.x = cvt_pk_bf16(a[0], a[1]); w.y = cvt_pk_bf16(a[2], a[3]); w.z = cvt_pk_bf16(b[0], b[1]); w.w = cvt_pk_bf16(b[2], b[3]); return w; }
;     __device__ __forceinline__ void operator()(const f32x4 (&acc)[2][2][4][2], const Unit& u, int wr, int wc, int fr, int fq) const {
;     ...
;             for (int m = 0; m < 4; ++m) {
;                 const int row = u.pm * BM + ai * HALF + wr * 64 + m * 16 + fr; float ss = 0.f;
; #pragma unroll
;                 for (int bj = 0; bj < 2; ++bj) {
;                     const size_t off = (size_t)row * DM + u.pn * BM + bj * HALF + wc * 32 + 8 * fq;
;                     const f32x4 a0 = xa[m][bj][0] + acc[ai][bj][m][0] * scale, a1 = xa[m][bj][1] + acc[ai][bj][m][1] * scale;
;                     *(f32x4*)(X + off) = a0; *(f32x4*)(X + off + 4) = a1;
;                     ss += (a0[0] * a0[0] + a0[1] * a0[1]) + (a0[2] * a0[2] + a0[3] * a0[3]) + (a1[0] * a1[0] + a1[1] * a1[1]) + (a1[2] * a1[2] + a1[3] * a1[3]);
;                     *(u32x4*)(XB + off) = pack8(a0, a1);
;                 }
;                 ss += __shfl_xor(ss, 16); ss += __shfl_xor(ss, 32);
;                 if (fq == 0) SSo[(size_t)(u.pn * 4 + wc) * MPAD + row] = ss;
.LBB0_358:
	s_or_b64 exec, exec, s[6:7]
	s_waitcnt vmcnt(18)
	v_pk_add_f32 v[32:33], v[88:89], v[32:33]
	v_pk_add_f32 v[30:31], v[86:87], v[30:31]
	s_waitcnt lgkmcnt(0)
	v_lshlrev_b64 v[34:35], 11, v[126:127]
	v_mul_f32_e32 v38, v31, v31
	v_mul_f32_e32 v39, v33, v33
	v_lshl_add_u64 v[34:35], v[34:35], 0, v[106:107]
	v_pk_add_f32 v[26:27], v[82:83], v[26:27]
	v_fmac_f32_e32 v38, v30, v30
	v_fmac_f32_e32 v39, v32, v32
	v_lshl_add_u64 v[36:37], v[34:35], 2, s[14:15]
	v_add_f32_e32 v38, v38, v39
	v_mul_f32_e32 v39, v27, v27
	s_waitcnt vmcnt(16)
	v_pk_add_f32 v[20:21], v[80:81], v[20:21]
	v_pk_add_f32 v[18:19], v[78:79], v[18:19]
	v_pk_add_f32 v[28:29], v[84:85], v[28:29]
	global_store_dwordx4 v[36:37], v[30:33], off
	global_store_dwordx4 v[36:37], v[26:29], off offset:16
	v_fmac_f32_e32 v39, v26, v26
	v_cvt_pk_bf16_f32 v30, v30, v31
	v_cvt_pk_bf16_f32 v31, v32, v33
	v_cvt_pk_bf16_f32 v32, v26, v27
	v_add_f32_e32 v38, v39, v38
	v_pk_add_f32 v[26:27], v[74:75], v[10:11]
	v_mul_f32_e32 v10, v19, v19
	v_mul_f32_e32 v11, v21, v21
	v_fmac_f32_e32 v10, v18, v18
	v_fmac_f32_e32 v11, v20, v20
	v_mul_f32_e32 v39, v29, v29
	v_add_f32_e32 v10, v10, v11
	v_mul_f32_e32 v11, v27, v27
	v_fmac_f32_e32 v39, v28, v28
	v_cvt_pk_bf16_f32 v33, v28, v29
	v_pk_add_f32 v[28:29], v[76:77], v[12:13]
	v_fmac_f32_e32 v11, v26, v26
	v_add_f32_e32 v10, v11, v10
	v_mul_f32_e32 v11, v29, v29
	v_fmac_f32_e32 v11, v28, v28
	v_add_f32_e32 v38, v39, v38
	v_add_f32_e32 v10, v11, v10
	v_add_f32_e32 v10, v38, v10
	v_mov_b32_e32 v11, v10
	v_mov_b32_e32 v252, v10
	s_nop 1
	v_permlane16_swap_b32_e32 v11, v252
	v_lshl_add_u64 v[34:35], v[34:35], 1, s[16:17]
	global_store_dwordx4 v[34:35], v[30:33], off
	global_store_dwordx4 v[36:37], v[18:21], off offset:512
	global_store_dwordx4 v[36:37], v[26:29], off offset:528
	s_waitcnt lgkmcnt(0)
	v_add_f32_e32 v10, v11, v252
	v_mov_b32_e32 v11, v10
	v_mov_b32_e32 v252, v10
	s_nop 1
	v_permlane32_swap_b32_e32 v11, v252
	v_cvt_pk_bf16_f32 v18, v18, v19
	v_cvt_pk_bf16_f32 v19, v20, v21
	v_cvt_pk_bf16_f32 v20, v26, v27
	v_cvt_pk_bf16_f32 v21, v28, v29
	global_store_dwordx4 v[34:35], v[18:21], off offset:256
	s_and_saveexec_b64 s[6:7], vcc
	s_cbranch_execz .LBB0_360
	s_add_u32 s54, s66, s31
	s_addc_u32 s55, s67, s30
	v_lshl_add_u64 v[12:13], v[126:127], 2, s[54:55]
	s_waitcnt lgkmcnt(0)
	v_add_f32_e32 v10, v11, v252
	global_store_dword v[12:13], v10, off
.LBB0_360:
	s_or_b64 exec, exec, s[6:7]
	s_waitcnt lgkmcnt(0)
	v_lshlrev_b64 v[10:11], 11, v[124:125]
	v_lshl_add_u64 v[18:19], v[10:11], 0, v[106:107]
	s_waitcnt vmcnt(20)
	v_pk_add_f32 v[12:13], v[72:73], v[24:25]
	v_pk_add_f32 v[10:11], v[70:71], v[22:23]
	v_mul_f32_e32 v23, v13, v13
	v_mul_f32_e32 v22, v11, v11
	v_pk_add_f32 v[14:15], v[66:67], v[14:15]
	v_fmac_f32_e32 v22, v10, v10
	v_fmac_f32_e32 v23, v12, v12
	v_lshl_add_u64 v[20:21], v[18:19], 2, s[14:15]
	v_add_f32_e32 v22, v22, v23
	v_mul_f32_e32 v23, v15, v15
	s_waitcnt vmcnt(18)
	v_pk_add_f32 v[8:9], v[64:65], v[8:9]
	v_pk_add_f32 v[6:7], v[62:63], v[6:7]
	v_pk_add_f32 v[16:17], v[68:69], v[16:17]
	global_store_dwordx4 v[20:21], v[10:13], off
	global_store_dwordx4 v[20:21], v[14:17], off offset:16
	v_fmac_f32_e32 v23, v14, v14
	v_cvt_pk_bf16_f32 v10, v10, v11
	v_cvt_pk_bf16_f32 v11, v12, v13
	v_cvt_pk_bf16_f32 v12, v14, v15
	v_add_f32_e32 v22, v23, v22
	v_pk_add_f32 v[14:15], v[58:59], v[2:3]
	v_mul_f32_e32 v2, v7, v7
	v_mul_f32_e32 v3, v9, v9
	v_fmac_f32_e32 v2, v6, v6
	v_fmac_f32_e32 v3, v8, v8
	v_mul_f32_e32 v23, v17, v17
	v_add_f32_e32 v2, v2, v3
	v_mul_f32_e32 v3, v15, v15
	v_fmac_f32_e32 v23, v16, v16
	v_cvt_pk_bf16_f32 v13, v16, v17
	v_pk_add_f32 v[16:17], v[60:61], v[4:5]
	v_fmac_f32_e32 v3, v14, v14
	v_add_f32_e32 v2, v3, v2
	v_mul_f32_e32 v3, v17, v17
	v_fmac_f32_e32 v3, v16, v16
	v_add_f32_e32 v22, v23, v22
	v_add_f32_e32 v2, v3, v2
	v_add_f32_e32 v2, v22, v2
	v_mov_b32_e32 v3, v2
	v_mov_b32_e32 v252, v2
	s_nop 1
	v_permlane16_swap_b32_e32 v3, v252
	v_lshl_add_u64 v[18:19], v[18:19], 1, s[16:17]
	global_store_dwordx4 v[18:19], v[10:13], off
	global_store_dwordx4 v[20:21], v[6:9], off offset:512
	global_store_dwordx4 v[20:21], v[14:17], off offset:528
	v_cvt_pk_bf16_f32 v4, v6, v7
	v_cvt_pk_bf16_f32 v5, v8, v9
	s_waitcnt lgkmcnt(0)
	v_add_f32_e32 v2, v3, v252
	v_mov_b32_e32 v3, v2
	v_mov_b32_e32 v252, v2
	s_nop 1
	v_permlane32_swap_b32_e32 v3, v252
	v_cvt_pk_bf16_f32 v6, v14, v15
	v_cvt_pk_bf16_f32 v7, v16, v17
	global_store_dwordx4 v[18:19], v[4:7], off offset:256
	s_and_saveexec_b64 s[6:7], vcc
	s_cbranch_execz .LBB0_362
	s_add_u32 s54, s66, s31
	s_addc_u32 s55, s67, s30
	v_lshl_add_u64 v[4:5], v[124:125], 2, s[54:55]
	s_waitcnt lgkmcnt(0)
	v_add_f32_e32 v2, v3, v252
	global_store_dword v[4:5], v2, off

; template <int NSL>
; __device__ __forceinline__ void phase_samp_fin(KArgs a, float scale, int gw, int NGW, int lane) {
;     ...
;         const int rl = it >> 3, pn = it & 7, col = pn * 256 + lane * 4;
;         f32x4 p[NSL];
; #pragma unroll
;         for (int s2 = 0; s2 < NSL; ++s2) p[s2] = *(const f32x4*)(PS + ((size_t)s2 * 128 + rl) * DM + col);
;         const size_t off = (size_t)(MPROMPT + rl) * DM + col; f32x4 x = *(const f32x4*)(X + off); f32x4 s = p[0];
; #pragma unroll
;         for (int s2 = 1; s2 < NSL; ++s2) s = s + p[s2];
.LBB0_443:
	s_ashr_i32 s12, s2, 3
	s_ashr_i32 s13, s12, 31
	s_and_b32 s18, s2, 7
	s_lshl_b64 s[14:15], s[12:13], 13
	v_lshl_or_b32 v92, s18, 8, v2
	s_add_u32 s14, s16, s14
	s_addc_u32 s15, s17, s15
	v_lshlrev_b32_e32 v0, 2, v92
	v_lshl_add_u64 v[88:89], s[14:15], 0, v[0:1]
	v_add_co_u32_e32 v8, vcc, s45, v88
	s_waitcnt lgkmcnt(0)
	global_load_dwordx4 v[4:7], v0, s[14:15]
	v_addc_co_u32_e32 v9, vcc, 0, v89, vcc
	v_add_co_u32_e32 v12, vcc, s39, v88
	s_mov_b32 s14, 0x900000
	s_nop 0
	v_addc_co_u32_e32 v13, vcc, 0, v89, vcc
	v_add_co_u32_e32 v16, vcc, s47, v88
	global_load_dwordx4 v[8:11], v[8:9], off
	s_nop 0
	global_load_dwordx4 v[12:15], v[12:13], off
	v_addc_co_u32_e32 v17, vcc, 0, v89, vcc
	v_add_co_u32_e32 v20, vcc, s77, v88
	s_waitcnt vmcnt(1)
	v_pk_add_f32 v[6:7], v[6:7], v[10:11]
	v_addc_co_u32_e32 v21, vcc, 0, v89, vcc
	v_add_co_u32_e32 v24, vcc, s35, v88
	global_load_dwordx4 v[16:19], v[16:17], off
	s_nop 0
	global_load_dwordx4 v[20:23], v[20:21], off
	v_addc_co_u32_e32 v25, vcc, 0, v89, vcc
	v_add_co_u32_e32 v28, vcc, s74, v88
	v_pk_add_f32 v[4:5], v[4:5], v[8:9]
	s_nop 0
	v_addc_co_u32_e32 v29, vcc, 0, v89, vcc
	v_add_co_u32_e32 v32, vcc, s66, v88
	global_load_dwordx4 v[24:27], v[24:25], off
	s_nop 0
	global_load_dwordx4 v[28:31], v[28:29], off
	v_addc_co_u32_e32 v33, vcc, 0, v89, vcc
	v_add_co_u32_e32 v36, vcc, s37, v88
	s_waitcnt vmcnt(4)
	v_pk_add_f32 v[6:7], v[6:7], v[14:15]
	v_addc_co_u32_e32 v37, vcc, 0, v89, vcc
	v_add_co_u32_e32 v40, vcc, s14, v88
	s_mov_b32 s14, 0xb00000
	s_nop 0
	v_addc_co_u32_e32 v41, vcc, 0, v89, vcc
	v_add_co_u32_e32 v44, vcc, s97, v88
	global_load_dwordx4 v[32:35], v[32:33], off
	s_nop 0
	global_load_dwordx4 v[36:39], v[36:37], off
	v_addc_co_u32_e32 v45, vcc, 0, v89, vcc
	v_add_co_u32_e32 v48, vcc, s14, v88
	s_mov_b32 s14, 0xd00000
	s_nop 0
	v_addc_co_u32_e32 v49, vcc, 0, v89, vcc
	v_add_co_u32_e32 v52, vcc, s56, v88
	global_load_dwordx4 v[40:43], v[40:41], off
	s_nop 0
	global_load_dwordx4 v[44:47], v[44:45], off
	v_addc_co_u32_e32 v53, vcc, 0, v89, vcc
	v_add_co_u32_e32 v56, vcc, s14, v88
	s_mov_b32 s14, 0xf00000
	s_nop 0
	v_addc_co_u32_e32 v57, vcc, 0, v89, vcc
	v_add_co_u32_e32 v60, vcc, s57, v88
	global_load_dwordx4 v[48:51], v[48:49], off
	s_nop 0
	global_load_dwordx4 v[52:55], v[52:53], off
	v_addc_co_u32_e32 v61, vcc, 0, v89, vcc
	v_add_co_u32_e32 v64, vcc, s14, v88
	s_mov_b32 s14, 0x1000000
	s_nop 0
	v_addc_co_u32_e32 v65, vcc, 0, v89, vcc
	v_add_co_u32_e32 v68, vcc, s14, v88
	s_mov_b32 s14, 0x1100000
	s_nop 0
	v_addc_co_u32_e32 v69, vcc, 0, v89, vcc
	v_add_co_u32_e32 v72, vcc, s14, v88
	s_mov_b32 s14, 0x1200000
	s_nop 0
	v_addc_co_u32_e32 v73, vcc, 0, v89, vcc
	v_add_co_u32_e32 v76, vcc, s14, v88
	s_mov_b32 s14, 0x1300000
	s_nop 0
	v_addc_co_u32_e32 v77, vcc, 0, v89, vcc
	v_add_co_u32_e32 v80, vcc, s14, v88
	global_load_dwordx4 v[56:59], v[56:57], off
	s_nop 0
	global_load_dwordx4 v[60:63], v[60:61], off
	v_addc_co_u32_e32 v81, vcc, 0, v89, vcc
	s_mov_b32 s14, 0x1400000
	v_add_co_u32_e32 v84, vcc, s14, v88
	global_load_dwordx4 v[64:67], v[64:65], off
	s_nop 0
	global_load_dwordx4 v[68:71], v[68:69], off
	v_addc_co_u32_e32 v85, vcc, 0, v89, vcc
	s_mov_b32 s14, 0x1500000
	v_add_co_u32_e32 v88, vcc, s14, v88
	s_lshl_b64 s[14:15], s[12:13], 11
	global_load_dwordx4 v[72:75], v[72:73], off
	s_nop 0
	global_load_dwordx4 v[76:79], v[76:77], off
	s_add_u32 s14, s14, 0x1000000
	s_addc_u32 s15, s15, 0
	global_load_dwordx4 v[80:83], v[80:81], off
	s_nop 0
	global_load_dwordx4 v[84:87], v[84:85], off
	v_addc_co_u32_e32 v89, vcc, 0, v89, vcc
	v_or_b32_e32 v96, s14, v92
	v_mov_b32_e32 v97, s15
	global_load_dwordx4 v[88:91], v[88:89], off
	v_lshl_add_u64 v[98:99], v[96:97], 2, s[10:11]
	global_load_dwordx4 v[92:95], v[98:99], off
	v_pk_add_f32 v[4:5], v[4:5], v[12:13]
	s_waitcnt vmcnt(19)
; __device__ __forceinline__ unsigned cvtpk(float lo, float hi) { unsigned r; asm volatile("v_cvt_pk_bf16_f32 %0, %1, %2" : "=v"(r) : "v"(lo), "v"(hi)); return r; }
; template <int NSL>
; __device__ __forceinline__ void phase_samp_fin(KArgs a, float scale, int gw, int NGW, int lane) {
;     ...
;         for (int s2 = 0; s2 < NSL; ++s2) p[s2] = *(const f32x4*)(PS + ((size_t)s2 * 128 + rl) * DM + col);
;         const size_t off = (size_t)(MPROMPT + rl) * DM + col; f32x4 x = *(const f32x4*)(X + off); f32x4 s = p[0];
; #pragma unroll
;         for (int s2 = 1; s2 < NSL; ++s2) s = s + p[s2];
;         x = x + s * scale; *(f32x4*)(X + off) = x;
;         u32x2 w; w.x = cvtpk(x[0], x[1]); w.y = cvtpk(x[2], x[3]); *(u32x2*)(XB + off) = w;
;         float ss = (x[0] * x[0] + x[1] * x[1]) + (x[2] * x[2] + x[3] * x[3]);
;         ss += __shfl_xor(ss, 1); ss += __shfl_xor(ss, 2); ss += __shfl_xor(ss, 4); ss += __shfl_xor(ss, 8);
;         if ((lane & 15) == 0) SS[(size_t)(pn * 4 + (lane >> 4)) * MPAD + MPROMPT + rl] = ss;
	v_pk_add_f32 v[6:7], v[6:7], v[18:19]
	v_pk_add_f32 v[4:5], v[4:5], v[16:17]
	s_waitcnt vmcnt(18)
	v_pk_add_f32 v[6:7], v[6:7], v[22:23]
	v_pk_add_f32 v[4:5], v[4:5], v[20:21]
	s_waitcnt vmcnt(17)
	v_pk_add_f32 v[6:7], v[6:7], v[26:27]
	v_pk_add_f32 v[4:5], v[4:5], v[24:25]
	s_waitcnt vmcnt(16)
	v_pk_add_f32 v[6:7], v[6:7], v[30:31]
	v_pk_add_f32 v[4:5], v[4:5], v[28:29]
	s_waitcnt vmcnt(15)
	v_pk_add_f32 v[6:7], v[6:7], v[34:35]
	v_pk_add_f32 v[4:5], v[4:5], v[32:33]
	s_waitcnt vmcnt(14)
	v_pk_add_f32 v[6:7], v[6:7], v[38:39]
	v_pk_add_f32 v[4:5], v[4:5], v[36:37]
	s_waitcnt vmcnt(13)
	v_pk_add_f32 v[6:7], v[6:7], v[42:43]
	v_pk_add_f32 v[4:5], v[4:5], v[40:41]
	s_waitcnt vmcnt(12)
	v_pk_add_f32 v[6:7], v[6:7], v[46:47]
	v_pk_add_f32 v[4:5], v[4:5], v[44:45]
	s_waitcnt vmcnt(11)
	v_pk_add_f32 v[6:7], v[6:7], v[50:51]
	v_pk_add_f32 v[4:5], v[4:5], v[48:49]
	s_waitcnt vmcnt(10)
	v_pk_add_f32 v[6:7], v[6:7], v[54:55]
	v_pk_add_f32 v[4:5], v[4:5], v[52:53]
	s_waitcnt vmcnt(9)
	v_pk_add_f32 v[6:7], v[6:7], v[58:59]
	v_pk_add_f32 v[4:5], v[4:5], v[56:57]
	s_waitcnt vmcnt(8)
	v_pk_add_f32 v[6:7], v[6:7], v[62:63]
	v_pk_add_f32 v[4:5], v[4:5], v[60:61]
	s_waitcnt vmcnt(7)
	v_pk_add_f32 v[6:7], v[6:7], v[66:67]
	v_pk_add_f32 v[4:5], v[4:5], v[64:65]
	s_waitcnt vmcnt(6)
	v_pk_add_f32 v[6:7], v[6:7], v[70:71]
	v_pk_add_f32 v[4:5], v[4:5], v[68:69]
	s_waitcnt vmcnt(5)
	v_pk_add_f32 v[6:7], v[6:7], v[74:75]
	v_pk_add_f32 v[4:5], v[4:5], v[72:73]
	s_waitcnt vmcnt(4)
	v_pk_add_f32 v[6:7], v[6:7], v[78:79]
	v_pk_add_f32 v[4:5], v[4:5], v[76:77]
	s_waitcnt vmcnt(3)
	v_pk_add_f32 v[6:7], v[6:7], v[82:83]
	v_pk_add_f32 v[4:5], v[4:5], v[80:81]
	s_waitcnt vmcnt(2)
	v_pk_add_f32 v[6:7], v[6:7], v[86:87]
	v_pk_add_f32 v[4:5], v[4:5], v[84:85]
	s_waitcnt vmcnt(1)
	v_pk_add_f32 v[6:7], v[6:7], v[90:91]
	v_pk_add_f32 v[4:5], v[4:5], v[88:89]
	s_waitcnt vmcnt(0)
	v_pk_fma_f32 v[8:9], v[6:7], 0.5, v[94:95] op_sel_hi:[1,0,1]
	v_pk_fma_f32 v[6:7], v[4:5], 0.5, v[92:93] op_sel_hi:[1,0,1]
	v_mul_f32_e32 v4, v9, v9
	v_mul_f32_e32 v0, v7, v7
	v_fmac_f32_e32 v0, v6, v6
	v_fmac_f32_e32 v4, v8, v8
	v_and_b32_e32 v5, 64, v219
	v_add_f32_e32 v0, v0, v4
	v_xor_b32_e32 v4, 1, v219
	v_add_u32_e32 v5, 64, v5
	v_cmp_lt_i32_e32 vcc, v4, v5
	global_store_dwordx4 v[98:99], v[6:9], off
	s_nop 0
	v_cndmask_b32_e32 v4, v219, v4, vcc
	v_lshlrev_b32_e32 v4, 2, v4
	s_nop 1
	v_add_f32_dpp v4, v0, v0 quad_perm:[1,0,3,2] row_mask:0xf bank_mask:0xf
	v_cvt_pk_bf16_f32 v6, v6, v7
	v_cvt_pk_bf16_f32 v7, v8, v9
	v_lshl_add_u64 v[8:9], v[96:97], 1, s[8:9]
	global_store_dwordx2 v[8:9], v[6:7], off
	s_waitcnt lgkmcnt(0)
	v_mov_b32_e32 v0, v4
	v_xor_b32_e32 v4, 2, v219
	v_cmp_lt_i32_e32 vcc, v4, v5
	s_nop 1
	v_cndmask_b32_e32 v4, v219, v4, vcc
	v_lshlrev_b32_e32 v4, 2, v4
	s_nop 1
	v_add_f32_dpp v4, v0, v0 quad_perm:[2,3,0,1] row_mask:0xf bank_mask:0xf
	s_waitcnt lgkmcnt(0)
	v_mov_b32_e32 v0, v4
	v_xor_b32_e32 v4, 4, v219
	v_cmp_lt_i32_e32 vcc, v4, v5
	s_nop 1
	v_cndmask_b32_e32 v4, v219, v4, vcc
	v_lshlrev_b32_e32 v4, 2, v4
	s_nop 1
	v_add_f32_dpp v4, v0, v0 row_half_mirror row_mask:0xf bank_mask:0xf
	s_waitcnt lgkmcnt(0)
	v_mov_b32_e32 v0, v4
	v_xor_b32_e32 v4, 8, v219
	v_cmp_lt_i32_e32 vcc, v4, v5
	s_nop 1
	v_cndmask_b32_e32 v4, v219, v4, vcc
	v_lshlrev_b32_e32 v4, 2, v4
	s_nop 1
	v_add_f32_dpp v4, v0, v0 row_mirror row_mask:0xf bank_mask:0xf
	s_and_saveexec_b64 s[14:15], s[4:5]
	s_cbranch_execz .LBB0_442
	s_waitcnt lgkmcnt(0)
	v_mov_b32_e32 v6, v4
	v_lshl_or_b32 v0, s18, 2, v3
	v_mul_u32_u24_e32 v0, 0x2100, v0
	v_lshlrev_b32_e32 v0, 2, v0
	v_lshl_add_u64 v[4:5], s[6:7], 0, v[0:1]
	v_lshl_add_u64 v[4:5], s[12:13], 2, v[4:5]
	v_add_co_u32_e32 v4, vcc, 0x8000, v4
	s_nop 1
	v_addc_co_u32_e32 v5, vcc, 0, v5, vcc
	global_store_dword v[4:5], v6, off
	s_branch .LBB0_442

; __device__ __forceinline__ void rows_rstd(const float* SS, const Unit& u, int wr, int fr, int fq, float (&rs)[2][4]) {
;     ...
;             for (int m = 0; m < 4; ++m) {
;                 const int row = u.pm * BM + ai * HALF + wr * 64 + m * 16 + fr; float s = 0.f;
; #pragma unroll
;                 for (int j = 0; j < 8; ++j) s += SS[(size_t)(fq * 8 + j) * MPAD + row];
;                 s += __shfl_xor(s, 16); s += __shfl_xor(s, 32);
;                 rs[ai][m] = 1.0f / sqrtf(s * (1.0f / 2048.0f) + RMS_EPS);
.LBB0_525:
	s_lshl_b32 s6, s48, 8
	v_mov_b32_e32 v141, v189
	v_mov_b32_e32 v140, v194
	s_add_i32 s6, s6, s56
	s_cmp_lt_i32 s48, 32
	v_add_u32_e32 v170, s6, v140
	v_add_u32_e32 v152, 16, v170
	v_add_u32_e32 v150, 32, v170
	v_add_u32_e32 v148, 48, v170
	v_add_u32_e32 v146, 0x80, v170
	v_add_u32_e32 v144, 0x90, v170
	v_add_u32_e32 v142, 0xa0, v170
	s_mov_b64 s[6:7], -1
	v_ashrrev_i32_e32 v171, 31, v170
	v_lshlrev_b32_e32 v155, 3, v141
	v_ashrrev_i32_e32 v153, 31, v152
	v_ashrrev_i32_e32 v151, 31, v150
	v_ashrrev_i32_e32 v149, 31, v148
	v_ashrrev_i32_e32 v147, 31, v146
	v_ashrrev_i32_e32 v145, 31, v144
	v_ashrrev_i32_e32 v143, 31, v142
	v_add_u32_e32 v140, 0xb0, v170
	s_cbranch_scc1 .LBB0_527
	v_and_b32_e32 v154, 64, v219
	v_lshlrev_b32_e32 v157, 3, v141
	v_xor_b32_e32 v141, 16, v219
	v_add_u32_e32 v154, 64, v154
	v_cmp_lt_i32_e32 vcc, v141, v154
	v_lshl_add_u64 v[174:175], v[170:171], 2, s[18:19]
	v_mad_i64_i32 v[162:163], s[6:7], v157, s46, v[174:175]
	v_cndmask_b32_e32 v141, v219, v141, vcc
	v_lshlrev_b32_e32 v160, 2, v141
	v_xor_b32_e32 v141, 32, v219
	v_cmp_lt_i32_e32 vcc, v141, v154
	v_or_b32_e32 v161, 1, v157
	s_nop 0
	v_cndmask_b32_e32 v141, v219, v141, vcc
	v_lshlrev_b32_e32 v159, 2, v141
	global_load_dword v208, v[162:163], off
	v_mad_i64_i32 v[162:163], s[6:7], v161, s46, v[174:175]
	global_load_dword v209, v[162:163], off
	v_or_b32_e32 v163, 2, v157
	v_mad_i64_i32 v[164:165], s[6:7], v163, s46, v[174:175]
	global_load_dword v210, v[164:165], off
	v_or_b32_e32 v165, 3, v157
	v_mad_i64_i32 v[166:167], s[6:7], v165, s46, v[174:175]
	global_load_dword v211, v[166:167], off
	v_or_b32_e32 v166, 4, v157
	v_mad_i64_i32 v[168:169], s[6:7], v166, s46, v[174:175]
	v_or_b32_e32 v167, 5, v157
	global_load_dword v212, v[168:169], off
	v_mad_i64_i32 v[168:169], s[6:7], v167, s46, v[174:175]
	global_load_dword v213, v[168:169], off
	v_or_b32_e32 v169, 6, v157
	v_mad_i64_i32 v[172:173], s[6:7], v169, s46, v[174:175]
	global_load_dword v214, v[172:173], off
	v_or_b32_e32 v173, 7, v157
	v_mad_i64_i32 v[174:175], s[6:7], v173, s46, v[174:175]
	global_load_dword v215, v[174:175], off
	v_lshl_add_u64 v[174:175], v[152:153], 2, s[18:19]
	s_waitcnt vmcnt(0)
	v_add_f32_e32 v141, 0, v208
	v_add_f32_e32 v141, v141, v209
	v_add_f32_e32 v141, v141, v210
	v_add_f32_e32 v141, v141, v211
	v_add_f32_e32 v141, v141, v212
	v_add_f32_e32 v141, v141, v213
	v_add_f32_e32 v141, v141, v214
	v_add_f32_e32 v141, v141, v215
	v_mov_b32_e32 v154, v141
	v_mov_b32_e32 v216, v141
	s_nop 1
	v_permlane16_swap_b32_e32 v154, v216
	s_waitcnt lgkmcnt(0)
	v_add_f32_e32 v141, v154, v216
	v_mov_b32_e32 v154, v141
	v_mov_b32_e32 v216, v141
	s_nop 1
	v_permlane32_swap_b32_e32 v154, v216
	s_waitcnt lgkmcnt(0)
	v_add_f32_e32 v141, v154, v216
	v_fmamk_f32 v141, v141, 0x3a000000, v220
	v_cmp_gt_f32_e32 vcc, s43, v141
	v_mul_f32_e32 v154, 0x4f800000, v141
	s_nop 0
	v_cndmask_b32_e32 v141, v141, v154, vcc
	v_sqrt_f32_e32 v154, v141
	s_nop 0
	v_add_u32_e32 v156, -1, v154
	v_fma_f32 v158, -v156, v154, v141
	v_cmp_ge_f32_e64 s[6:7], 0, v158
	v_add_u32_e32 v158, 1, v154
	s_nop 0
	v_cndmask_b32_e64 v156, v154, v156, s[6:7]
	v_fma_f32 v154, -v158, v154, v141
	v_cmp_lt_f32_e64 s[6:7], 0, v154
	s_nop 1
	v_cndmask_b32_e64 v154, v156, v158, s[6:7]
	v_mul_f32_e32 v156, 0x37800000, v154
	v_cndmask_b32_e32 v154, v154, v156, vcc
	v_cmp_class_f32_e32 vcc, v141, v221
	v_mad_i64_i32 v[176:177], s[6:7], v157, s46, v[174:175]
	s_nop 0
	v_cndmask_b32_e32 v141, v154, v141, vcc
	v_div_scale_f32 v154, s[6:7], v141, v141, 1.0
	v_rcp_f32_e32 v156, v154
	s_nop 0
	v_fma_f32 v158, -v154, v156, 1.0
	v_fmac_f32_e32 v156, v158, v156
	v_div_scale_f32 v158, vcc, 1.0, v141, 1.0
	v_mul_f32_e32 v162, v158, v156
	v_fma_f32 v164, -v154, v162, v158
	v_fmac_f32_e32 v162, v164, v156
	v_fma_f32 v154, -v154, v162, v158
	v_div_fmas_f32 v154, v154, v156, v162
	v_div_fixup_f32 v172, v154, v141, 1.0
	global_load_dword v208, v[176:177], off
	v_mad_i64_i32 v[176:177], s[6:7], v161, s46, v[174:175]
	global_load_dword v209, v[176:177], off
	v_mad_i64_i32 v[176:177], s[6:7], v163, s46, v[174:175]
	global_load_dword v210, v[176:177], off
	v_mad_i64_i32 v[176:177], s[6:7], v165, s46, v[174:175]
	global_load_dword v211, v[176:177], off
	v_mad_i64_i32 v[176:177], s[6:7], v166, s46, v[174:175]
	global_load_dword v212, v[176:177], off
	v_mad_i64_i32 v[176:177], s[6:7], v167, s46, v[174:175]
	global_load_dword v213, v[176:177], off
	v_mad_i64_i32 v[176:177], s[6:7], v169, s46, v[174:175]
	v_mad_i64_i32 v[174:175], s[6:7], v173, s46, v[174:175]
	global_load_dword v214, v[176:177], off
	global_load_dword v215, v[174:175], off
	v_lshl_add_u64 v[174:175], v[150:151], 2, s[18:19]
	s_waitcnt vmcnt(0)
	v_add_f32_e32 v141, 0, v208
	v_add_f32_e32 v141, v141, v209
	v_add_f32_e32 v141, v141, v210
	v_add_f32_e32 v141, v141, v211
	v_add_f32_e32 v141, v141, v212
	v_add_f32_e32 v141, v141, v213
	v_add_f32_e32 v141, v141, v214
	v_add_f32_e32 v141, v141, v215
	v_mov_b32_e32 v154, v141
	v_mov_b32_e32 v216, v141
	s_nop 1
	v_permlane16_swap_b32_e32 v154, v216
	s_waitcnt lgkmcnt(0)
	v_add_f32_e32 v141, v154, v216
	v_mov_b32_e32 v154, v141
	v_mov_b32_e32 v216, v141
	s_nop 1
	v_permlane32_swap_b32_e32 v154, v216
	s_waitcnt lgkmcnt(0)
; __device__ __forceinline__ void rows_rstd(const float* SS, const Unit& u, int wr, int fr, int fq, float (&rs)[2][4]) {
;     ...
;             for (int m = 0; m < 4; ++m) {
;                 const int row = u.pm * BM + ai * HALF + wr * 64 + m * 16 + fr; float s = 0.f;
; #pragma unroll
;                 for (int j = 0; j < 8; ++j) s += SS[(size_t)(fq * 8 + j) * MPAD + row];
;                 s += __shfl_xor(s, 16); s += __shfl_xor(s, 32);
;                 rs[ai][m] = 1.0f / sqrtf(s * (1.0f / 2048.0f) + RMS_EPS);
	v_add_f32_e32 v141, v154, v216
	v_fmamk_f32 v141, v141, 0x3a000000, v220
	v_cmp_gt_f32_e32 vcc, s43, v141
	v_mul_f32_e32 v154, 0x4f800000, v141
	s_nop 0
	v_cndmask_b32_e32 v141, v141, v154, vcc
	v_sqrt_f32_e32 v154, v141
	s_nop 0
	v_add_u32_e32 v156, -1, v154
	v_fma_f32 v158, -v156, v154, v141
	v_cmp_ge_f32_e64 s[6:7], 0, v158
	v_add_u32_e32 v158, 1, v154
	s_nop 0
	v_cndmask_b32_e64 v156, v154, v156, s[6:7]
	v_fma_f32 v154, -v158, v154, v141
	v_cmp_lt_f32_e64 s[6:7], 0, v154
	s_nop 1
	v_cndmask_b32_e64 v154, v156, v158, s[6:7]
	v_mul_f32_e32 v156, 0x37800000, v154
	v_cndmask_b32_e32 v154, v154, v156, vcc
	v_cmp_class_f32_e32 vcc, v141, v221
	v_mad_i64_i32 v[176:177], s[6:7], v157, s46, v[174:175]
	s_nop 0
	v_cndmask_b32_e32 v141, v154, v141, vcc
	v_div_scale_f32 v154, s[6:7], v141, v141, 1.0
	v_rcp_f32_e32 v156, v154
	s_nop 0
	v_fma_f32 v158, -v154, v156, 1.0
	v_fmac_f32_e32 v156, v158, v156
	v_div_scale_f32 v158, vcc, 1.0, v141, 1.0
	v_mul_f32_e32 v162, v158, v156
	v_fma_f32 v164, -v154, v162, v158
	v_fmac_f32_e32 v162, v164, v156
	v_fma_f32 v154, -v154, v162, v158
	v_div_fmas_f32 v154, v154, v156, v162
	v_div_fixup_f32 v168, v154, v141, 1.0
	global_load_dword v208, v[176:177], off
	v_mad_i64_i32 v[176:177], s[6:7], v161, s46, v[174:175]
	global_load_dword v209, v[176:177], off
	v_mad_i64_i32 v[176:177], s[6:7], v163, s46, v[174:175]
	global_load_dword v210, v[176:177], off
	v_mad_i64_i32 v[176:177], s[6:7], v165, s46, v[174:175]
	global_load_dword v211, v[176:177], off
	v_mad_i64_i32 v[176:177], s[6:7], v166, s46, v[174:175]
	global_load_dword v212, v[176:177], off
	v_mad_i64_i32 v[176:177], s[6:7], v167, s46, v[174:175]
	global_load_dword v213, v[176:177], off
	v_mad_i64_i32 v[176:177], s[6:7], v169, s46, v[174:175]
	v_mad_i64_i32 v[174:175], s[6:7], v173, s46, v[174:175]
	global_load_dword v214, v[176:177], off
	global_load_dword v215, v[174:175], off
	v_lshl_add_u64 v[174:175], v[148:149], 2, s[18:19]
	s_waitcnt vmcnt(0)
	v_add_f32_e32 v141, 0, v208
	v_add_f32_e32 v141, v141, v209
	v_add_f32_e32 v141, v141, v210
	v_add_f32_e32 v141, v141, v211
	v_add_f32_e32 v141, v141, v212
	v_add_f32_e32 v141, v141, v213
	v_add_f32_e32 v141, v141, v214
	v_add_f32_e32 v141, v141, v215
	v_mov_b32_e32 v154, v141
	v_mov_b32_e32 v216, v141
	s_nop 1
	v_permlane16_swap_b32_e32 v154, v216
	s_waitcnt lgkmcnt(0)
	v_add_f32_e32 v141, v154, v216
	v_mov_b32_e32 v154, v141
	v_mov_b32_e32 v216, v141
	s_nop 1
	v_permlane32_swap_b32_e32 v154, v216
	s_waitcnt lgkmcnt(0)
	v_add_f32_e32 v141, v154, v216
	v_fmamk_f32 v141, v141, 0x3a000000, v220
	v_cmp_gt_f32_e32 vcc, s43, v141
	v_mul_f32_e32 v154, 0x4f800000, v141
	s_nop 0
	v_cndmask_b32_e32 v141, v141, v154, vcc
	v_sqrt_f32_e32 v154, v141
	s_nop 0
	v_add_u32_e32 v156, -1, v154
	v_fma_f32 v158, -v156, v154, v141
	v_cmp_ge_f32_e64 s[6:7], 0, v158
	v_add_u32_e32 v158, 1, v154
	s_nop 0
	v_cndmask_b32_e64 v156, v154, v156, s[6:7]
	v_fma_f32 v154, -v158, v154, v141
	v_cmp_lt_f32_e64 s[6:7], 0, v154
	s_nop 1
	v_cndmask_b32_e64 v154, v156, v158, s[6:7]
	v_mul_f32_e32 v156, 0x37800000, v154
	v_cndmask_b32_e32 v154, v154, v156, vcc
	v_cmp_class_f32_e32 vcc, v141, v221
	v_mad_i64_i32 v[176:177], s[6:7], v157, s46, v[174:175]
	s_nop 0
	v_cndmask_b32_e32 v141, v154, v141, vcc
	v_div_scale_f32 v154, s[6:7], v141, v141, 1.0
	v_rcp_f32_e32 v156, v154
	s_nop 0
	v_fma_f32 v158, -v154, v156, 1.0
	v_fmac_f32_e32 v156, v158, v156
	v_div_scale_f32 v158, vcc, 1.0, v141, 1.0
	v_mul_f32_e32 v162, v158, v156
	v_fma_f32 v164, -v154, v162, v158
	v_fmac_f32_e32 v162, v164, v156
	v_fma_f32 v154, -v154, v162, v158
	v_div_fmas_f32 v154, v154, v156, v162
	v_div_fixup_f32 v164, v154, v141, 1.0
	global_load_dword v208, v[176:177], off
	v_mad_i64_i32 v[176:177], s[6:7], v161, s46, v[174:175]
	global_load_dword v209, v[176:177], off
	v_mad_i64_i32 v[176:177], s[6:7], v163, s46, v[174:175]
	global_load_dword v210, v[176:177], off
	v_mad_i64_i32 v[176:177], s[6:7], v165, s46, v[174:175]
	global_load_dword v211, v[176:177], off
	v_mad_i64_i32 v[176:177], s[6:7], v166, s46, v[174:175]
	global_load_dword v212, v[176:177], off
	v_mad_i64_i32 v[176:177], s[6:7], v167, s46, v[174:175]
	global_load_dword v213, v[176:177], off
	v_mad_i64_i32 v[176:177], s[6:7], v169, s46, v[174:175]
	v_mad_i64_i32 v[174:175], s[6:7], v173, s46, v[174:175]
	global_load_dword v214, v[176:177], off
	global_load_dword v215, v[174:175], off
	s_waitcnt vmcnt(0)
	v_add_f32_e32 v141, 0, v208
	v_add_f32_e32 v141, v141, v209
	v_add_f32_e32 v141, v141, v210
	v_add_f32_e32 v141, v141, v211
	v_add_f32_e32 v141, v141, v212
	v_add_f32_e32 v141, v141, v213
	v_add_f32_e32 v141, v141, v214
	v_add_f32_e32 v141, v141, v215
	v_mov_b32_e32 v154, v141
	v_mov_b32_e32 v216, v141
	s_nop 1
	v_permlane16_swap_b32_e32 v154, v216
	s_waitcnt lgkmcnt(0)
	v_add_f32_e32 v141, v154, v216
	v_mov_b32_e32 v154, v141
	v_mov_b32_e32 v216, v141
	s_nop 1
	v_permlane32_swap_b32_e32 v154, v216
	s_waitcnt lgkmcnt(0)
; __device__ __forceinline__ void rows_rstd(const float* SS, const Unit& u, int wr, int fr, int fq, float (&rs)[2][4]) {
;     ...
;             for (int m = 0; m < 4; ++m) {
;                 const int row = u.pm * BM + ai * HALF + wr * 64 + m * 16 + fr; float s = 0.f;
; #pragma unroll
;                 for (int j = 0; j < 8; ++j) s += SS[(size_t)(fq * 8 + j) * MPAD + row];
;                 s += __shfl_xor(s, 16); s += __shfl_xor(s, 32);
;                 rs[ai][m] = 1.0f / sqrtf(s * (1.0f / 2048.0f) + RMS_EPS);
	v_add_f32_e32 v141, v154, v216
	v_fmamk_f32 v141, v141, 0x3a000000, v220
	v_cmp_gt_f32_e32 vcc, s43, v141
	v_mul_f32_e32 v154, 0x4f800000, v141
	s_nop 0
	v_cndmask_b32_e32 v141, v141, v154, vcc
	v_sqrt_f32_e32 v154, v141
	s_nop 0
	v_add_u32_e32 v156, -1, v154
	v_fma_f32 v158, -v156, v154, v141
	v_cmp_ge_f32_e64 s[6:7], 0, v158
	v_add_u32_e32 v158, 1, v154
	s_nop 0
	v_cndmask_b32_e64 v156, v154, v156, s[6:7]
	v_fma_f32 v154, -v158, v154, v141
	v_cmp_lt_f32_e64 s[6:7], 0, v154
	s_nop 1
	v_cndmask_b32_e64 v154, v156, v158, s[6:7]
	v_mul_f32_e32 v156, 0x37800000, v154
	v_cndmask_b32_e32 v154, v154, v156, vcc
	v_cmp_class_f32_e32 vcc, v141, v221
	s_nop 1
	v_cndmask_b32_e32 v141, v154, v141, vcc
	v_div_scale_f32 v154, s[6:7], v141, v141, 1.0
	v_rcp_f32_e32 v156, v154
	s_nop 0
	v_fma_f32 v158, -v154, v156, 1.0
	v_fmac_f32_e32 v156, v158, v156
	v_div_scale_f32 v158, vcc, 1.0, v141, 1.0
	v_mul_f32_e32 v162, v158, v156
	v_fma_f32 v174, -v154, v162, v158
	v_fmac_f32_e32 v162, v174, v156
	v_fma_f32 v154, -v154, v162, v158
	v_lshl_add_u64 v[174:175], v[146:147], 2, s[18:19]
	v_div_fmas_f32 v154, v154, v156, v162
	v_mad_i64_i32 v[176:177], s[6:7], v157, s46, v[174:175]
	v_div_fixup_f32 v162, v154, v141, 1.0
	global_load_dword v208, v[176:177], off
	v_mad_i64_i32 v[176:177], s[6:7], v161, s46, v[174:175]
	global_load_dword v209, v[176:177], off
	v_mad_i64_i32 v[176:177], s[6:7], v163, s46, v[174:175]
	global_load_dword v210, v[176:177], off
	v_mad_i64_i32 v[176:177], s[6:7], v165, s46, v[174:175]
	global_load_dword v211, v[176:177], off
	v_mad_i64_i32 v[176:177], s[6:7], v166, s46, v[174:175]
	global_load_dword v212, v[176:177], off
	v_mad_i64_i32 v[176:177], s[6:7], v167, s46, v[174:175]
	global_load_dword v213, v[176:177], off
	v_mad_i64_i32 v[176:177], s[6:7], v169, s46, v[174:175]
	v_mad_i64_i32 v[174:175], s[6:7], v173, s46, v[174:175]
	global_load_dword v214, v[176:177], off
	global_load_dword v215, v[174:175], off
	s_waitcnt vmcnt(0)
	v_add_f32_e32 v141, 0, v208
	v_add_f32_e32 v141, v141, v209
	v_add_f32_e32 v141, v141, v210
	v_add_f32_e32 v141, v141, v211
	v_add_f32_e32 v141, v141, v212
	v_add_f32_e32 v141, v141, v213
	v_add_f32_e32 v141, v141, v214
	v_add_f32_e32 v141, v141, v215
	v_mov_b32_e32 v154, v141
	v_mov_b32_e32 v216, v141
	s_nop 1
	v_permlane16_swap_b32_e32 v154, v216
	s_waitcnt lgkmcnt(0)
	v_add_f32_e32 v141, v154, v216
	v_mov_b32_e32 v154, v141
	v_mov_b32_e32 v216, v141
	s_nop 1
	v_permlane32_swap_b32_e32 v154, v216
	s_waitcnt lgkmcnt(0)
	v_add_f32_e32 v141, v154, v216
	v_fmamk_f32 v141, v141, 0x3a000000, v220
	v_cmp_gt_f32_e32 vcc, s43, v141
	v_mul_f32_e32 v154, 0x4f800000, v141
	s_nop 0
	v_cndmask_b32_e32 v141, v141, v154, vcc
	v_sqrt_f32_e32 v154, v141
	s_nop 0
	v_add_u32_e32 v156, -1, v154
	v_fma_f32 v158, -v156, v154, v141
	v_cmp_ge_f32_e64 s[6:7], 0, v158
	v_add_u32_e32 v158, 1, v154
	s_nop 0
	v_cndmask_b32_e64 v156, v154, v156, s[6:7]
	v_fma_f32 v154, -v158, v154, v141
	v_cmp_lt_f32_e64 s[6:7], 0, v154
	s_nop 1
	v_cndmask_b32_e64 v154, v156, v158, s[6:7]
	v_mul_f32_e32 v156, 0x37800000, v154
	v_cndmask_b32_e32 v154, v154, v156, vcc
	v_cmp_class_f32_e32 vcc, v141, v221
	s_nop 1
	v_cndmask_b32_e32 v141, v154, v141, vcc
	v_div_scale_f32 v154, s[6:7], v141, v141, 1.0
	v_rcp_f32_e32 v156, v154
	s_nop 0
	v_fma_f32 v158, -v154, v156, 1.0
	v_fmac_f32_e32 v156, v158, v156
	v_div_scale_f32 v158, vcc, 1.0, v141, 1.0
	v_mul_f32_e32 v174, v158, v156
	v_fma_f32 v175, -v154, v174, v158
	v_fmac_f32_e32 v174, v175, v156
	v_fma_f32 v154, -v154, v174, v158
	v_div_fmas_f32 v154, v154, v156, v174
	v_lshl_add_u64 v[174:175], v[144:145], 2, s[18:19]
	v_mad_i64_i32 v[176:177], s[6:7], v157, s46, v[174:175]
	v_div_fixup_f32 v158, v154, v141, 1.0
	global_load_dword v208, v[176:177], off
	v_mad_i64_i32 v[176:177], s[6:7], v161, s46, v[174:175]
	global_load_dword v209, v[176:177], off
	v_mad_i64_i32 v[176:177], s[6:7], v163, s46, v[174:175]
	global_load_dword v210, v[176:177], off
	v_mad_i64_i32 v[176:177], s[6:7], v165, s46, v[174:175]
	global_load_dword v211, v[176:177], off
	v_mad_i64_i32 v[176:177], s[6:7], v166, s46, v[174:175]
	global_load_dword v212, v[176:177], off
	v_mad_i64_i32 v[176:177], s[6:7], v167, s46, v[174:175]
	global_load_dword v213, v[176:177], off
	v_mad_i64_i32 v[176:177], s[6:7], v169, s46, v[174:175]
	v_mad_i64_i32 v[174:175], s[6:7], v173, s46, v[174:175]
	global_load_dword v214, v[176:177], off
	global_load_dword v215, v[174:175], off
	s_waitcnt vmcnt(0)
	v_add_f32_e32 v141, 0, v208
	v_add_f32_e32 v141, v141, v209
	v_add_f32_e32 v141, v141, v210
	v_add_f32_e32 v141, v141, v211
	v_add_f32_e32 v141, v141, v212
	v_add_f32_e32 v141, v141, v213
	v_add_f32_e32 v141, v141, v214
	v_add_f32_e32 v141, v141, v215
	v_mov_b32_e32 v154, v141
	v_mov_b32_e32 v216, v141
	s_nop 1
	v_permlane16_swap_b32_e32 v154, v216
	s_waitcnt lgkmcnt(0)
	v_add_f32_e32 v141, v154, v216
	v_mov_b32_e32 v154, v141
	v_mov_b32_e32 v216, v141
	s_nop 1
	v_permlane32_swap_b32_e32 v154, v216
	s_waitcnt lgkmcnt(0)
; __device__ __forceinline__ void rows_rstd(const float* SS, const Unit& u, int wr, int fr, int fq, float (&rs)[2][4]) {
;     ...
;             for (int m = 0; m < 4; ++m) {
;                 const int row = u.pm * BM + ai * HALF + wr * 64 + m * 16 + fr; float s = 0.f;
; #pragma unroll
;                 for (int j = 0; j < 8; ++j) s += SS[(size_t)(fq * 8 + j) * MPAD + row];
;                 s += __shfl_xor(s, 16); s += __shfl_xor(s, 32);
;                 rs[ai][m] = 1.0f / sqrtf(s * (1.0f / 2048.0f) + RMS_EPS);
	v_add_f32_e32 v141, v154, v216
	v_fmamk_f32 v141, v141, 0x3a000000, v220
	v_cmp_gt_f32_e32 vcc, s43, v141
	v_mul_f32_e32 v154, 0x4f800000, v141
	s_nop 0
	v_cndmask_b32_e32 v141, v141, v154, vcc
	v_sqrt_f32_e32 v154, v141
	s_nop 0
	v_add_u32_e32 v156, -1, v154
	v_fma_f32 v174, -v156, v154, v141
	v_cmp_ge_f32_e64 s[6:7], 0, v174
	v_add_u32_e32 v174, 1, v154
	s_nop 0
	v_cndmask_b32_e64 v156, v154, v156, s[6:7]
	v_fma_f32 v154, -v174, v154, v141
	v_cmp_lt_f32_e64 s[6:7], 0, v154
	s_nop 1
	v_cndmask_b32_e64 v154, v156, v174, s[6:7]
	v_mul_f32_e32 v156, 0x37800000, v154
	v_cndmask_b32_e32 v154, v154, v156, vcc
	v_cmp_class_f32_e32 vcc, v141, v221
	s_nop 1
	v_cndmask_b32_e32 v141, v154, v141, vcc
	v_div_scale_f32 v154, s[6:7], v141, v141, 1.0
	v_rcp_f32_e32 v156, v154
	s_nop 0
	v_fma_f32 v174, -v154, v156, 1.0
	v_fmac_f32_e32 v156, v174, v156
	v_div_scale_f32 v174, vcc, 1.0, v141, 1.0
	v_mul_f32_e32 v175, v174, v156
	v_fma_f32 v176, -v154, v175, v174
	v_fmac_f32_e32 v175, v176, v156
	v_fma_f32 v154, -v154, v175, v174
	v_div_fmas_f32 v154, v154, v156, v175
	v_lshl_add_u64 v[174:175], v[142:143], 2, s[18:19]
	v_mad_i64_i32 v[176:177], s[6:7], v157, s46, v[174:175]
	v_div_fixup_f32 v156, v154, v141, 1.0
	global_load_dword v208, v[176:177], off
	v_mad_i64_i32 v[176:177], s[6:7], v161, s46, v[174:175]
	global_load_dword v209, v[176:177], off
	v_mad_i64_i32 v[176:177], s[6:7], v163, s46, v[174:175]
	global_load_dword v210, v[176:177], off
	v_mad_i64_i32 v[176:177], s[6:7], v165, s46, v[174:175]
	global_load_dword v211, v[176:177], off
	v_mad_i64_i32 v[176:177], s[6:7], v166, s46, v[174:175]
	global_load_dword v212, v[176:177], off
	v_mad_i64_i32 v[176:177], s[6:7], v167, s46, v[174:175]
	global_load_dword v213, v[176:177], off
	v_mad_i64_i32 v[176:177], s[6:7], v169, s46, v[174:175]
	v_mad_i64_i32 v[174:175], s[6:7], v173, s46, v[174:175]
	global_load_dword v214, v[176:177], off
	global_load_dword v215, v[174:175], off
	s_waitcnt vmcnt(0)
	v_add_f32_e32 v141, 0, v208
	v_add_f32_e32 v141, v141, v209
	v_add_f32_e32 v141, v141, v210
	v_add_f32_e32 v141, v141, v211
	v_add_f32_e32 v141, v141, v212
	v_add_f32_e32 v141, v141, v213
	v_add_f32_e32 v141, v141, v214
	v_add_f32_e32 v141, v141, v215
	v_mov_b32_e32 v154, v141
	v_mov_b32_e32 v216, v141
	s_nop 1
	v_permlane16_swap_b32_e32 v154, v216
	s_waitcnt lgkmcnt(0)
	v_add_f32_e32 v141, v154, v216
	v_mov_b32_e32 v154, v141
	v_mov_b32_e32 v216, v141
	s_nop 1
	v_permlane32_swap_b32_e32 v154, v216
	s_waitcnt lgkmcnt(0)
	v_add_f32_e32 v141, v154, v216
	v_fmamk_f32 v141, v141, 0x3a000000, v220
	v_cmp_gt_f32_e32 vcc, s43, v141
	v_mul_f32_e32 v154, 0x4f800000, v141
	s_nop 0
	v_cndmask_b32_e32 v141, v141, v154, vcc
	v_sqrt_f32_e32 v154, v141
	s_nop 0
	v_add_u32_e32 v174, -1, v154
	v_fma_f32 v175, -v174, v154, v141
	v_cmp_ge_f32_e64 s[6:7], 0, v175
	v_add_u32_e32 v175, 1, v154
	s_nop 0
	v_cndmask_b32_e64 v174, v154, v174, s[6:7]
	v_fma_f32 v154, -v175, v154, v141
	v_cmp_lt_f32_e64 s[6:7], 0, v154
	s_nop 1
	v_cndmask_b32_e64 v154, v174, v175, s[6:7]
	v_mul_f32_e32 v174, 0x37800000, v154
	v_cndmask_b32_e32 v154, v154, v174, vcc
	v_cmp_class_f32_e32 vcc, v141, v221
	s_nop 1
	v_cndmask_b32_e32 v141, v154, v141, vcc
	v_div_scale_f32 v154, s[6:7], v141, v141, 1.0
	v_rcp_f32_e32 v174, v154
	s_nop 0
	v_fma_f32 v175, -v154, v174, 1.0
	v_fmac_f32_e32 v174, v175, v174
	v_div_scale_f32 v175, vcc, 1.0, v141, 1.0
	v_mul_f32_e32 v176, v175, v174
	v_fma_f32 v177, -v154, v176, v175
	v_fmac_f32_e32 v176, v177, v174
	v_fma_f32 v154, -v154, v176, v175
	v_div_fmas_f32 v154, v154, v174, v176
	v_div_fixup_f32 v154, v154, v141, 1.0
	v_ashrrev_i32_e32 v141, 31, v140
	v_lshl_add_u64 v[174:175], v[140:141], 2, s[18:19]
	v_mad_i64_i32 v[176:177], s[6:7], v157, s46, v[174:175]
	global_load_dword v208, v[176:177], off
	v_mad_i64_i32 v[176:177], s[6:7], v161, s46, v[174:175]
	global_load_dword v209, v[176:177], off
	v_mad_i64_i32 v[176:177], s[6:7], v163, s46, v[174:175]
	global_load_dword v210, v[176:177], off
	v_mad_i64_i32 v[176:177], s[6:7], v165, s46, v[174:175]
	global_load_dword v211, v[176:177], off
	v_mad_i64_i32 v[176:177], s[6:7], v166, s46, v[174:175]
	v_mad_i64_i32 v[166:167], s[6:7], v167, s46, v[174:175]
	global_load_dword v212, v[176:177], off
	global_load_dword v213, v[166:167], off
	v_mad_i64_i32 v[166:167], s[6:7], v169, s46, v[174:175]
	global_load_dword v214, v[166:167], off
	v_mad_i64_i32 v[166:167], s[6:7], v173, s46, v[174:175]
	global_load_dword v215, v[166:167], off
	s_waitcnt vmcnt(0)
	v_add_f32_e32 v141, 0, v208
	v_add_f32_e32 v141, v141, v209
	v_add_f32_e32 v141, v141, v210
	v_add_f32_e32 v141, v141, v211
	v_add_f32_e32 v141, v141, v212
	v_add_f32_e32 v141, v141, v213
	v_add_f32_e32 v141, v141, v214
	v_add_f32_e32 v141, v141, v215
	v_mov_b32_e32 v160, v141
	v_mov_b32_e32 v216, v141
	s_nop 1
	v_permlane16_swap_b32_e32 v160, v216
	s_waitcnt lgkmcnt(0)
	v_add_f32_e32 v141, v160, v216
	v_mov_b32_e32 v159, v141
	v_mov_b32_e32 v216, v141
	s_nop 1
	v_permlane32_swap_b32_e32 v159, v216
	s_waitcnt lgkmcnt(0)
	v_add_f32_e32 v141, v159, v216
	v_fmamk_f32 v141, v141, 0x3a000000, v220
	v_cmp_gt_f32_e32 vcc, s43, v141
	v_mul_f32_e32 v159, 0x4f800000, v141
	s_nop 0
	v_cndmask_b32_e32 v141, v141, v159, vcc
	v_sqrt_f32_e32 v159, v141
	s_nop 0
	v_add_u32_e32 v160, -1, v159
	v_fma_f32 v161, -v160, v159, v141
	v_cmp_ge_f32_e64 s[6:7], 0, v161
	v_add_u32_e32 v161, 1, v159
	s_nop 0
	v_cndmask_b32_e64 v160, v159, v160, s[6:7]
	v_fma_f32 v159, -v161, v159, v141
	v_cmp_lt_f32_e64 s[6:7], 0, v159
	s_nop 1
	v_cndmask_b32_e64 v159, v160, v161, s[6:7]
	v_mul_f32_e32 v160, 0x37800000, v159
	v_cndmask_b32_e32 v159, v159, v160, vcc
	v_cmp_class_f32_e32 vcc, v141, v221
	s_nop 1
	v_cndmask_b32_e32 v141, v159, v141, vcc
	v_div_scale_f32 v159, s[6:7], v141, v141, 1.0
	v_rcp_f32_e32 v160, v159
	s_mov_b64 s[6:7], 0
	v_fma_f32 v161, -v159, v160, 1.0
	v_fmac_f32_e32 v160, v161, v160
	v_div_scale_f32 v161, vcc, 1.0, v141, 1.0
	v_mul_f32_e32 v163, v161, v160
	v_fma_f32 v165, -v159, v163, v161
	v_fmac_f32_e32 v163, v165, v160
	v_fma_f32 v159, -v159, v163, v161
	v_div_fmas_f32 v159, v159, v160, v163
	v_div_fixup_f32 v166, v159, v141, 1.0

; __device__ __forceinline__ unsigned cvtpk(float lo, float hi) { unsigned r; asm volatile("v_cvt_pk_bf16_f32 %0, %1, %2" : "=v"(r) : "v"(lo), "v"(hi)); return r; }
; __device__ __forceinline__ float wave_sum(float v) {
; #pragma unroll
;     for (int o = 1; o < 64; o <<= 1) v += __shfl_xor(v, o);
;     return v;
; __device__ __forceinline__ void phase_gla_norm(KArgs a, int gw, int NGW, int lane) {
;     ...
;         for (int i = 0; i < 4; ++i) { const int it = it0 + i * NGW; if (it < MPROMPT * 4) { const size_t off = (size_t)(it >> 2) * DM + (it & 3) * 512 + lane * 4;
;             const f32x4 o0 = oa[i], o1 = ob[i];
;             const float ss = wave_sum((o0[0] * o0[0] + o0[1] * o0[1]) + (o0[2] * o0[2] + o0[3] * o0[3]) + (o1[0] * o1[0] + o1[1] * o1[1]) + (o1[2] * o1[2] + o1[3] * o1[3]));
;             const float rs = 1.0f / sqrtf(ss * (1.0f / 512.0f) + RMS_EPS);
;             u32x2 w0, w1;
;             w0.x = cvtpk(o0[0] * rs * g0[0] * bflo(ra[i].x), o0[1] * rs * g0[1] * bfhi(ra[i].x)); w0.y = cvtpk(o0[2] * rs * g0[2] * bflo(ra[i].y), o0[3] * rs * g0[3] * bfhi(ra[i].y));
;             w1.x = cvtpk(o1[0] * rs * g1[0] * bflo(rb[i].x), o1[1] * rs * g1[1] * bfhi(rb[i].x)); w1.y = cvtpk(o1[2] * rs * g1[2] * bflo(rb[i].y), o1[3] * rs * g1[3] * bfhi(rb[i].y));
;             *(u32x2*)(OG + off) = w0; *(u32x2*)(OG + off + 256) = w1; } }
.LBB0_962:
	s_waitcnt vmcnt(3)
	v_mul_f32_e32 v66, v39, v39
	v_mul_f32_e32 v67, v41, v41
	v_fmac_f32_e32 v66, v38, v38
	v_fmac_f32_e32 v67, v40, v40
	v_add_f32_e32 v66, v66, v67
	s_waitcnt vmcnt(2)
	v_mul_f32_e32 v67, v35, v35
	v_fmac_f32_e32 v67, v34, v34
	v_add_f32_e32 v66, v67, v66
	v_mul_f32_e32 v67, v37, v37
	v_fmac_f32_e32 v67, v36, v36
	v_add_f32_e32 v66, v67, v66
	s_nop 1
	v_add_f32_dpp v67, v66, v66 quad_perm:[1,0,3,2] row_mask:0xf bank_mask:0xf
	s_waitcnt vmcnt(1)
	v_lshlrev_b32_e32 v68, 16, v58
	v_and_b32_e32 v58, 0xffff0000, v58
	v_lshlrev_b32_e32 v69, 16, v59
	v_and_b32_e32 v59, 0xffff0000, v59
	s_waitcnt lgkmcnt(0)
	v_mov_b32_e32 v66, v67
	s_nop 1
	v_add_f32_dpp v67, v66, v66 quad_perm:[2,3,0,1] row_mask:0xf bank_mask:0xf
	s_waitcnt lgkmcnt(0)
	v_mov_b32_e32 v66, v67
	s_nop 1
	v_add_f32_dpp v67, v66, v66 row_half_mirror row_mask:0xf bank_mask:0xf
	s_waitcnt lgkmcnt(0)
	v_mov_b32_e32 v66, v67
	s_nop 1
	v_add_f32_dpp v67, v66, v66 row_mirror row_mask:0xf bank_mask:0xf
	s_waitcnt lgkmcnt(0)
	v_mov_b32_e32 v66, v67
	v_mov_b32_e32 v67, v66
	v_mov_b32_e32 v90, v66
	s_nop 1
	v_permlane16_swap_b32_e32 v67, v90
	s_waitcnt lgkmcnt(0)
	v_add_f32_e32 v66, v67, v90
	v_mov_b32_e32 v67, v66
	v_mov_b32_e32 v90, v66
	s_nop 1
	v_permlane32_swap_b32_e32 v67, v90
	s_waitcnt lgkmcnt(0)
	v_add_f32_e32 v66, v67, v90
	v_fmamk_f32 v66, v66, 0x3b000000, v220
	v_mul_f32_e32 v67, 0x4f800000, v66
	v_cmp_gt_f32_e32 vcc, s43, v66
	s_nop 1
	v_cndmask_b32_e32 v66, v66, v67, vcc
	v_sqrt_f32_e32 v67, v66
	s_nop 0
	v_add_u32_e32 v70, -1, v67
	v_add_u32_e32 v71, 1, v67
	v_fma_f32 v72, -v70, v67, v66
	v_fma_f32 v73, -v71, v67, v66
	v_cmp_ge_f32_e64 s[4:5], 0, v72
	s_nop 1
	v_cndmask_b32_e64 v67, v67, v70, s[4:5]
	v_cmp_lt_f32_e64 s[4:5], 0, v73
	s_nop 1
	v_cndmask_b32_e64 v67, v67, v71, s[4:5]
	v_mul_f32_e32 v70, 0x37800000, v67
	v_cndmask_b32_e32 v67, v67, v70, vcc
	v_cmp_class_f32_e32 vcc, v66, v221
	s_nop 1
	v_cndmask_b32_e32 v66, v67, v66, vcc
	v_div_scale_f32 v67, s[4:5], v66, v66, 1.0
	v_rcp_f32_e32 v70, v67
	v_div_scale_f32 v71, vcc, 1.0, v66, 1.0
	s_lshl_b64 s[4:5], s[18:19], 12
	v_fma_f32 v72, -v67, v70, 1.0
	v_fmac_f32_e32 v70, v72, v70
	v_mul_f32_e32 v72, v71, v70
	v_fma_f32 v73, -v67, v72, v71
	v_fmac_f32_e32 v72, v73, v70
	v_fma_f32 v67, -v67, v72, v71
	v_div_fmas_f32 v67, v67, v70, v72
	v_div_fixup_f32 v66, v67, v66, 1.0
	v_mul_f32_e32 v38, v38, v66
	v_mul_f32_e32 v39, v39, v66
	v_mul_f32_e32 v40, v40, v66
	v_mul_f32_e32 v41, v41, v66
	v_mul_f32_e32 v38, v2, v38
	v_mul_f32_e32 v39, v3, v39
	v_mul_f32_e32 v40, v4, v40
	v_mul_f32_e32 v41, v5, v41
	v_mul_f32_e32 v38, v38, v68
	v_mul_f32_e32 v39, v39, v58
	v_mul_f32_e32 v40, v40, v69
	v_mul_f32_e32 v34, v34, v66
	v_mul_f32_e32 v41, v41, v59
	v_cvt_pk_bf16_f32 v38, v38, v39
	v_cvt_pk_bf16_f32 v39, v40, v41
	v_mul_f32_e32 v34, v6, v34
	s_waitcnt vmcnt(0)
	v_lshlrev_b32_e32 v40, 16, v56
	v_mul_f32_e32 v35, v35, v66
	v_mul_f32_e32 v34, v34, v40
	v_mul_f32_e32 v35, v7, v35
	v_and_b32_e32 v40, 0xffff0000, v56
	v_mul_f32_e32 v35, v35, v40
	v_cvt_pk_bf16_f32 v34, v34, v35
	v_mul_f32_e32 v35, v36, v66
	s_add_u32 s4, s10, s4
	v_mul_f32_e32 v35, v8, v35
	v_lshlrev_b32_e32 v36, 16, v57
	s_addc_u32 s5, s11, s5
	s_lshl_b32 s27, s27, 1
	v_mul_f32_e32 v35, v35, v36
	v_mul_f32_e32 v36, v37, v66
	s_add_u32 s4, s4, s27
	v_mul_f32_e32 v36, v9, v36
	v_and_b32_e32 v37, 0xffff0000, v57
	s_addc_u32 s5, s5, 0
	s_andn2_b64 vcc, exec, s[20:21]
	v_mul_f32_e32 v36, v36, v37
	v_cvt_pk_bf16_f32 v35, v35, v36
	global_store_dwordx2 v42, v[38:39], s[4:5]
	global_store_dwordx2 v42, v[34:35], s[4:5] offset:512
	s_cbranch_vccz .LBB0_965
	s_andn2_b64 vcc, exec, s[16:17]
	s_cbranch_vccz .LBB0_966

; __device__ __forceinline__ unsigned cvtpk(float lo, float hi) { unsigned r; asm volatile("v_cvt_pk_bf16_f32 %0, %1, %2" : "=v"(r) : "v"(lo), "v"(hi)); return r; }
; __device__ __forceinline__ float wave_sum(float v) {
; #pragma unroll
;     for (int o = 1; o < 64; o <<= 1) v += __shfl_xor(v, o);
;     return v;
; __device__ __forceinline__ void phase_gla_norm(KArgs a, int gw, int NGW, int lane) {
;     ...
;         for (int i = 0; i < 4; ++i) { const int it = it0 + i * NGW; if (it < MPROMPT * 4) { const size_t off = (size_t)(it >> 2) * DM + (it & 3) * 512 + lane * 4;
;             const f32x4 o0 = oa[i], o1 = ob[i];
;             const float ss = wave_sum((o0[0] * o0[0] + o0[1] * o0[1]) + (o0[2] * o0[2] + o0[3] * o0[3]) + (o1[0] * o1[0] + o1[1] * o1[1]) + (o1[2] * o1[2] + o1[3] * o1[3]));
;             const float rs = 1.0f / sqrtf(ss * (1.0f / 512.0f) + RMS_EPS);
;             u32x2 w0, w1;
;             w0.x = cvtpk(o0[0] * rs * g0[0] * bflo(ra[i].x), o0[1] * rs * g0[1] * bfhi(ra[i].x)); w0.y = cvtpk(o0[2] * rs * g0[2] * bflo(ra[i].y), o0[3] * rs * g0[3] * bfhi(ra[i].y));
;             w1.x = cvtpk(o1[0] * rs * g1[0] * bflo(rb[i].x), o1[1] * rs * g1[1] * bfhi(rb[i].x)); w1.y = cvtpk(o1[2] * rs * g1[2] * bflo(rb[i].y), o1[3] * rs * g1[3] * bfhi(rb[i].y));
;             *(u32x2*)(OG + off) = w0; *(u32x2*)(OG + off + 256) = w1; } }
.LBB0_965:
	v_mul_f32_e32 v34, v23, v23
	v_mul_f32_e32 v35, v25, v25
	v_fmac_f32_e32 v34, v22, v22
	v_fmac_f32_e32 v35, v24, v24
	v_add_f32_e32 v34, v34, v35
	v_mul_f32_e32 v35, v19, v19
	v_fmac_f32_e32 v35, v18, v18
	v_add_f32_e32 v34, v35, v34
	v_mul_f32_e32 v35, v21, v21
	v_fmac_f32_e32 v35, v20, v20
	v_add_f32_e32 v34, v35, v34
	s_nop 1
	v_add_f32_dpp v35, v34, v34 quad_perm:[1,0,3,2] row_mask:0xf bank_mask:0xf
	v_lshlrev_b32_e32 v36, 16, v44
	v_and_b32_e32 v37, 0xffff0000, v44
	v_lshlrev_b32_e32 v38, 16, v45
	v_and_b32_e32 v39, 0xffff0000, v45
	s_waitcnt lgkmcnt(0)
	v_mov_b32_e32 v34, v35
	s_nop 1
	v_add_f32_dpp v35, v34, v34 quad_perm:[2,3,0,1] row_mask:0xf bank_mask:0xf
	s_ashr_i32 s18, s24, 2
	s_ashr_i32 s19, s18, 31
	s_waitcnt lgkmcnt(0)
	v_mov_b32_e32 v34, v35
	s_nop 1
	v_add_f32_dpp v35, v34, v34 row_half_mirror row_mask:0xf bank_mask:0xf
	s_waitcnt lgkmcnt(0)
	v_mov_b32_e32 v34, v35
	s_nop 1
	v_add_f32_dpp v35, v34, v34 row_mirror row_mask:0xf bank_mask:0xf
	s_waitcnt lgkmcnt(0)
	v_mov_b32_e32 v34, v35
	v_mov_b32_e32 v35, v34
	v_mov_b32_e32 v90, v34
	s_nop 1
	v_permlane16_swap_b32_e32 v35, v90
	s_waitcnt lgkmcnt(0)
	v_add_f32_e32 v34, v35, v90
	v_mov_b32_e32 v35, v34
	v_mov_b32_e32 v90, v34
	s_nop 1
	v_permlane32_swap_b32_e32 v35, v90
	s_waitcnt lgkmcnt(0)
	v_add_f32_e32 v34, v35, v90
	v_fmamk_f32 v34, v34, 0x3b000000, v220
	v_mul_f32_e32 v35, 0x4f800000, v34
	v_cmp_gt_f32_e32 vcc, s43, v34
	s_nop 1
	v_cndmask_b32_e32 v34, v34, v35, vcc
	v_sqrt_f32_e32 v35, v34
	s_nop 0
	v_add_u32_e32 v40, -1, v35
	v_add_u32_e32 v41, 1, v35
	v_fma_f32 v56, -v40, v35, v34
	v_fma_f32 v57, -v41, v35, v34
	v_cmp_ge_f32_e64 s[4:5], 0, v56
	s_nop 1
	v_cndmask_b32_e64 v35, v35, v40, s[4:5]
	v_cmp_lt_f32_e64 s[4:5], 0, v57
	s_nop 1
	v_cndmask_b32_e64 v35, v35, v41, s[4:5]
	v_mul_f32_e32 v40, 0x37800000, v35
	v_cndmask_b32_e32 v35, v35, v40, vcc
	v_cmp_class_f32_e32 vcc, v34, v221
	s_nop 1
	v_cndmask_b32_e32 v34, v35, v34, vcc
	v_div_scale_f32 v35, s[4:5], v34, v34, 1.0
	v_rcp_f32_e32 v40, v35
	v_div_scale_f32 v41, vcc, 1.0, v34, 1.0
	s_lshl_b64 s[4:5], s[18:19], 12
	v_fma_f32 v56, -v35, v40, 1.0
	v_fmac_f32_e32 v40, v56, v40
	v_mul_f32_e32 v56, v41, v40
	v_fma_f32 v57, -v35, v56, v41
	v_fmac_f32_e32 v56, v57, v40
	v_fma_f32 v35, -v35, v56, v41
	v_div_fmas_f32 v35, v35, v40, v56
	v_div_fixup_f32 v40, v35, v34, 1.0
	v_mul_f32_e32 v34, v22, v40
	v_mul_f32_e32 v35, v23, v40
	v_mul_f32_e32 v41, v24, v40
	v_mul_f32_e32 v56, v25, v40
	v_mul_f32_e32 v34, v2, v34
	v_mul_f32_e32 v35, v3, v35
	v_mul_f32_e32 v41, v4, v41
	v_mul_f32_e32 v56, v5, v56
	v_mul_f32_e32 v34, v34, v36
	v_mul_f32_e32 v35, v35, v37
	v_mul_f32_e32 v36, v41, v38
	v_cvt_pk_bf16_f32 v34, v34, v35
	v_mul_f32_e32 v35, v56, v39
	v_cvt_pk_bf16_f32 v35, v36, v35
	v_mul_f32_e32 v36, v18, v40
	v_mul_f32_e32 v36, v6, v36
	v_lshlrev_b32_e32 v37, 16, v50
	v_mul_f32_e32 v36, v36, v37
	v_mul_f32_e32 v37, v19, v40
	v_mul_f32_e32 v37, v7, v37
	v_and_b32_e32 v38, 0xffff0000, v50
	v_mul_f32_e32 v37, v37, v38
	v_cvt_pk_bf16_f32 v36, v36, v37
	v_mul_f32_e32 v37, v20, v40
	s_add_u32 s4, s10, s4
	v_mul_f32_e32 v37, v8, v37
	v_lshlrev_b32_e32 v38, 16, v51
	s_addc_u32 s5, s11, s5
	v_mul_f32_e32 v37, v37, v38
	v_mul_f32_e32 v38, v21, v40
	s_add_u32 s4, s4, s27
	v_mul_f32_e32 v38, v9, v38
	v_and_b32_e32 v39, 0xffff0000, v51
	s_addc_u32 s5, s5, 0
	v_mul_f32_e32 v38, v38, v39
	v_cvt_pk_bf16_f32 v37, v37, v38
	global_store_dwordx2 v42, v[34:35], s[4:5]
	global_store_dwordx2 v42, v[36:37], s[4:5] offset:512
	s_andn2_b64 vcc, exec, s[16:17]
	s_cbranch_vccnz .LBB0_964
.LBB0_966:
	v_mul_f32_e32 v34, v27, v27
	v_mul_f32_e32 v35, v29, v29
	v_fmac_f32_e32 v34, v26, v26
	v_fmac_f32_e32 v35, v28, v28
	v_add_f32_e32 v34, v34, v35
	v_mul_f32_e32 v35, v15, v15
	v_fmac_f32_e32 v35, v14, v14
	v_add_f32_e32 v34, v35, v34
	v_mul_f32_e32 v35, v17, v17
	v_fmac_f32_e32 v35, v16, v16
	v_add_f32_e32 v34, v35, v34
	s_nop 1
	v_add_f32_dpp v35, v34, v34 quad_perm:[1,0,3,2] row_mask:0xf bank_mask:0xf
	v_lshlrev_b32_e32 v36, 16, v46
	v_and_b32_e32 v37, 0xffff0000, v46
	v_lshlrev_b32_e32 v38, 16, v47
	v_and_b32_e32 v39, 0xffff0000, v47
	s_waitcnt lgkmcnt(0)
	v_mov_b32_e32 v34, v35
	s_nop 1
	v_add_f32_dpp v35, v34, v34 quad_perm:[2,3,0,1] row_mask:0xf bank_mask:0xf
	s_ashr_i32 s16, s28, 2
	s_ashr_i32 s17, s16, 31
	s_waitcnt lgkmcnt(0)
	v_mov_b32_e32 v34, v35
	s_nop 1
	v_add_f32_dpp v35, v34, v34 row_half_mirror row_mask:0xf bank_mask:0xf
	s_waitcnt lgkmcnt(0)
	v_mov_b32_e32 v34, v35
	s_nop 1
	v_add_f32_dpp v35, v34, v34 row_mirror row_mask:0xf bank_mask:0xf
	s_waitcnt lgkmcnt(0)
	v_mov_b32_e32 v34, v35
	v_mov_b32_e32 v35, v34
	v_mov_b32_e32 v90, v34
	s_nop 1
	v_permlane16_swap_b32_e32 v35, v90
	s_waitcnt lgkmcnt(0)
	v_add_f32_e32 v34, v35, v90
	v_mov_b32_e32 v35, v34
	v_mov_b32_e32 v90, v34
	s_nop 1
	v_permlane32_swap_b32_e32 v35, v90
	s_waitcnt lgkmcnt(0)
; __device__ __forceinline__ unsigned cvtpk(float lo, float hi) { unsigned r; asm volatile("v_cvt_pk_bf16_f32 %0, %1, %2" : "=v"(r) : "v"(lo), "v"(hi)); return r; }
; __device__ __forceinline__ float wave_sum(float v) {
; #pragma unroll
;     for (int o = 1; o < 64; o <<= 1) v += __shfl_xor(v, o);
;     return v;
; __device__ __forceinline__ void phase_gla_norm(KArgs a, int gw, int NGW, int lane) {
;     ...
;         for (int i = 0; i < 4; ++i) { const int it = it0 + i * NGW; if (it < MPROMPT * 4) { const size_t off = (size_t)(it >> 2) * DM + (it & 3) * 512 + lane * 4;
;             const f32x4 o0 = oa[i], o1 = ob[i];
;             const float ss = wave_sum((o0[0] * o0[0] + o0[1] * o0[1]) + (o0[2] * o0[2] + o0[3] * o0[3]) + (o1[0] * o1[0] + o1[1] * o1[1]) + (o1[2] * o1[2] + o1[3] * o1[3]));
;             const float rs = 1.0f / sqrtf(ss * (1.0f / 512.0f) + RMS_EPS);
;             u32x2 w0, w1;
;             w0.x = cvtpk(o0[0] * rs * g0[0] * bflo(ra[i].x), o0[1] * rs * g0[1] * bfhi(ra[i].x)); w0.y = cvtpk(o0[2] * rs * g0[2] * bflo(ra[i].y), o0[3] * rs * g0[3] * bfhi(ra[i].y));
;             w1.x = cvtpk(o1[0] * rs * g1[0] * bflo(rb[i].x), o1[1] * rs * g1[1] * bfhi(rb[i].x)); w1.y = cvtpk(o1[2] * rs * g1[2] * bflo(rb[i].y), o1[3] * rs * g1[3] * bfhi(rb[i].y));
;             *(u32x2*)(OG + off) = w0; *(u32x2*)(OG + off + 256) = w1; } }
	v_add_f32_e32 v34, v35, v90
	v_fmamk_f32 v34, v34, 0x3b000000, v220
	v_mul_f32_e32 v35, 0x4f800000, v34
	v_cmp_gt_f32_e32 vcc, s43, v34
	s_nop 1
	v_cndmask_b32_e32 v34, v34, v35, vcc
	v_sqrt_f32_e32 v35, v34
	s_nop 0
	v_add_u32_e32 v40, -1, v35
	v_add_u32_e32 v41, 1, v35
	v_fma_f32 v56, -v40, v35, v34
	v_fma_f32 v57, -v41, v35, v34
	v_cmp_ge_f32_e64 s[4:5], 0, v56
	s_nop 1
	v_cndmask_b32_e64 v35, v35, v40, s[4:5]
	v_cmp_lt_f32_e64 s[4:5], 0, v57
	s_nop 1
	v_cndmask_b32_e64 v35, v35, v41, s[4:5]
	v_mul_f32_e32 v40, 0x37800000, v35
	v_cndmask_b32_e32 v35, v35, v40, vcc
	v_cmp_class_f32_e32 vcc, v34, v221
	s_nop 1
	v_cndmask_b32_e32 v34, v35, v34, vcc
	v_div_scale_f32 v35, s[4:5], v34, v34, 1.0
	v_rcp_f32_e32 v40, v35
	v_div_scale_f32 v41, vcc, 1.0, v34, 1.0
	s_lshl_b64 s[4:5], s[16:17], 12
	v_fma_f32 v56, -v35, v40, 1.0
	v_fmac_f32_e32 v40, v56, v40
	v_mul_f32_e32 v56, v41, v40
	v_fma_f32 v57, -v35, v56, v41
	v_fmac_f32_e32 v56, v57, v40
	v_fma_f32 v35, -v35, v56, v41
	v_div_fmas_f32 v35, v35, v40, v56
	v_div_fixup_f32 v40, v35, v34, 1.0
	v_mul_f32_e32 v34, v26, v40
	v_mul_f32_e32 v35, v27, v40
	v_mul_f32_e32 v41, v28, v40
	v_mul_f32_e32 v56, v29, v40
	v_mul_f32_e32 v34, v2, v34
	v_mul_f32_e32 v35, v3, v35
	v_mul_f32_e32 v41, v4, v41
	v_mul_f32_e32 v56, v5, v56
	v_mul_f32_e32 v34, v34, v36
	v_mul_f32_e32 v35, v35, v37
	v_mul_f32_e32 v36, v41, v38
	v_cvt_pk_bf16_f32 v34, v34, v35
	v_mul_f32_e32 v35, v56, v39
	v_cvt_pk_bf16_f32 v35, v36, v35
	v_mul_f32_e32 v36, v14, v40
	v_mul_f32_e32 v36, v6, v36
	v_lshlrev_b32_e32 v37, 16, v52
	v_mul_f32_e32 v36, v36, v37
	v_mul_f32_e32 v37, v15, v40
	v_mul_f32_e32 v37, v7, v37
	v_and_b32_e32 v38, 0xffff0000, v52
	v_mul_f32_e32 v37, v37, v38
	v_cvt_pk_bf16_f32 v36, v36, v37
	v_mul_f32_e32 v37, v16, v40
	s_add_u32 s4, s10, s4
	v_mul_f32_e32 v37, v8, v37
	v_lshlrev_b32_e32 v38, 16, v53
	s_addc_u32 s5, s11, s5
	v_mul_f32_e32 v37, v37, v38
	v_mul_f32_e32 v38, v17, v40
	s_add_u32 s4, s4, s27
	v_mul_f32_e32 v38, v9, v38
	v_and_b32_e32 v39, 0xffff0000, v53
	s_addc_u32 s5, s5, 0
	v_mul_f32_e32 v38, v38, v39
	v_cvt_pk_bf16_f32 v37, v37, v38
	global_store_dwordx2 v42, v[34:35], s[4:5]
	global_store_dwordx2 v42, v[36:37], s[4:5] offset:512
	s_andn2_b64 vcc, exec, s[12:13]
	s_cbranch_vccnz .LBB0_955
.LBB0_967:
	v_mul_f32_e32 v34, v31, v31
	v_mul_f32_e32 v35, v33, v33
	v_fmac_f32_e32 v34, v30, v30
	v_fmac_f32_e32 v35, v32, v32
	v_add_f32_e32 v34, v34, v35
	v_mul_f32_e32 v35, v11, v11
	v_fmac_f32_e32 v35, v10, v10
	v_add_f32_e32 v34, v35, v34
	v_mul_f32_e32 v35, v13, v13
	v_fmac_f32_e32 v35, v12, v12
	v_add_f32_e32 v34, v35, v34
	s_nop 1
	v_add_f32_dpp v35, v34, v34 quad_perm:[1,0,3,2] row_mask:0xf bank_mask:0xf
	v_lshlrev_b32_e32 v36, 16, v48
	v_and_b32_e32 v37, 0xffff0000, v48
	v_lshlrev_b32_e32 v38, 16, v49
	v_and_b32_e32 v39, 0xffff0000, v49
	s_waitcnt lgkmcnt(0)
	v_mov_b32_e32 v34, v35
	s_nop 1
	v_add_f32_dpp v35, v34, v34 quad_perm:[2,3,0,1] row_mask:0xf bank_mask:0xf
	s_ashr_i32 s12, s25, 2
	s_ashr_i32 s13, s12, 31
	s_waitcnt lgkmcnt(0)
	v_mov_b32_e32 v34, v35
	s_nop 1
	v_add_f32_dpp v35, v34, v34 row_half_mirror row_mask:0xf bank_mask:0xf
	s_waitcnt lgkmcnt(0)
	v_mov_b32_e32 v34, v35
	s_nop 1
	v_add_f32_dpp v35, v34, v34 row_mirror row_mask:0xf bank_mask:0xf
	s_waitcnt lgkmcnt(0)
	v_mov_b32_e32 v34, v35
	v_mov_b32_e32 v35, v34
	v_mov_b32_e32 v90, v34
	s_nop 1
	v_permlane16_swap_b32_e32 v35, v90
	s_waitcnt lgkmcnt(0)
	v_add_f32_e32 v34, v35, v90
	v_mov_b32_e32 v35, v34
	v_mov_b32_e32 v90, v34
	s_nop 1
	v_permlane32_swap_b32_e32 v35, v90
	s_waitcnt lgkmcnt(0)
	v_add_f32_e32 v34, v35, v90
	v_fmamk_f32 v34, v34, 0x3b000000, v220
	v_mul_f32_e32 v35, 0x4f800000, v34
	v_cmp_gt_f32_e32 vcc, s43, v34
	s_nop 1
	v_cndmask_b32_e32 v34, v34, v35, vcc
	v_sqrt_f32_e32 v35, v34
	s_nop 0
	v_add_u32_e32 v40, -1, v35
	v_add_u32_e32 v41, 1, v35
	v_fma_f32 v56, -v40, v35, v34
	v_fma_f32 v57, -v41, v35, v34
	v_cmp_ge_f32_e64 s[4:5], 0, v56
	s_nop 1
	v_cndmask_b32_e64 v35, v35, v40, s[4:5]
	v_cmp_lt_f32_e64 s[4:5], 0, v57
	s_nop 1
	v_cndmask_b32_e64 v35, v35, v41, s[4:5]
	v_mul_f32_e32 v40, 0x37800000, v35
	v_cndmask_b32_e32 v35, v35, v40, vcc
	v_cmp_class_f32_e32 vcc, v34, v221
	s_nop 1
	v_cndmask_b32_e32 v34, v35, v34, vcc
	v_div_scale_f32 v35, s[4:5], v34, v34, 1.0
	v_rcp_f32_e32 v40, v35
	v_div_scale_f32 v41, vcc, 1.0, v34, 1.0
	s_lshl_b64 s[4:5], s[12:13], 12
	v_fma_f32 v56, -v35, v40, 1.0
	v_fmac_f32_e32 v40, v56, v40
	v_mul_f32_e32 v56, v41, v40
	v_fma_f32 v57, -v35, v56, v41
	v_fmac_f32_e32 v56, v57, v40
	v_fma_f32 v35, -v35, v56, v41
	v_div_fmas_f32 v35, v35, v40, v56
	v_div_fixup_f32 v40, v35, v34, 1.0
	v_mul_f32_e32 v34, v30, v40
	v_mul_f32_e32 v35, v31, v40
	v_mul_f32_e32 v41, v32, v40
	v_mul_f32_e32 v56, v33, v40
	v_mul_f32_e32 v34, v2, v34
	v_mul_f32_e32 v35, v3, v35
	v_mul_f32_e32 v41, v4, v41
	v_mul_f32_e32 v56, v5, v56
	v_mul_f32_e32 v34, v34, v36
	v_mul_f32_e32 v35, v35, v37
	v_mul_f32_e32 v36, v41, v38
	v_cvt_pk_bf16_f32 v34, v34, v35
	v_mul_f32_e32 v35, v56, v39
	v_cvt_pk_bf16_f32 v35, v36, v35
	v_mul_f32_e32 v36, v10, v40
	v_mul_f32_e32 v36, v6, v36
	v_lshlrev_b32_e32 v37, 16, v54
	v_mul_f32_e32 v36, v36, v37
	v_mul_f32_e32 v37, v11, v40
	v_mul_f32_e32 v37, v7, v37
	v_and_b32_e32 v38, 0xffff0000, v54
	v_mul_f32_e32 v37, v37, v38
	v_cvt_pk_bf16_f32 v36, v36, v37
	v_mul_f32_e32 v37, v12, v40
	s_add_u32 s4, s10, s4
	v_mul_f32_e32 v37, v8, v37
	v_lshlrev_b32_e32 v38, 16, v55
	s_addc_u32 s5, s11, s5
	v_mul_f32_e32 v37, v37, v38
	v_mul_f32_e32 v38, v13, v40
	s_add_u32 s4, s4, s27
	v_mul_f32_e32 v38, v9, v38
	v_and_b32_e32 v39, 0xffff0000, v55
	s_addc_u32 s5, s5, 0
	v_mul_f32_e32 v38, v38, v39
	v_cvt_pk_bf16_f32 v37, v37, v38
	global_store_dwordx2 v42, v[34:35], s[4:5]
	global_store_dwordx2 v42, v[36:37], s[4:5] offset:512
	s_branch .LBB0_955

; __device__ __forceinline__ unsigned cvtpk(float lo, float hi) { unsigned r; asm volatile("v_cvt_pk_bf16_f32 %0, %1, %2" : "=v"(r) : "v"(lo), "v"(hi)); return r; }
; __device__ __forceinline__ void phase_gla_norm(KArgs a, int gw, int NGW, int lane) {
;     ...
;         const float ss = wave_sum((o0[0] * o0[0] + o0[1] * o0[1]) + (o0[2] * o0[2] + o0[3] * o0[3]) + (o1[0] * o1[0] + o1[1] * o1[1]) + (o1[2] * o1[2] + o1[3] * o1[3]));
;         const float rs = 1.0f / sqrtf(ss * (1.0f / 512.0f) + RMS_EPS);
;         const u32x2 ra = *(const u32x2*)(R + off), rb = *(const u32x2*)(R + off + 256);
;         u32x2 w0, w1;
;         w0.x = cvtpk(o0[0] * rs * g0[0] * bflo(ra.x), o0[1] * rs * g0[1] * bfhi(ra.x)); w0.y = cvtpk(o0[2] * rs * g0[2] * bflo(ra.y), o0[3] * rs * g0[3] * bfhi(ra.y));
;         w1.x = cvtpk(o1[0] * rs * g1[0] * bflo(rb.x), o1[1] * rs * g1[1] * bfhi(rb.x)); w1.y = cvtpk(o1[2] * rs * g1[2] * bflo(rb.y), o1[3] * rs * g1[3] * bfhi(rb.y));
;         *(u32x2*)(OG + off) = w0; *(u32x2*)(OG + off + 256) = w1;
.LBB0_970:
	s_waitcnt vmcnt(1)
	v_mul_f32_e32 v26, v11, v11
	v_mul_f32_e32 v27, v13, v13
	v_fmac_f32_e32 v26, v10, v10
	v_fmac_f32_e32 v27, v12, v12
	v_add_f32_e32 v26, v26, v27
	s_waitcnt vmcnt(0)
	v_mul_f32_e32 v27, v15, v15
	v_fmac_f32_e32 v27, v14, v14
	v_add_f32_e32 v26, v27, v26
	v_mul_f32_e32 v27, v17, v17
	v_fmac_f32_e32 v27, v16, v16
	v_add_f32_e32 v26, v27, v26
	s_nop 1
	v_add_f32_dpp v27, v26, v26 quad_perm:[1,0,3,2] row_mask:0xf bank_mask:0xf
	v_lshlrev_b64 v[24:25], 1, v[24:25]
	s_add_i32 s2, s2, s26
	s_cmp_lt_i32 s2, 0x8200
	s_waitcnt lgkmcnt(0)
	v_mov_b32_e32 v26, v27
	s_nop 1
	v_add_f32_dpp v27, v26, v26 quad_perm:[2,3,0,1] row_mask:0xf bank_mask:0xf
	s_waitcnt lgkmcnt(0)
	v_mov_b32_e32 v26, v27
	s_nop 1
	v_add_f32_dpp v27, v26, v26 row_half_mirror row_mask:0xf bank_mask:0xf
	s_waitcnt lgkmcnt(0)
	v_mov_b32_e32 v26, v27
	s_nop 1
	v_add_f32_dpp v27, v26, v26 row_mirror row_mask:0xf bank_mask:0xf
	s_waitcnt lgkmcnt(0)
	v_mov_b32_e32 v26, v27
	v_mov_b32_e32 v27, v26
	v_mov_b32_e32 v90, v26
	s_nop 1
	v_permlane16_swap_b32_e32 v27, v90
	s_waitcnt lgkmcnt(0)
	v_add_f32_e32 v26, v27, v90
	v_mov_b32_e32 v27, v26
	v_mov_b32_e32 v90, v26
	s_nop 1
	v_permlane32_swap_b32_e32 v27, v90
	s_waitcnt lgkmcnt(0)
	v_add_f32_e32 v26, v27, v90
	v_fmamk_f32 v26, v26, 0x3b000000, v220
	v_cmp_gt_f32_e32 vcc, s43, v26
	v_mul_f32_e32 v27, 0x4f800000, v26
	s_nop 0
	v_cndmask_b32_e32 v26, v26, v27, vcc
	v_sqrt_f32_e32 v27, v26
	s_nop 0
	v_add_u32_e32 v34, -1, v27
	v_fma_f32 v35, -v34, v27, v26
	v_cmp_ge_f32_e64 s[4:5], 0, v35
	v_add_u32_e32 v35, 1, v27
	s_nop 0
	v_cndmask_b32_e64 v34, v27, v34, s[4:5]
	v_fma_f32 v27, -v35, v27, v26
	v_cmp_lt_f32_e64 s[4:5], 0, v27
	s_nop 1
	v_cndmask_b32_e64 v27, v34, v35, s[4:5]
	v_mul_f32_e32 v34, 0x37800000, v27
	v_cndmask_b32_e32 v27, v27, v34, vcc
	v_cmp_class_f32_e32 vcc, v26, v221
	s_nop 1
	v_cndmask_b32_e32 v26, v27, v26, vcc
	v_div_scale_f32 v27, s[4:5], v26, v26, 1.0
	v_rcp_f32_e32 v34, v27
	s_nop 0
	v_fma_f32 v35, -v27, v34, 1.0
	v_fmac_f32_e32 v34, v35, v34
	v_div_scale_f32 v35, vcc, 1.0, v26, 1.0
	v_mul_f32_e32 v36, v35, v34
	v_fma_f32 v37, -v27, v36, v35
	v_fmac_f32_e32 v36, v37, v34
	v_fma_f32 v27, -v27, v36, v35
	v_div_fmas_f32 v27, v27, v34, v36
	v_div_fixup_f32 v36, v27, v26, 1.0
	v_lshl_add_u64 v[26:27], s[8:9], 0, v[24:25]
	global_load_dwordx2 v[34:35], v[26:27], off
	s_nop 0
	global_load_dwordx2 v[26:27], v[26:27], off offset:512
	v_mul_f32_e32 v10, v10, v36
	v_mul_f32_e32 v11, v11, v36
	v_mul_f32_e32 v10, v2, v10
	v_mul_f32_e32 v11, v3, v11
	s_waitcnt vmcnt(1)
	v_lshlrev_b32_e32 v37, 16, v34
	v_and_b32_e32 v34, 0xffff0000, v34
	v_mul_f32_e32 v10, v10, v37
	v_mul_f32_e32 v11, v11, v34
	v_cvt_pk_bf16_f32 v10, v10, v11
	v_mul_f32_e32 v11, v12, v36
	v_mul_f32_e32 v11, v4, v11
	v_lshlrev_b32_e32 v12, 16, v35
	v_mul_f32_e32 v11, v11, v12
	v_mul_f32_e32 v12, v13, v36
	v_mul_f32_e32 v12, v5, v12
	v_and_b32_e32 v13, 0xffff0000, v35
	v_mul_f32_e32 v12, v12, v13
	v_cvt_pk_bf16_f32 v11, v11, v12
	v_mul_f32_e32 v12, v14, v36
	v_mul_f32_e32 v12, v6, v12
	s_waitcnt vmcnt(0)
	v_lshlrev_b32_e32 v13, 16, v26
	v_mul_f32_e32 v12, v12, v13
	v_mul_f32_e32 v13, v15, v36
	v_mul_f32_e32 v13, v7, v13
	v_and_b32_e32 v14, 0xffff0000, v26
	v_mul_f32_e32 v13, v13, v14
	v_cvt_pk_bf16_f32 v12, v12, v13
	v_mul_f32_e32 v13, v16, v36
	v_mul_f32_e32 v13, v8, v13
	v_lshlrev_b32_e32 v14, 16, v27
	v_mul_f32_e32 v13, v13, v14
	v_mul_f32_e32 v14, v17, v36
	v_mul_f32_e32 v14, v9, v14
	v_and_b32_e32 v15, 0xffff0000, v27
	v_mul_f32_e32 v14, v14, v15
	v_cvt_pk_bf16_f32 v13, v13, v14
	v_lshl_add_u64 v[14:15], s[10:11], 0, v[24:25]
	global_store_dwordx2 v[14:15], v[10:11], off
	global_store_dwordx2 v[14:15], v[12:13], off offset:512
	s_cbranch_scc0 .LBB0_975
; __device__ __forceinline__ void phase_gla_norm(KArgs a, int gw, int NGW, int lane) {
;     ...
;         else { const int s = row - MPROMPT; const u32x2 qw = *(const u32x2*)(Q + (size_t)row * 1024 + h * 256 + lane * 4), kw = *(const u32x2*)(Kf + (size_t)row * 1024 + h * 256 + lane * 4); const f32x4 q = (f32x4){bflo(qw.x), bfhi(qw.x), bflo(qw.y), bfhi(qw.y)}, k = (f32x4){bflo(kw.x), bfhi(kw.x), bflo(kw.y), bfhi(kw.y)};
;             const float qk = wave_sum((q[0] * k[0] + q[1] * k[1]) + (q[2] * k[2] + q[3] * k[3]));
;             const u32x2 va = *(const u32x2*)(V + off), vb = *(const u32x2*)(V + off + 256);
;             o0 = (f32x4){bflo(va.x), bfhi(va.x), bflo(va.y), bfhi(va.y)} * qk; o1 = (f32x4){bflo(vb.x), bfhi(vb.x), bflo(vb.y), bfhi(vb.y)} * qk;
; #pragma unroll
;             for (int p = 0; p < 8; ++p) { const float* op = OP + ((size_t)p * MSAMP + s) * DM + h * 512 + lane * 4; o0 = o0 + *(const f32x4*)op; o1 = o1 + *(const f32x4*)(op + 256); } }
.LBB0_971:
	s_ashr_i32 s14, s2, 2
	s_ashr_i32 s15, s14, 31
	s_lshl_b64 s[4:5], s[14:15], 11
	v_mov_b32_e32 v25, s5
	v_or_b32_e32 v24, s4, v0
	s_cmpk_gt_i32 s14, 0x1fff
	s_mov_b64 s[16:17], -1
	s_cbranch_scc0 .LBB0_973
	v_lshl_add_u64 v[10:11], v[18:19], 0, s[4:5]
	v_lshl_add_u64 v[12:13], v[20:21], 0, s[4:5]
	global_load_dwordx2 v[10:11], v[10:11], off
	s_add_i32 s48, s14, 0xffffe000
	global_load_dwordx2 v[12:13], v[12:13], off
	s_lshl_b64 s[4:5], s[48:49], 13
	s_mov_b64 s[16:17], 0
	s_waitcnt vmcnt(1)
	v_lshlrev_b32_e32 v15, 16, v11
	v_lshlrev_b32_e32 v14, 16, v10
	v_and_b32_e32 v11, 0xffff0000, v11
	v_and_b32_e32 v10, 0xffff0000, v10
	s_waitcnt vmcnt(0)
	v_lshlrev_b32_e32 v17, 16, v13
	v_lshlrev_b32_e32 v16, 16, v12
	v_and_b32_e32 v13, 0xffff0000, v13
	v_and_b32_e32 v12, 0xffff0000, v12
	v_pk_mul_f32 v[10:11], v[10:11], v[12:13]
	s_nop 0
	v_pk_fma_f32 v[10:11], v[14:15], v[16:17], v[10:11]
	s_nop 0
	v_add_f32_e32 v10, v10, v11
	s_nop 1
	v_add_f32_dpp v11, v10, v10 quad_perm:[1,0,3,2] row_mask:0xf bank_mask:0xf
	s_waitcnt lgkmcnt(0)
	v_mov_b32_e32 v10, v11
	s_nop 1
	v_add_f32_dpp v11, v10, v10 quad_perm:[2,3,0,1] row_mask:0xf bank_mask:0xf
	s_waitcnt lgkmcnt(0)
	v_mov_b32_e32 v10, v11
	s_nop 1
	v_add_f32_dpp v11, v10, v10 row_half_mirror row_mask:0xf bank_mask:0xf
	s_waitcnt lgkmcnt(0)
	v_mov_b32_e32 v10, v11
	s_nop 1
	v_add_f32_dpp v11, v10, v10 row_mirror row_mask:0xf bank_mask:0xf
	s_waitcnt lgkmcnt(0)
	v_mov_b32_e32 v10, v11
	v_mov_b32_e32 v11, v10
	v_mov_b32_e32 v90, v10
	s_nop 1
	v_permlane16_swap_b32_e32 v11, v90
	s_waitcnt lgkmcnt(0)
	v_add_f32_e32 v10, v11, v90
	v_mov_b32_e32 v11, v10
	v_mov_b32_e32 v90, v10
	s_nop 1
	v_permlane32_swap_b32_e32 v11, v90
	s_waitcnt lgkmcnt(0)
	v_add_f32_e32 v16, v11, v90
	v_lshl_add_u64 v[10:11], v[24:25], 1, s[12:13]
	global_load_dwordx2 v[176:177], v[10:11], off
	s_nop 0
	global_load_dwordx2 v[174:175], v[10:11], off offset:512
	v_lshl_add_u64 v[10:11], v[22:23], 0, s[4:5]
	global_load_dwordx4 v[96:99], v[10:11], off
	global_load_dwordx4 v[100:103], v[10:11], off offset:1024
	v_add_co_u32_e32 v38, vcc, s45, v10
	s_nop 1
	v_addc_co_u32_e32 v39, vcc, 0, v11, vcc
	global_load_dwordx4 v[104:107], v[38:39], off
	global_load_dwordx4 v[108:111], v[38:39], off offset:1024
	v_add_co_u32_e32 v38, vcc, s39, v10
	s_nop 1
	v_addc_co_u32_e32 v39, vcc, 0, v11, vcc
	global_load_dwordx4 v[112:115], v[38:39], off
	global_load_dwordx4 v[116:119], v[38:39], off offset:1024
	v_add_co_u32_e32 v38, vcc, s47, v10
	s_nop 1
	v_addc_co_u32_e32 v39, vcc, 0, v11, vcc
	global_load_dwordx4 v[120:123], v[38:39], off
	global_load_dwordx4 v[124:127], v[38:39], off offset:1024
	v_add_co_u32_e32 v38, vcc, s77, v10
	s_nop 1
	v_addc_co_u32_e32 v39, vcc, 0, v11, vcc
	global_load_dwordx4 v[128:131], v[38:39], off
	global_load_dwordx4 v[132:135], v[38:39], off offset:1024
	v_add_co_u32_e32 v38, vcc, s35, v10
	s_nop 1
	v_addc_co_u32_e32 v39, vcc, 0, v11, vcc
	global_load_dwordx4 v[136:139], v[38:39], off
	global_load_dwordx4 v[140:143], v[38:39], off offset:1024
	s_waitcnt vmcnt(0)
	v_lshlrev_b32_e32 v173, 16, v176
	v_lshlrev_b32_e32 v172, 16, v174
	v_and_b32_e32 v171, 0xffff0000, v174
	v_lshlrev_b32_e32 v174, 16, v175
	v_and_b32_e32 v170, 0xffff0000, v175
	v_and_b32_e32 v175, 0xffff0000, v176
	v_lshlrev_b32_e32 v176, 16, v177
	v_and_b32_e32 v169, 0xffff0000, v177
	v_mov_b32_e32 v166, v173
	v_mov_b32_e32 v167, v175
	v_pk_fma_f32 v[164:165], v[16:17], v[166:167], v[96:97] op_sel_hi:[0,1,1]
	v_mov_b32_e32 v96, v176
	v_mov_b32_e32 v97, v169
	v_pk_fma_f32 v[162:163], v[16:17], v[96:97], v[98:99] op_sel_hi:[0,1,1]
	v_mov_b32_e32 v176, v172
	v_mov_b32_e32 v177, v171
	v_pk_fma_f32 v[98:99], v[16:17], v[176:177], v[100:101] op_sel_hi:[0,1,1]
	v_mov_b32_e32 v172, v174
	v_mov_b32_e32 v173, v170
	v_pk_fma_f32 v[100:101], v[16:17], v[172:173], v[102:103] op_sel_hi:[0,1,1]
	v_pk_add_f32 v[174:175], v[106:107], v[162:163]
	v_pk_add_f32 v[170:171], v[104:105], v[164:165]
	v_pk_add_f32 v[164:165], v[110:111], v[100:101]
	v_pk_add_f32 v[162:163], v[108:109], v[98:99]
	v_pk_add_f32 v[110:111], v[112:113], v[170:171]
	v_pk_add_f32 v[170:171], v[114:115], v[174:175]
	v_pk_add_f32 v[174:175], v[116:117], v[162:163]
	v_pk_add_f32 v[162:163], v[118:119], v[164:165]
	v_pk_add_f32 v[164:165], v[122:123], v[170:171]
	v_pk_add_f32 v[170:171], v[120:121], v[110:111]
	v_pk_add_f32 v[122:123], v[126:127], v[162:163]
	v_pk_add_f32 v[162:163], v[124:125], v[174:175]
	v_pk_add_f32 v[174:175], v[128:129], v[170:171]
	v_pk_add_f32 v[170:171], v[130:131], v[164:165]
	v_pk_add_f32 v[164:165], v[132:133], v[162:163]
	v_pk_add_f32 v[162:163], v[134:135], v[122:123]
	v_pk_add_f32 v[134:135], v[138:139], v[170:171]
	v_pk_add_f32 v[170:171], v[136:137], v[174:175]
	v_pk_add_f32 v[174:175], v[142:143], v[162:163]
	v_mov_b32_e32 v12, v140
	v_mov_b32_e32 v13, v141
	v_mov_b32_e32 v14, v142
	v_mov_b32_e32 v15, v143
	v_mov_b32_e32 v16, v162
	v_mov_b32_e32 v17, v163
	v_mov_b32_e32 v26, v170
	v_mov_b32_e32 v27, v171
	v_mov_b32_e32 v34, v134
	v_mov_b32_e32 v35, v135
	v_mov_b32_e32 v36, v164
	v_mov_b32_e32 v37, v165
	v_mov_b32_e32 v38, v174
	v_mov_b32_e32 v39, v175
	v_add_co_u32_e32 v16, vcc, s74, v10
	v_pk_add_f32 v[36:37], v[12:13], v[36:37]
	s_nop 0
	v_addc_co_u32_e32 v17, vcc, 0, v11, vcc
	global_load_dwordx4 v[96:99], v[16:17], off
	global_load_dwordx4 v[100:103], v[16:17], off offset:1024
	v_mov_b32_e32 v174, v36
	v_mov_b32_e32 v175, v37
	v_add_co_u32_e32 v36, vcc, s66, v10
	s_nop 0
	s_nop 1
	v_addc_co_u32_e32 v37, vcc, 0, v11, vcc
	global_load_dwordx4 v[104:107], v[36:37], off
	global_load_dwordx4 v[108:111], v[36:37], off offset:1024
	s_waitcnt vmcnt(0)
	v_pk_add_f32 v[176:177], v[34:35], v[98:99]
	v_pk_add_f32 v[98:99], v[26:27], v[96:97]
	v_pk_add_f32 v[96:97], v[174:175], v[100:101]
	v_pk_add_f32 v[100:101], v[38:39], v[102:103]
	v_pk_add_f32 v[102:103], v[176:177], v[106:107]
	v_pk_add_f32 v[176:177], v[98:99], v[104:105]
	v_pk_add_f32 v[106:107], v[100:101], v[110:111]
	v_pk_add_f32 v[104:105], v[96:97], v[108:109]
	v_mov_b32_e32 v10, v176
	v_mov_b32_e32 v11, v177
	v_mov_b32_e32 v12, v102
	v_mov_b32_e32 v13, v103
	v_mov_b32_e32 v14, v104
	v_mov_b32_e32 v15, v105
	v_mov_b32_e32 v16, v106
	v_mov_b32_e32 v17, v107
	v_mov_b32_e32 v26, v98
	v_mov_b32_e32 v27, v99
	v_mov_b32_e32 v34, v108
	v_mov_b32_e32 v35, v109
	v_mov_b32_e32 v36, v110
	v_mov_b32_e32 v37, v111

; __device__ __forceinline__ u32x4 pack8(const f32x4 a, const f32x4 b) { u32x4 w; w.x = cvt_pk_bf16(a[0], a[1]); w.y = cvt_pk_bf16(a[2], a[3]); w.z = cvt_pk_bf16(b[0], b[1]); w.w = cvt_pk_bf16(b[2], b[3]); return w; }
;     __device__ __forceinline__ void operator()(const f32x4 (&acc)[2][2][4][2], const Unit& u, int wr, int wc, int fr, int fq) const {
;     ...
;                 for (int bj = 0; bj < 2; ++bj) { const float* p = Xin + (size_t)(u.pm * BM + ai * HALF + wr * 64 + m * 16 + fr) * DM + u.pn * BM + bj * HALF + wc * 32 + 8 * fq;
;                     xa[m][bj][0] = *(const f32x4*)p; xa[m][bj][1] = *(const f32x4*)(p + 4); }
; #pragma unroll
;             for (int m = 0; m < 4; ++m) {
;                 const int row = u.pm * BM + ai * HALF + wr * 64 + m * 16 + fr; float ss = 0.f;
; #pragma unroll
;                 for (int bj = 0; bj < 2; ++bj) {
;                     const size_t off = (size_t)row * DM + u.pn * BM + bj * HALF + wc * 32 + 8 * fq;
;                     const f32x4 a0 = xa[m][bj][0] + acc[ai][bj][m][0] * scale, a1 = xa[m][bj][1] + acc[ai][bj][m][1] * scale;
;                     *(f32x4*)(X + off) = a0; *(f32x4*)(X + off + 4) = a1;
;                     ss += (a0[0] * a0[0] + a0[1] * a0[1]) + (a0[2] * a0[2] + a0[3] * a0[3]) + (a1[0] * a1[0] + a1[1] * a1[1]) + (a1[2] * a1[2] + a1[3] * a1[3]);
;                     *(u32x4*)(XB + off) = pack8(a0, a1);
;                 }
;                 ss += __shfl_xor(ss, 16); ss += __shfl_xor(ss, 32);
;                 if (fq == 0) SSo[(size_t)(u.pn * 4 + wc) * MPAD + row] = ss;
.LBB0_1054:
	s_lshl_b32 s6, s84, 8
	v_mov_b32_e32 v130, v216
	v_mov_b32_e32 v132, v189
	s_add_i32 s6, s6, s70
	s_nop 0
	v_add_u32_e32 v206, s6, v130
	s_lshl_b32 s6, s76, 8
	s_ashr_i32 s7, s6, 31
	v_lshlrev_b32_e32 v130, 3, v132
	v_ashrrev_i32_e32 v131, 31, v130
	s_or_b64 s[30:31], s[6:7], s[48:49]
	v_lshl_add_u64 v[204:205], s[30:31], 0, v[130:131]
	s_lshl_b32 s30, s76, 2
	s_or_b32 s31, s30, s68
	s_lshl_b64 s[6:7], s[6:7], 2
	s_add_u32 s6, s78, s6
	s_addc_u32 s7, s79, s7
	v_ashrrev_i32_e32 v207, 31, v206
	v_lshl_add_u64 v[208:209], v[130:131], 2, s[6:7]
	v_lshlrev_b64 v[130:131], 13, v[206:207]
	v_lshl_add_u64 v[130:131], v[208:209], 0, v[130:131]
	global_load_dwordx4 v[234:237], v[130:131], off offset:16
	global_load_dwordx4 v[238:241], v[130:131], off
	global_load_dwordx4 v[242:245], v[130:131], off offset:528
	global_load_dwordx4 v[246:249], v[130:131], off offset:512
	v_add_u32_e32 v214, 16, v206
	v_ashrrev_i32_e32 v215, 31, v214
	v_lshlrev_b64 v[130:131], 13, v[214:215]
	v_add_u32_e32 v212, 32, v206
	v_lshl_add_u64 v[130:131], v[208:209], 0, v[130:131]
	v_ashrrev_i32_e32 v213, 31, v212
	global_load_dwordx4 v[170:173], v[130:131], off offset:16
	global_load_dwordx4 v[174:177], v[130:131], off
	global_load_dwordx4 v[162:165], v[130:131], off offset:528
	global_load_dwordx4 v[166:169], v[130:131], off offset:512
	v_lshlrev_b64 v[130:131], 13, v[212:213]
	v_add_u32_e32 v210, 48, v206
	v_lshl_add_u64 v[130:131], v[208:209], 0, v[130:131]
	v_ashrrev_i32_e32 v211, 31, v210
	global_load_dwordx4 v[154:157], v[130:131], off offset:16
	global_load_dwordx4 v[158:161], v[130:131], off
	global_load_dwordx4 v[138:141], v[130:131], off offset:528
	global_load_dwordx4 v[146:149], v[130:131], off offset:512
	v_lshlrev_b64 v[130:131], 13, v[210:211]
	v_lshl_add_u64 v[134:135], v[208:209], 0, v[130:131]
	v_cmp_eq_u32_e32 vcc, 0, v132
	global_load_dwordx4 v[142:145], v[134:135], off offset:16
	global_load_dwordx4 v[150:153], v[134:135], off
	global_load_dwordx4 v[130:133], v[134:135], off offset:528
	s_nop 0
	global_load_dwordx4 v[134:137], v[134:135], off offset:512
	v_lshlrev_b64 v[222:223], 11, v[206:207]
	v_lshl_add_u64 v[222:223], v[204:205], 0, v[222:223]
	s_mul_hi_i32 s30, s31, 0x8400
	s_mul_i32 s31, s31, 0x8400
	s_waitcnt vmcnt(0)
	v_pk_add_f32 v[128:129], v[128:129], v[236:237]
	v_pk_add_f32 v[124:125], v[124:125], v[240:241]
	v_pk_add_f32 v[122:123], v[122:123], v[238:239]
	v_mul_f32_e32 v236, v125, v125
	v_mul_f32_e32 v232, v123, v123
	v_pk_add_f32 v[126:127], v[126:127], v[234:235]
	v_fmac_f32_e32 v232, v122, v122
	v_fmac_f32_e32 v236, v124, v124
	v_lshl_add_u64 v[234:235], v[222:223], 2, s[14:15]
	v_add_f32_e32 v232, v232, v236
	v_mul_f32_e32 v236, v127, v127
	global_store_dwordx4 v[234:235], v[122:125], off
	global_store_dwordx4 v[234:235], v[126:129], off offset:16
	v_fmac_f32_e32 v236, v126, v126
	v_cvt_pk_bf16_f32 v122, v122, v123
	v_cvt_pk_bf16_f32 v123, v124, v125
	v_cvt_pk_bf16_f32 v124, v126, v127
	v_pk_add_f32 v[120:121], v[120:121], v[248:249]
	v_lshl_add_u64 v[126:127], v[222:223], 1, s[16:17]
	v_pk_add_f32 v[118:119], v[118:119], v[246:247]
	v_cvt_pk_bf16_f32 v125, v128, v129
	global_store_dwordx4 v[126:127], v[122:125], off
	v_pk_add_f32 v[114:115], v[114:115], v[242:243]
	v_pk_add_f32 v[116:117], v[116:117], v[244:245]
	v_mul_f32_e32 v122, v119, v119
	v_mul_f32_e32 v123, v121, v121
	v_fmac_f32_e32 v122, v118, v118
	v_fmac_f32_e32 v123, v120, v120
	v_add_f32_e32 v122, v122, v123
	v_mul_f32_e32 v123, v115, v115
	global_store_dwordx4 v[234:235], v[118:121], off offset:512
	global_store_dwordx4 v[234:235], v[114:117], off offset:528
	v_fmac_f32_e32 v123, v114, v114
	v_cvt_pk_bf16_f32 v118, v118, v119
	v_cvt_pk_bf16_f32 v119, v120, v121
	v_cvt_pk_bf16_f32 v120, v114, v115
	v_add_f32_e32 v232, v236, v232
	v_and_b32_e32 v115, 64, v219
	v_mul_f32_e32 v236, v129, v129
	v_add_f32_e32 v122, v123, v122
	v_mul_f32_e32 v123, v117, v117
	v_xor_b32_e32 v114, 16, v219
	v_add_u32_e32 v115, 64, v115
	v_fmac_f32_e32 v236, v128, v128
	v_fmac_f32_e32 v123, v116, v116
	v_cmp_lt_i32_e64 s[6:7], v114, v115
	v_add_f32_e32 v232, v236, v232
	v_add_f32_e32 v122, v123, v122
	v_cndmask_b32_e64 v114, v219, v114, s[6:7]
	v_add_f32_e32 v122, v232, v122
	v_lshlrev_b32_e32 v234, 2, v114
	v_mov_b32_e32 v114, v122
	v_mov_b32_e32 v252, v122
	s_nop 1
	v_permlane16_swap_b32_e32 v114, v252
	v_cvt_pk_bf16_f32 v121, v116, v117
	v_xor_b32_e32 v116, 32, v219
	v_cmp_lt_i32_e64 s[6:7], v116, v115
	global_store_dwordx4 v[126:127], v[118:121], off offset:256
	s_waitcnt lgkmcnt(0)
	v_add_f32_e32 v114, v114, v252
	v_cndmask_b32_e64 v115, v219, v116, s[6:7]
	v_lshlrev_b32_e32 v235, 2, v115
	v_mov_b32_e32 v115, v114
	v_mov_b32_e32 v252, v114
	s_nop 1
	v_permlane32_swap_b32_e32 v115, v252
	s_and_saveexec_b64 s[6:7], vcc
	s_cbranch_execz .LBB0_1056
	s_add_u32 s54, s58, s31
	s_addc_u32 s55, s59, s30
	v_lshl_add_u64 v[116:117], v[206:207], 2, s[54:55]
	s_waitcnt lgkmcnt(0)
	v_add_f32_e32 v114, v115, v252
	global_store_dword v[116:117], v114, off
; __device__ __forceinline__ u32x4 pack8(const f32x4 a, const f32x4 b) { u32x4 w; w.x = cvt_pk_bf16(a[0], a[1]); w.y = cvt_pk_bf16(a[2], a[3]); w.z = cvt_pk_bf16(b[0], b[1]); w.w = cvt_pk_bf16(b[2], b[3]); return w; }
;     __device__ __forceinline__ void operator()(const f32x4 (&acc)[2][2][4][2], const Unit& u, int wr, int wc, int fr, int fq) const {
;     ...
;             for (int m = 0; m < 4; ++m) {
;                 const int row = u.pm * BM + ai * HALF + wr * 64 + m * 16 + fr; float ss = 0.f;
; #pragma unroll
;                 for (int bj = 0; bj < 2; ++bj) {
;                     const size_t off = (size_t)row * DM + u.pn * BM + bj * HALF + wc * 32 + 8 * fq;
;                     const f32x4 a0 = xa[m][bj][0] + acc[ai][bj][m][0] * scale, a1 = xa[m][bj][1] + acc[ai][bj][m][1] * scale;
;                     *(f32x4*)(X + off) = a0; *(f32x4*)(X + off + 4) = a1;
;                     ss += (a0[0] * a0[0] + a0[1] * a0[1]) + (a0[2] * a0[2] + a0[3] * a0[3]) + (a1[0] * a1[0] + a1[1] * a1[1]) + (a1[2] * a1[2] + a1[3] * a1[3]);
;                     *(u32x4*)(XB + off) = pack8(a0, a1);
;                 }
;                 ss += __shfl_xor(ss, 16); ss += __shfl_xor(ss, 32);
;                 if (fq == 0) SSo[(size_t)(u.pn * 4 + wc) * MPAD + row] = ss;
.LBB0_1056:
	s_or_b64 exec, exec, s[6:7]
	v_pk_add_f32 v[112:113], v[112:113], v[176:177]
	v_pk_add_f32 v[110:111], v[110:111], v[174:175]
	s_waitcnt lgkmcnt(0)
	v_lshlrev_b64 v[114:115], 11, v[214:215]
	v_mul_f32_e32 v118, v111, v111
	v_mul_f32_e32 v119, v113, v113
	v_lshl_add_u64 v[114:115], v[114:115], 0, v[204:205]
	v_pk_add_f32 v[106:107], v[106:107], v[170:171]
	v_fmac_f32_e32 v118, v110, v110
	v_fmac_f32_e32 v119, v112, v112
	v_lshl_add_u64 v[116:117], v[114:115], 2, s[14:15]
	v_add_f32_e32 v118, v118, v119
	v_mul_f32_e32 v119, v107, v107
	v_pk_add_f32 v[104:105], v[104:105], v[168:169]
	v_pk_add_f32 v[102:103], v[102:103], v[166:167]
	v_pk_add_f32 v[108:109], v[108:109], v[172:173]
	global_store_dwordx4 v[116:117], v[110:113], off
	global_store_dwordx4 v[116:117], v[106:109], off offset:16
	v_fmac_f32_e32 v119, v106, v106
	v_cvt_pk_bf16_f32 v110, v110, v111
	v_cvt_pk_bf16_f32 v111, v112, v113
	v_cvt_pk_bf16_f32 v112, v106, v107
	v_add_f32_e32 v118, v119, v118
	v_pk_add_f32 v[106:107], v[98:99], v[162:163]
	v_mul_f32_e32 v98, v103, v103
	v_mul_f32_e32 v99, v105, v105
	v_fmac_f32_e32 v98, v102, v102
	v_fmac_f32_e32 v99, v104, v104
	v_mul_f32_e32 v119, v109, v109
	v_add_f32_e32 v98, v98, v99
	v_mul_f32_e32 v99, v107, v107
	v_fmac_f32_e32 v119, v108, v108
	v_cvt_pk_bf16_f32 v113, v108, v109
	v_pk_add_f32 v[108:109], v[100:101], v[164:165]
	v_fmac_f32_e32 v99, v106, v106
	v_add_f32_e32 v98, v99, v98
	v_mul_f32_e32 v99, v109, v109
	v_fmac_f32_e32 v99, v108, v108
	v_add_f32_e32 v118, v119, v118
	v_add_f32_e32 v98, v99, v98
	v_add_f32_e32 v98, v118, v98
	v_mov_b32_e32 v99, v98
	v_mov_b32_e32 v252, v98
	s_nop 1
	v_permlane16_swap_b32_e32 v99, v252
	v_lshl_add_u64 v[114:115], v[114:115], 1, s[16:17]
	global_store_dwordx4 v[114:115], v[110:113], off
	global_store_dwordx4 v[116:117], v[102:105], off offset:512
	global_store_dwordx4 v[116:117], v[106:109], off offset:528
	v_cvt_pk_bf16_f32 v100, v102, v103
	v_cvt_pk_bf16_f32 v101, v104, v105
	s_waitcnt lgkmcnt(0)
	v_add_f32_e32 v98, v99, v252
	v_mov_b32_e32 v99, v98
	v_mov_b32_e32 v252, v98
	s_nop 1
	v_permlane32_swap_b32_e32 v99, v252
	v_cvt_pk_bf16_f32 v102, v106, v107
	v_cvt_pk_bf16_f32 v103, v108, v109
	global_store_dwordx4 v[114:115], v[100:103], off offset:256
	s_and_saveexec_b64 s[6:7], vcc
	s_cbranch_execz .LBB0_1058
	s_add_u32 s54, s58, s31
	s_addc_u32 s55, s59, s30
	v_lshl_add_u64 v[100:101], v[214:215], 2, s[54:55]
	s_waitcnt lgkmcnt(0)
	v_add_f32_e32 v98, v99, v252
	global_store_dword v[100:101], v98, off
.LBB0_1058:
	s_or_b64 exec, exec, s[6:7]
	v_pk_add_f32 v[96:97], v[96:97], v[160:161]
	v_pk_add_f32 v[94:95], v[94:95], v[158:159]
	s_waitcnt lgkmcnt(0)
	v_lshlrev_b64 v[98:99], 11, v[212:213]
	v_mul_f32_e32 v102, v95, v95
	v_mul_f32_e32 v103, v97, v97
	v_lshl_add_u64 v[98:99], v[98:99], 0, v[204:205]
	v_pk_add_f32 v[90:91], v[90:91], v[154:155]
	v_fmac_f32_e32 v102, v94, v94
	v_fmac_f32_e32 v103, v96, v96
	v_lshl_add_u64 v[100:101], v[98:99], 2, s[14:15]
	v_add_f32_e32 v102, v102, v103
	v_mul_f32_e32 v103, v91, v91
	v_pk_add_f32 v[88:89], v[88:89], v[148:149]
	v_pk_add_f32 v[86:87], v[86:87], v[146:147]
	v_pk_add_f32 v[92:93], v[92:93], v[156:157]
	global_store_dwordx4 v[100:101], v[94:97], off
	global_store_dwordx4 v[100:101], v[90:93], off offset:16
	v_fmac_f32_e32 v103, v90, v90
	v_cvt_pk_bf16_f32 v94, v94, v95
	v_cvt_pk_bf16_f32 v95, v96, v97
	v_cvt_pk_bf16_f32 v96, v90, v91
	v_add_f32_e32 v102, v103, v102
	v_pk_add_f32 v[90:91], v[82:83], v[138:139]
	v_mul_f32_e32 v82, v87, v87
	v_mul_f32_e32 v83, v89, v89
	v_fmac_f32_e32 v82, v86, v86
	v_fmac_f32_e32 v83, v88, v88
	v_mul_f32_e32 v103, v93, v93
	v_add_f32_e32 v82, v82, v83
	v_mul_f32_e32 v83, v91, v91
	v_fmac_f32_e32 v103, v92, v92
	v_cvt_pk_bf16_f32 v97, v92, v93
	v_pk_add_f32 v[92:93], v[84:85], v[140:141]
	v_fmac_f32_e32 v83, v90, v90
	v_add_f32_e32 v82, v83, v82
	v_mul_f32_e32 v83, v93, v93
	v_fmac_f32_e32 v83, v92, v92
	v_add_f32_e32 v102, v103, v102
	v_add_f32_e32 v82, v83, v82
	v_add_f32_e32 v82, v102, v82
	v_mov_b32_e32 v83, v82
	v_mov_b32_e32 v252, v82
	s_nop 1
	v_permlane16_swap_b32_e32 v83, v252
	v_lshl_add_u64 v[98:99], v[98:99], 1, s[16:17]
	global_store_dwordx4 v[98:99], v[94:97], off
	global_store_dwordx4 v[100:101], v[86:89], off offset:512
	global_store_dwordx4 v[100:101], v[90:93], off offset:528
	v_cvt_pk_bf16_f32 v84, v86, v87
	v_cvt_pk_bf16_f32 v85, v88, v89
	s_waitcnt lgkmcnt(0)
	v_add_f32_e32 v82, v83, v252
	v_mov_b32_e32 v83, v82
	v_mov_b32_e32 v252, v82
	s_nop 1
	v_permlane32_swap_b32_e32 v83, v252
	v_cvt_pk_bf16_f32 v86, v90, v91
	v_cvt_pk_bf16_f32 v87, v92, v93
	global_store_dwordx4 v[98:99], v[84:87], off offset:256
	s_and_saveexec_b64 s[6:7], vcc
	s_cbranch_execz .LBB0_1060
	s_add_u32 s54, s58, s31
	s_addc_u32 s55, s59, s30
	v_lshl_add_u64 v[84:85], v[212:213], 2, s[54:55]
	s_waitcnt lgkmcnt(0)
	v_add_f32_e32 v82, v83, v252
	global_store_dword v[84:85], v82, off
; __device__ __forceinline__ u32x4 pack8(const f32x4 a, const f32x4 b) { u32x4 w; w.x = cvt_pk_bf16(a[0], a[1]); w.y = cvt_pk_bf16(a[2], a[3]); w.z = cvt_pk_bf16(b[0], b[1]); w.w = cvt_pk_bf16(b[2], b[3]); return w; }
;     __device__ __forceinline__ void operator()(const f32x4 (&acc)[2][2][4][2], const Unit& u, int wr, int wc, int fr, int fq) const {
;     ...
;                 for (int bj = 0; bj < 2; ++bj) { const float* p = Xin + (size_t)(u.pm * BM + ai * HALF + wr * 64 + m * 16 + fr) * DM + u.pn * BM + bj * HALF + wc * 32 + 8 * fq;
;                     xa[m][bj][0] = *(const f32x4*)p; xa[m][bj][1] = *(const f32x4*)(p + 4); }
; #pragma unroll
;             for (int m = 0; m < 4; ++m) {
;                 const int row = u.pm * BM + ai * HALF + wr * 64 + m * 16 + fr; float ss = 0.f;
; #pragma unroll
;                 for (int bj = 0; bj < 2; ++bj) {
;                     const size_t off = (size_t)row * DM + u.pn * BM + bj * HALF + wc * 32 + 8 * fq;
;                     const f32x4 a0 = xa[m][bj][0] + acc[ai][bj][m][0] * scale, a1 = xa[m][bj][1] + acc[ai][bj][m][1] * scale;
;                     *(f32x4*)(X + off) = a0; *(f32x4*)(X + off + 4) = a1;
;                     ss += (a0[0] * a0[0] + a0[1] * a0[1]) + (a0[2] * a0[2] + a0[3] * a0[3]) + (a1[0] * a1[0] + a1[1] * a1[1]) + (a1[2] * a1[2] + a1[3] * a1[3]);
;                     *(u32x4*)(XB + off) = pack8(a0, a1);
;                 }
;                 ss += __shfl_xor(ss, 16); ss += __shfl_xor(ss, 32);
;                 if (fq == 0) SSo[(size_t)(u.pn * 4 + wc) * MPAD + row] = ss;
.LBB0_1060:
	s_or_b64 exec, exec, s[6:7]
	v_pk_add_f32 v[80:81], v[80:81], v[152:153]
	v_pk_add_f32 v[78:79], v[78:79], v[150:151]
	s_waitcnt lgkmcnt(0)
	v_lshlrev_b64 v[82:83], 11, v[210:211]
	v_mul_f32_e32 v86, v79, v79
	v_mul_f32_e32 v87, v81, v81
	v_lshl_add_u64 v[82:83], v[82:83], 0, v[204:205]
	v_pk_add_f32 v[74:75], v[74:75], v[142:143]
	v_fmac_f32_e32 v86, v78, v78
	v_fmac_f32_e32 v87, v80, v80
	v_lshl_add_u64 v[84:85], v[82:83], 2, s[14:15]
	v_add_f32_e32 v86, v86, v87
	v_mul_f32_e32 v87, v75, v75
	v_pk_add_f32 v[72:73], v[72:73], v[136:137]
	v_pk_add_f32 v[70:71], v[70:71], v[134:135]
	v_pk_add_f32 v[76:77], v[76:77], v[144:145]
	global_store_dwordx4 v[84:85], v[78:81], off
	global_store_dwordx4 v[84:85], v[74:77], off offset:16
	v_fmac_f32_e32 v87, v74, v74
	v_cvt_pk_bf16_f32 v78, v78, v79
	v_cvt_pk_bf16_f32 v79, v80, v81
	v_cvt_pk_bf16_f32 v80, v74, v75
	v_add_f32_e32 v86, v87, v86
	v_pk_add_f32 v[74:75], v[66:67], v[130:131]
	v_mul_f32_e32 v66, v71, v71
	v_mul_f32_e32 v67, v73, v73
	v_fmac_f32_e32 v66, v70, v70
	v_fmac_f32_e32 v67, v72, v72
	v_mul_f32_e32 v87, v77, v77
	v_add_f32_e32 v66, v66, v67
	v_mul_f32_e32 v67, v75, v75
	v_fmac_f32_e32 v87, v76, v76
	v_cvt_pk_bf16_f32 v81, v76, v77
	v_pk_add_f32 v[76:77], v[68:69], v[132:133]
	v_fmac_f32_e32 v67, v74, v74
	v_add_f32_e32 v66, v67, v66
	v_mul_f32_e32 v67, v77, v77
	v_fmac_f32_e32 v67, v76, v76
	v_add_f32_e32 v86, v87, v86
	v_add_f32_e32 v66, v67, v66
	v_add_f32_e32 v66, v86, v66
	v_mov_b32_e32 v67, v66
	v_mov_b32_e32 v252, v66
	s_nop 1
	v_permlane16_swap_b32_e32 v67, v252
	v_lshl_add_u64 v[82:83], v[82:83], 1, s[16:17]
	global_store_dwordx4 v[82:83], v[78:81], off
	global_store_dwordx4 v[84:85], v[70:73], off offset:512
	global_store_dwordx4 v[84:85], v[74:77], off offset:528
	v_cvt_pk_bf16_f32 v68, v70, v71
	v_cvt_pk_bf16_f32 v69, v72, v73
	s_waitcnt lgkmcnt(0)
	v_add_f32_e32 v66, v67, v252
	v_mov_b32_e32 v67, v66
	v_mov_b32_e32 v252, v66
	s_nop 1
	v_permlane32_swap_b32_e32 v67, v252
	v_cvt_pk_bf16_f32 v70, v74, v75
	v_cvt_pk_bf16_f32 v71, v76, v77
	global_store_dwordx4 v[82:83], v[68:71], off offset:256
	s_and_saveexec_b64 s[6:7], vcc
	s_cbranch_execz .LBB0_1062
	s_add_u32 s54, s58, s31
	s_addc_u32 s55, s59, s30
	v_lshl_add_u64 v[68:69], v[210:211], 2, s[54:55]
	s_waitcnt lgkmcnt(0)
	v_add_f32_e32 v66, v67, v252
	global_store_dword v[68:69], v66, off
.LBB0_1062:
	s_or_b64 exec, exec, s[6:7]
	v_add_u32_e32 v128, 0x80, v206
	v_ashrrev_i32_e32 v129, 31, v128
	s_waitcnt lgkmcnt(0)
	v_lshlrev_b64 v[66:67], 13, v[128:129]
	v_lshl_add_u64 v[66:67], v[208:209], 0, v[66:67]
	global_load_dwordx4 v[130:133], v[66:67], off offset:16
	global_load_dwordx4 v[134:137], v[66:67], off
	global_load_dwordx4 v[114:117], v[66:67], off offset:528
	global_load_dwordx4 v[118:121], v[66:67], off offset:512
	v_add_u32_e32 v126, 0x90, v206
	v_ashrrev_i32_e32 v127, 31, v126
	v_lshlrev_b64 v[66:67], 13, v[126:127]
	v_add_u32_e32 v124, 0xa0, v206
	v_lshl_add_u64 v[66:67], v[208:209], 0, v[66:67]
	v_ashrrev_i32_e32 v125, 31, v124
	global_load_dwordx4 v[106:109], v[66:67], off offset:16
	global_load_dwordx4 v[110:113], v[66:67], off
	global_load_dwordx4 v[98:101], v[66:67], off offset:528
	global_load_dwordx4 v[102:105], v[66:67], off offset:512
	v_lshlrev_b64 v[66:67], 13, v[124:125]
	v_add_u32_e32 v122, 0xb0, v206
	v_lshl_add_u64 v[66:67], v[208:209], 0, v[66:67]
	v_ashrrev_i32_e32 v123, 31, v122
	global_load_dwordx4 v[90:93], v[66:67], off offset:16
	global_load_dwordx4 v[94:97], v[66:67], off
	global_load_dwordx4 v[74:77], v[66:67], off offset:528
	global_load_dwordx4 v[82:85], v[66:67], off offset:512
	v_lshlrev_b64 v[66:67], 13, v[122:123]
	v_lshl_add_u64 v[70:71], v[208:209], 0, v[66:67]
	global_load_dwordx4 v[78:81], v[70:71], off offset:16
	global_load_dwordx4 v[86:89], v[70:71], off
	global_load_dwordx4 v[66:69], v[70:71], off offset:528
	s_nop 0
	global_load_dwordx4 v[70:73], v[70:71], off offset:512
	v_lshlrev_b64 v[138:139], 11, v[128:129]
	v_lshl_add_u64 v[138:139], v[138:139], 0, v[204:205]
	s_waitcnt vmcnt(15)
	v_pk_add_f32 v[60:61], v[60:61], v[132:133]
	s_waitcnt vmcnt(14)
	v_pk_add_f32 v[64:65], v[64:65], v[136:137]
	v_pk_add_f32 v[62:63], v[62:63], v[134:135]
	v_mul_f32_e32 v133, v65, v65
	v_mul_f32_e32 v132, v63, v63
	v_pk_add_f32 v[58:59], v[58:59], v[130:131]
	v_fmac_f32_e32 v132, v62, v62
	v_fmac_f32_e32 v133, v64, v64
	v_add_f32_e32 v132, v132, v133
	v_mul_f32_e32 v133, v59, v59
	v_fmac_f32_e32 v133, v58, v58
	v_lshl_add_u64 v[130:131], v[138:139], 2, s[14:15]
	v_add_f32_e32 v132, v133, v132
	v_mul_f32_e32 v133, v61, v61
	s_waitcnt vmcnt(12)
	v_pk_add_f32 v[56:57], v[56:57], v[120:121]
	v_pk_add_f32 v[54:55], v[54:55], v[118:119]
	global_store_dwordx4 v[130:131], v[62:65], off
	global_store_dwordx4 v[130:131], v[58:61], off offset:16
	v_fmac_f32_e32 v133, v60, v60
	v_cvt_pk_bf16_f32 v62, v62, v63
	v_cvt_pk_bf16_f32 v63, v64, v65
	v_cvt_pk_bf16_f32 v64, v58, v59
	v_cvt_pk_bf16_f32 v65, v60, v61
	s_nop 0
	v_mul_f32_e32 v60, v55, v55
	v_mul_f32_e32 v61, v57, v57
	v_pk_add_f32 v[50:51], v[50:51], v[114:115]
	v_fmac_f32_e32 v60, v54, v54
	v_fmac_f32_e32 v61, v56, v56
	v_add_f32_e32 v60, v60, v61
	v_mul_f32_e32 v61, v51, v51
	v_pk_add_f32 v[52:53], v[52:53], v[116:117]
	v_fmac_f32_e32 v61, v50, v50
	v_add_f32_e32 v60, v61, v60
	v_mul_f32_e32 v61, v53, v53
	v_fmac_f32_e32 v61, v52, v52
	v_add_f32_e32 v132, v133, v132
	v_add_f32_e32 v60, v61, v60
	v_lshl_add_u64 v[58:59], v[138:139], 1, s[16:17]
	v_add_f32_e32 v60, v132, v60
	global_store_dwordx4 v[58:59], v[62:65], off
	global_store_dwordx4 v[130:131], v[54:57], off offset:512
	global_store_dwordx4 v[130:131], v[50:53], off offset:528
	s_nop 0
	v_cvt_pk_bf16_f32 v54, v54, v55
	v_cvt_pk_bf16_f32 v55, v56, v57
	v_cvt_pk_bf16_f32 v56, v50, v51
	v_mov_b32_e32 v50, v60
	v_mov_b32_e32 v252, v60
	s_nop 1
	v_permlane16_swap_b32_e32 v50, v252
	v_cvt_pk_bf16_f32 v57, v52, v53
	global_store_dwordx4 v[58:59], v[54:57], off offset:256
	s_waitcnt lgkmcnt(0)
	v_add_f32_e32 v50, v50, v252
	v_mov_b32_e32 v51, v50
	v_mov_b32_e32 v252, v50
	s_nop 1
	v_permlane32_swap_b32_e32 v51, v252
	s_and_saveexec_b64 s[6:7], vcc
	s_cbranch_execz .LBB0_1064
	s_add_u32 s54, s58, s31
	s_addc_u32 s55, s59, s30
	v_lshl_add_u64 v[52:53], v[128:129], 2, s[54:55]
	s_waitcnt lgkmcnt(0)
	v_add_f32_e32 v50, v51, v252
	global_store_dword v[52:53], v50, off
; __device__ __forceinline__ u32x4 pack8(const f32x4 a, const f32x4 b) { u32x4 w; w.x = cvt_pk_bf16(a[0], a[1]); w.y = cvt_pk_bf16(a[2], a[3]); w.z = cvt_pk_bf16(b[0], b[1]); w.w = cvt_pk_bf16(b[2], b[3]); return w; }
;     __device__ __forceinline__ void operator()(const f32x4 (&acc)[2][2][4][2], const Unit& u, int wr, int wc, int fr, int fq) const {
;     ...
;             for (int m = 0; m < 4; ++m) {
;                 const int row = u.pm * BM + ai * HALF + wr * 64 + m * 16 + fr; float ss = 0.f;
; #pragma unroll
;                 for (int bj = 0; bj < 2; ++bj) {
;                     const size_t off = (size_t)row * DM + u.pn * BM + bj * HALF + wc * 32 + 8 * fq;
;                     const f32x4 a0 = xa[m][bj][0] + acc[ai][bj][m][0] * scale, a1 = xa[m][bj][1] + acc[ai][bj][m][1] * scale;
;                     *(f32x4*)(X + off) = a0; *(f32x4*)(X + off + 4) = a1;
;                     ss += (a0[0] * a0[0] + a0[1] * a0[1]) + (a0[2] * a0[2] + a0[3] * a0[3]) + (a1[0] * a1[0] + a1[1] * a1[1]) + (a1[2] * a1[2] + a1[3] * a1[3]);
;                     *(u32x4*)(XB + off) = pack8(a0, a1);
;                 }
;                 ss += __shfl_xor(ss, 16); ss += __shfl_xor(ss, 32);
;                 if (fq == 0) SSo[(size_t)(u.pn * 4 + wc) * MPAD + row] = ss;
.LBB0_1064:
	s_or_b64 exec, exec, s[6:7]
	s_waitcnt vmcnt(16)
	v_pk_add_f32 v[48:49], v[48:49], v[112:113]
	v_pk_add_f32 v[46:47], v[46:47], v[110:111]
	s_waitcnt lgkmcnt(0)
	v_lshlrev_b64 v[50:51], 11, v[126:127]
	v_mul_f32_e32 v54, v47, v47
	v_mul_f32_e32 v55, v49, v49
	v_lshl_add_u64 v[50:51], v[50:51], 0, v[204:205]
	v_pk_add_f32 v[42:43], v[42:43], v[106:107]
	v_fmac_f32_e32 v54, v46, v46
	v_fmac_f32_e32 v55, v48, v48
	v_lshl_add_u64 v[52:53], v[50:51], 2, s[14:15]
	v_add_f32_e32 v54, v54, v55
	v_mul_f32_e32 v55, v43, v43
	s_waitcnt vmcnt(14)
	v_pk_add_f32 v[40:41], v[40:41], v[104:105]
	v_pk_add_f32 v[38:39], v[38:39], v[102:103]
	v_pk_add_f32 v[44:45], v[44:45], v[108:109]
	global_store_dwordx4 v[52:53], v[46:49], off
	global_store_dwordx4 v[52:53], v[42:45], off offset:16
	v_fmac_f32_e32 v55, v42, v42
	v_cvt_pk_bf16_f32 v46, v46, v47
	v_cvt_pk_bf16_f32 v47, v48, v49
	v_cvt_pk_bf16_f32 v48, v42, v43
	v_add_f32_e32 v54, v55, v54
	v_pk_add_f32 v[42:43], v[34:35], v[98:99]
	v_mul_f32_e32 v34, v39, v39
	v_mul_f32_e32 v35, v41, v41
	v_fmac_f32_e32 v34, v38, v38
	v_fmac_f32_e32 v35, v40, v40
	v_mul_f32_e32 v55, v45, v45
	v_add_f32_e32 v34, v34, v35
	v_mul_f32_e32 v35, v43, v43
	v_fmac_f32_e32 v55, v44, v44
	v_cvt_pk_bf16_f32 v49, v44, v45
	v_pk_add_f32 v[44:45], v[36:37], v[100:101]
	v_fmac_f32_e32 v35, v42, v42
	v_add_f32_e32 v34, v35, v34
	v_mul_f32_e32 v35, v45, v45
	v_fmac_f32_e32 v35, v44, v44
	v_add_f32_e32 v54, v55, v54
	v_add_f32_e32 v34, v35, v34
	v_add_f32_e32 v34, v54, v34
	v_mov_b32_e32 v35, v34
	v_mov_b32_e32 v252, v34
	s_nop 1
	v_permlane16_swap_b32_e32 v35, v252
	v_lshl_add_u64 v[50:51], v[50:51], 1, s[16:17]
	global_store_dwordx4 v[50:51], v[46:49], off
	global_store_dwordx4 v[52:53], v[38:41], off offset:512
	global_store_dwordx4 v[52:53], v[42:45], off offset:528
	v_cvt_pk_bf16_f32 v36, v38, v39
	v_cvt_pk_bf16_f32 v37, v40, v41
	s_waitcnt lgkmcnt(0)
	v_add_f32_e32 v34, v35, v252
	v_mov_b32_e32 v35, v34
	v_mov_b32_e32 v252, v34
	s_nop 1
	v_permlane32_swap_b32_e32 v35, v252
	v_cvt_pk_bf16_f32 v38, v42, v43
	v_cvt_pk_bf16_f32 v39, v44, v45
	global_store_dwordx4 v[50:51], v[36:39], off offset:256
	s_and_saveexec_b64 s[6:7], vcc
	s_cbranch_execz .LBB0_1066
	s_add_u32 s54, s58, s31
	s_addc_u32 s55, s59, s30
	v_lshl_add_u64 v[36:37], v[126:127], 2, s[54:55]
	s_waitcnt lgkmcnt(0)
	v_add_f32_e32 v34, v35, v252
	global_store_dword v[36:37], v34, off
; __device__ __forceinline__ u32x4 pack8(const f32x4 a, const f32x4 b) { u32x4 w; w.x = cvt_pk_bf16(a[0], a[1]); w.y = cvt_pk_bf16(a[2], a[3]); w.z = cvt_pk_bf16(b[0], b[1]); w.w = cvt_pk_bf16(b[2], b[3]); return w; }
;     __device__ __forceinline__ void operator()(const f32x4 (&acc)[2][2][4][2], const Unit& u, int wr, int wc, int fr, int fq) const {
;     ...
;             for (int m = 0; m < 4; ++m) {
;                 const int row = u.pm * BM + ai * HALF + wr * 64 + m * 16 + fr; float ss = 0.f;
; #pragma unroll
;                 for (int bj = 0; bj < 2; ++bj) {
;                     const size_t off = (size_t)row * DM + u.pn * BM + bj * HALF + wc * 32 + 8 * fq;
;                     const f32x4 a0 = xa[m][bj][0] + acc[ai][bj][m][0] * scale, a1 = xa[m][bj][1] + acc[ai][bj][m][1] * scale;
;                     *(f32x4*)(X + off) = a0; *(f32x4*)(X + off + 4) = a1;
;                     ss += (a0[0] * a0[0] + a0[1] * a0[1]) + (a0[2] * a0[2] + a0[3] * a0[3]) + (a1[0] * a1[0] + a1[1] * a1[1]) + (a1[2] * a1[2] + a1[3] * a1[3]);
;                     *(u32x4*)(XB + off) = pack8(a0, a1);
;                 }
;                 ss += __shfl_xor(ss, 16); ss += __shfl_xor(ss, 32);
;                 if (fq == 0) SSo[(size_t)(u.pn * 4 + wc) * MPAD + row] = ss;
.LBB0_1066:
	s_or_b64 exec, exec, s[6:7]
	s_waitcnt vmcnt(18)
	v_pk_add_f32 v[32:33], v[32:33], v[96:97]
	v_pk_add_f32 v[30:31], v[30:31], v[94:95]
	s_waitcnt lgkmcnt(0)
	v_lshlrev_b64 v[34:35], 11, v[124:125]
	v_mul_f32_e32 v38, v31, v31
	v_mul_f32_e32 v39, v33, v33
	v_lshl_add_u64 v[34:35], v[34:35], 0, v[204:205]
	v_pk_add_f32 v[26:27], v[26:27], v[90:91]
	v_fmac_f32_e32 v38, v30, v30
	v_fmac_f32_e32 v39, v32, v32
	v_lshl_add_u64 v[36:37], v[34:35], 2, s[14:15]
	v_add_f32_e32 v38, v38, v39
	v_mul_f32_e32 v39, v27, v27
	s_waitcnt vmcnt(16)
	v_pk_add_f32 v[24:25], v[24:25], v[84:85]
	v_pk_add_f32 v[22:23], v[22:23], v[82:83]
	v_pk_add_f32 v[28:29], v[28:29], v[92:93]
	global_store_dwordx4 v[36:37], v[30:33], off
	global_store_dwordx4 v[36:37], v[26:29], off offset:16
	v_fmac_f32_e32 v39, v26, v26
	v_cvt_pk_bf16_f32 v30, v30, v31
	v_cvt_pk_bf16_f32 v31, v32, v33
	v_cvt_pk_bf16_f32 v32, v26, v27
	v_add_f32_e32 v38, v39, v38
	v_pk_add_f32 v[26:27], v[18:19], v[74:75]
	v_mul_f32_e32 v18, v23, v23
	v_mul_f32_e32 v19, v25, v25
	v_fmac_f32_e32 v18, v22, v22
	v_fmac_f32_e32 v19, v24, v24
	v_mul_f32_e32 v39, v29, v29
	v_add_f32_e32 v18, v18, v19
	v_mul_f32_e32 v19, v27, v27
	v_fmac_f32_e32 v39, v28, v28
	v_cvt_pk_bf16_f32 v33, v28, v29
	v_pk_add_f32 v[28:29], v[20:21], v[76:77]
	v_fmac_f32_e32 v19, v26, v26
	v_add_f32_e32 v18, v19, v18
	v_mul_f32_e32 v19, v29, v29
	v_fmac_f32_e32 v19, v28, v28
	v_add_f32_e32 v38, v39, v38
	v_add_f32_e32 v18, v19, v18
	v_add_f32_e32 v18, v38, v18
	v_mov_b32_e32 v19, v18
	v_mov_b32_e32 v252, v18
	s_nop 1
	v_permlane16_swap_b32_e32 v19, v252
	v_lshl_add_u64 v[34:35], v[34:35], 1, s[16:17]
	global_store_dwordx4 v[34:35], v[30:33], off
	global_store_dwordx4 v[36:37], v[22:25], off offset:512
	global_store_dwordx4 v[36:37], v[26:29], off offset:528
	v_cvt_pk_bf16_f32 v20, v22, v23
	v_cvt_pk_bf16_f32 v21, v24, v25
	s_waitcnt lgkmcnt(0)
	v_add_f32_e32 v18, v19, v252
	v_mov_b32_e32 v19, v18
	v_mov_b32_e32 v252, v18
	s_nop 1
	v_permlane32_swap_b32_e32 v19, v252
	v_cvt_pk_bf16_f32 v22, v26, v27
	v_cvt_pk_bf16_f32 v23, v28, v29
	global_store_dwordx4 v[34:35], v[20:23], off offset:256
	s_and_saveexec_b64 s[6:7], vcc
	s_cbranch_execz .LBB0_1068
	s_add_u32 s54, s58, s31
	s_addc_u32 s55, s59, s30
	v_lshl_add_u64 v[20:21], v[124:125], 2, s[54:55]
	s_waitcnt lgkmcnt(0)
	v_add_f32_e32 v18, v19, v252
	global_store_dword v[20:21], v18, off
.LBB0_1068:
	s_or_b64 exec, exec, s[6:7]
	s_waitcnt vmcnt(20)
	v_pk_add_f32 v[16:17], v[16:17], v[88:89]
	v_pk_add_f32 v[14:15], v[14:15], v[86:87]
	s_waitcnt lgkmcnt(0)
	v_lshlrev_b64 v[18:19], 11, v[122:123]
	v_mul_f32_e32 v22, v15, v15
	v_mul_f32_e32 v23, v17, v17
	v_lshl_add_u64 v[18:19], v[18:19], 0, v[204:205]
	v_pk_add_f32 v[10:11], v[10:11], v[78:79]
	v_fmac_f32_e32 v22, v14, v14
	v_fmac_f32_e32 v23, v16, v16
	v_lshl_add_u64 v[20:21], v[18:19], 2, s[14:15]
	v_add_f32_e32 v22, v22, v23
	v_mul_f32_e32 v23, v11, v11
	s_waitcnt vmcnt(18)
	v_pk_add_f32 v[8:9], v[8:9], v[72:73]
	v_pk_add_f32 v[6:7], v[6:7], v[70:71]
	v_pk_add_f32 v[12:13], v[12:13], v[80:81]
	global_store_dwordx4 v[20:21], v[14:17], off
	global_store_dwordx4 v[20:21], v[10:13], off offset:16
	v_fmac_f32_e32 v23, v10, v10
	v_cvt_pk_bf16_f32 v14, v14, v15
	v_cvt_pk_bf16_f32 v15, v16, v17
	v_cvt_pk_bf16_f32 v16, v10, v11
	v_add_f32_e32 v22, v23, v22
	v_pk_add_f32 v[10:11], v[2:3], v[66:67]
	v_mul_f32_e32 v2, v7, v7
	v_mul_f32_e32 v3, v9, v9
	v_fmac_f32_e32 v2, v6, v6
	v_fmac_f32_e32 v3, v8, v8
	v_mul_f32_e32 v23, v13, v13
	v_add_f32_e32 v2, v2, v3
	v_mul_f32_e32 v3, v11, v11
	v_fmac_f32_e32 v23, v12, v12
	v_cvt_pk_bf16_f32 v17, v12, v13
	v_pk_add_f32 v[12:13], v[4:5], v[68:69]
	v_fmac_f32_e32 v3, v10, v10
	v_add_f32_e32 v2, v3, v2
	v_mul_f32_e32 v3, v13, v13
	v_fmac_f32_e32 v3, v12, v12
	v_add_f32_e32 v22, v23, v22
	v_add_f32_e32 v2, v3, v2
	v_add_f32_e32 v2, v22, v2
	v_mov_b32_e32 v3, v2
	v_mov_b32_e32 v252, v2
	s_nop 1
	v_permlane16_swap_b32_e32 v3, v252
	v_lshl_add_u64 v[18:19], v[18:19], 1, s[16:17]
	global_store_dwordx4 v[18:19], v[14:17], off
	global_store_dwordx4 v[20:21], v[6:9], off offset:512
	global_store_dwordx4 v[20:21], v[10:13], off offset:528
	v_cvt_pk_bf16_f32 v4, v6, v7
	v_cvt_pk_bf16_f32 v5, v8, v9
	s_waitcnt lgkmcnt(0)
	v_add_f32_e32 v2, v3, v252
	v_mov_b32_e32 v3, v2
	v_mov_b32_e32 v252, v2
	s_nop 1
	v_permlane32_swap_b32_e32 v3, v252
	v_cvt_pk_bf16_f32 v6, v10, v11
	v_cvt_pk_bf16_f32 v7, v12, v13
	global_store_dwordx4 v[18:19], v[4:7], off offset:256
	s_and_saveexec_b64 s[6:7], vcc
	s_cbranch_execz .LBB0_1070
	s_add_u32 s54, s58, s31
	s_addc_u32 s55, s59, s30
	v_lshl_add_u64 v[4:5], v[122:123], 2, s[54:55]
	s_waitcnt lgkmcnt(0)
	v_add_f32_e32 v2, v3, v252
	global_store_dword v[4:5], v2, off

; __device__ __forceinline__ unsigned cvtpk(float lo, float hi) { unsigned r; asm volatile("v_cvt_pk_bf16_f32 %0, %1, %2" : "=v"(r) : "v"(lo), "v"(hi)); return r; }
; template <int NSL>
; __device__ __forceinline__ void phase_samp_fin(KArgs a, float scale, int gw, int NGW, int lane) {
;     ...
;         const int rl = it >> 3, pn = it & 7, col = pn * 256 + lane * 4;
;         f32x4 p[NSL];
; #pragma unroll
;         for (int s2 = 0; s2 < NSL; ++s2) p[s2] = *(const f32x4*)(PS + ((size_t)s2 * 128 + rl) * DM + col);
;         const size_t off = (size_t)(MPROMPT + rl) * DM + col; f32x4 x = *(const f32x4*)(X + off); f32x4 s = p[0];
; #pragma unroll
;         for (int s2 = 1; s2 < NSL; ++s2) s = s + p[s2];
;         x = x + s * scale; *(f32x4*)(X + off) = x;
;         u32x2 w; w.x = cvtpk(x[0], x[1]); w.y = cvtpk(x[2], x[3]); *(u32x2*)(XB + off) = w;
;         float ss = (x[0] * x[0] + x[1] * x[1]) + (x[2] * x[2] + x[3] * x[3]);
;         ss += __shfl_xor(ss, 1); ss += __shfl_xor(ss, 2); ss += __shfl_xor(ss, 4); ss += __shfl_xor(ss, 8);
;         if ((lane & 15) == 0) SS[(size_t)(pn * 4 + (lane >> 4)) * MPAD + MPROMPT + rl] = ss;
.LBB0_1151:
	s_ashr_i32 s12, s2, 3
	s_ashr_i32 s13, s12, 31
	s_and_b32 s18, s2, 7
	s_lshl_b64 s[14:15], s[12:13], 13
	v_lshl_or_b32 v36, s18, 8, v2
	s_add_u32 s14, s16, s14
	s_addc_u32 s15, s17, s15
	v_lshlrev_b32_e32 v0, 2, v36
	v_lshl_add_u64 v[32:33], s[14:15], 0, v[0:1]
	v_add_co_u32_e32 v8, vcc, s45, v32
	s_waitcnt lgkmcnt(0)
	global_load_dwordx4 v[4:7], v0, s[14:15]
	v_addc_co_u32_e32 v9, vcc, 0, v33, vcc
	v_add_co_u32_e32 v12, vcc, s39, v32
	global_load_dwordx4 v[8:11], v[8:9], off
	s_nop 0
	v_addc_co_u32_e32 v13, vcc, 0, v33, vcc
	v_add_co_u32_e32 v16, vcc, s47, v32
	global_load_dwordx4 v[12:15], v[12:13], off
	s_nop 0
	v_addc_co_u32_e32 v17, vcc, 0, v33, vcc
	v_add_co_u32_e32 v20, vcc, s77, v32
	global_load_dwordx4 v[16:19], v[16:17], off
	s_nop 0
	v_addc_co_u32_e32 v21, vcc, 0, v33, vcc
	v_add_co_u32_e32 v24, vcc, s35, v32
	s_lshl_b64 s[14:15], s[12:13], 11
	s_nop 0
	v_addc_co_u32_e32 v25, vcc, 0, v33, vcc
	v_add_co_u32_e32 v28, vcc, s74, v32
	global_load_dwordx4 v[20:23], v[20:21], off
	s_nop 0
	v_addc_co_u32_e32 v29, vcc, 0, v33, vcc
	s_add_u32 s14, s14, 0x1000000
	global_load_dwordx4 v[24:27], v[24:25], off
	v_add_co_u32_e32 v32, vcc, s66, v32
	s_addc_u32 s15, s15, 0
	global_load_dwordx4 v[28:31], v[28:29], off
	v_addc_co_u32_e32 v33, vcc, 0, v33, vcc
	v_or_b32_e32 v40, s14, v36
	v_mov_b32_e32 v41, s15
	global_load_dwordx4 v[32:35], v[32:33], off
	v_lshl_add_u64 v[42:43], v[40:41], 2, s[10:11]
	global_load_dwordx4 v[36:39], v[42:43], off
	s_waitcnt vmcnt(7)
	v_pk_add_f32 v[4:5], v[4:5], v[8:9]
	v_pk_add_f32 v[6:7], v[6:7], v[10:11]
	v_lshl_add_u64 v[10:11], v[40:41], 1, s[8:9]
	s_waitcnt vmcnt(6)
	v_pk_add_f32 v[4:5], v[4:5], v[12:13]
	v_pk_add_f32 v[6:7], v[6:7], v[14:15]
	s_waitcnt vmcnt(5)
	v_pk_add_f32 v[4:5], v[4:5], v[16:17]
	v_pk_add_f32 v[6:7], v[6:7], v[18:19]
	s_waitcnt vmcnt(4)
	v_pk_add_f32 v[4:5], v[4:5], v[20:21]
	v_pk_add_f32 v[6:7], v[6:7], v[22:23]
	s_waitcnt vmcnt(3)
	v_pk_add_f32 v[4:5], v[4:5], v[24:25]
	v_pk_add_f32 v[6:7], v[6:7], v[26:27]
	s_waitcnt vmcnt(2)
	v_pk_add_f32 v[4:5], v[4:5], v[28:29]
	v_pk_add_f32 v[6:7], v[6:7], v[30:31]
	s_waitcnt vmcnt(1)
	v_pk_add_f32 v[4:5], v[4:5], v[32:33]
	v_pk_add_f32 v[6:7], v[6:7], v[34:35]
	s_waitcnt vmcnt(0)
	v_pk_add_f32 v[4:5], v[36:37], v[4:5]
	v_pk_add_f32 v[6:7], v[38:39], v[6:7]
	v_mul_f32_e32 v0, v5, v5
	global_store_dwordx4 v[42:43], v[4:7], off
	v_cvt_pk_bf16_f32 v8, v4, v5
	v_fmac_f32_e32 v0, v4, v4
	v_cvt_pk_bf16_f32 v9, v6, v7
	global_store_dwordx2 v[10:11], v[8:9], off
	v_mul_f32_e32 v4, v7, v7
	v_fmac_f32_e32 v4, v6, v6
	v_and_b32_e32 v5, 64, v219
	v_add_f32_e32 v0, v0, v4
	v_xor_b32_e32 v4, 1, v219
	v_add_u32_e32 v5, 64, v5
	v_cmp_lt_i32_e32 vcc, v4, v5
	s_nop 1
	v_cndmask_b32_e32 v4, v219, v4, vcc
	v_lshlrev_b32_e32 v4, 2, v4
	s_nop 1
	v_add_f32_dpp v4, v0, v0 quad_perm:[1,0,3,2] row_mask:0xf bank_mask:0xf
	s_waitcnt lgkmcnt(0)
	v_mov_b32_e32 v0, v4
	v_xor_b32_e32 v4, 2, v219
	v_cmp_lt_i32_e32 vcc, v4, v5
	s_nop 1
	v_cndmask_b32_e32 v4, v219, v4, vcc
	v_lshlrev_b32_e32 v4, 2, v4
	s_nop 1
	v_add_f32_dpp v4, v0, v0 quad_perm:[2,3,0,1] row_mask:0xf bank_mask:0xf
	s_waitcnt lgkmcnt(0)
	v_mov_b32_e32 v0, v4
	v_xor_b32_e32 v4, 4, v219
	v_cmp_lt_i32_e32 vcc, v4, v5
	s_nop 1
	v_cndmask_b32_e32 v4, v219, v4, vcc
	v_lshlrev_b32_e32 v4, 2, v4
	s_nop 1
	v_add_f32_dpp v4, v0, v0 row_half_mirror row_mask:0xf bank_mask:0xf
	s_waitcnt lgkmcnt(0)
	v_mov_b32_e32 v0, v4
	v_xor_b32_e32 v4, 8, v219
	v_cmp_lt_i32_e32 vcc, v4, v5
	s_nop 1
	v_cndmask_b32_e32 v4, v219, v4, vcc
	v_lshlrev_b32_e32 v4, 2, v4
	s_nop 1
	v_add_f32_dpp v4, v0, v0 row_mirror row_mask:0xf bank_mask:0xf
	s_and_saveexec_b64 s[14:15], s[4:5]
	s_cbranch_execz .LBB0_1150
	s_waitcnt lgkmcnt(0)
	v_mov_b32_e32 v6, v4
	v_lshl_or_b32 v0, s18, 2, v3
	v_mul_u32_u24_e32 v0, 0x2100, v0
	v_lshlrev_b32_e32 v0, 2, v0
	v_lshl_add_u64 v[4:5], s[6:7], 0, v[0:1]
	v_lshl_add_u64 v[4:5], s[12:13], 2, v[4:5]
	v_add_co_u32_e32 v4, vcc, 0x8000, v4
	s_nop 1
	v_addc_co_u32_e32 v5, vcc, 0, v5, vcc
	global_store_dword v[4:5], v6, off
	s_branch .LBB0_1150

; __device__ __forceinline__ void rows_rstd(const float* SS, const Unit& u, int wr, int fr, int fq, float (&rs)[2][4]) {
;     ...
;             for (int m = 0; m < 4; ++m) {
;                 const int row = u.pm * BM + ai * HALF + wr * 64 + m * 16 + fr; float s = 0.f;
; #pragma unroll
;                 for (int j = 0; j < 8; ++j) s += SS[(size_t)(fq * 8 + j) * MPAD + row];
;                 s += __shfl_xor(s, 16); s += __shfl_xor(s, 32);
;                 rs[ai][m] = 1.0f / sqrtf(s * (1.0f / 2048.0f) + RMS_EPS);
.LBB0_1235:
	s_lshl_b32 s6, s27, 8
	v_mov_b32_e32 v140, v189
	v_mov_b32_e32 v141, v194
	s_add_i32 s6, s6, s84
	s_cmp_lt_i32 s27, 32
	v_add_u32_e32 v168, s6, v141
	v_lshlrev_b32_e32 v170, 3, v140
	v_add_u32_e32 v154, 16, v168
	v_add_u32_e32 v150, 32, v168
	v_add_u32_e32 v148, 48, v168
	v_add_u32_e32 v146, 0x80, v168
	v_add_u32_e32 v144, 0x90, v168
	v_add_u32_e32 v142, 0xa0, v168
	s_mov_b64 s[6:7], -1
	v_ashrrev_i32_e32 v169, 31, v168
	v_ashrrev_i32_e32 v171, 31, v170
	v_ashrrev_i32_e32 v155, 31, v154
	v_ashrrev_i32_e32 v151, 31, v150
	v_ashrrev_i32_e32 v149, 31, v148
	v_ashrrev_i32_e32 v147, 31, v146
	v_ashrrev_i32_e32 v145, 31, v144
	v_ashrrev_i32_e32 v143, 31, v142
	v_add_u32_e32 v140, 0xb0, v168
	s_cbranch_scc1 .LBB0_1237
	v_and_b32_e32 v152, 64, v219
	v_xor_b32_e32 v141, 16, v219
	v_add_u32_e32 v152, 64, v152
	v_cmp_lt_i32_e32 vcc, v141, v152
	v_lshl_add_u64 v[174:175], v[168:169], 2, s[14:15]
	v_mad_i64_i32 v[158:159], s[6:7], v170, s46, v[174:175]
	v_cndmask_b32_e32 v141, v219, v141, vcc
	v_lshlrev_b32_e32 v157, 2, v141
	v_xor_b32_e32 v141, 32, v219
	v_cmp_lt_i32_e32 vcc, v141, v152
	s_nop 1
	v_cndmask_b32_e32 v141, v219, v141, vcc
	v_lshlrev_b32_e32 v153, 2, v141
	global_load_dword v208, v[158:159], off
	v_or_b32_e32 v158, 1, v170
	v_mad_i64_i32 v[160:161], s[6:7], v158, s46, v[174:175]
	global_load_dword v209, v[160:161], off
	v_or_b32_e32 v159, 2, v170
	v_mad_i64_i32 v[160:161], s[6:7], v159, s46, v[174:175]
	global_load_dword v210, v[160:161], off
	v_or_b32_e32 v161, 3, v170
	v_mad_i64_i32 v[162:163], s[6:7], v161, s46, v[174:175]
	global_load_dword v211, v[162:163], off
	v_or_b32_e32 v163, 4, v170
	v_mad_i64_i32 v[164:165], s[6:7], v163, s46, v[174:175]
	global_load_dword v212, v[164:165], off
	v_or_b32_e32 v165, 5, v170
	v_mad_i64_i32 v[166:167], s[6:7], v165, s46, v[174:175]
	global_load_dword v213, v[166:167], off
	v_or_b32_e32 v167, 6, v170
	v_mad_i64_i32 v[172:173], s[6:7], v167, s46, v[174:175]
	global_load_dword v214, v[172:173], off
	v_or_b32_e32 v173, 7, v170
	v_mad_i64_i32 v[174:175], s[6:7], v173, s46, v[174:175]
	global_load_dword v215, v[174:175], off
	v_lshl_add_u64 v[174:175], v[154:155], 2, s[14:15]
	s_waitcnt vmcnt(0)
	v_add_f32_e32 v141, 0, v208
	v_add_f32_e32 v141, v141, v209
	v_add_f32_e32 v141, v141, v210
	v_add_f32_e32 v141, v141, v211
	v_add_f32_e32 v141, v141, v212
	v_add_f32_e32 v141, v141, v213
	v_add_f32_e32 v141, v141, v214
	v_add_f32_e32 v141, v141, v215
	v_mov_b32_e32 v152, v141
	v_mov_b32_e32 v216, v141
	s_nop 1
	v_permlane16_swap_b32_e32 v152, v216
	s_waitcnt lgkmcnt(0)
	v_add_f32_e32 v141, v152, v216
	v_mov_b32_e32 v152, v141
	v_mov_b32_e32 v216, v141
	s_nop 1
	v_permlane32_swap_b32_e32 v152, v216
	s_waitcnt lgkmcnt(0)
	v_add_f32_e32 v141, v152, v216
	v_fmamk_f32 v141, v141, 0x3a000000, v220
	v_cmp_gt_f32_e32 vcc, s43, v141
	v_mul_f32_e32 v152, 0x4f800000, v141
	s_nop 0
	v_cndmask_b32_e32 v141, v141, v152, vcc
	v_sqrt_f32_e32 v152, v141
	s_nop 0
	v_add_u32_e32 v156, -1, v152
	v_fma_f32 v160, -v156, v152, v141
	v_cmp_ge_f32_e64 s[6:7], 0, v160
	v_add_u32_e32 v160, 1, v152
	s_nop 0
	v_cndmask_b32_e64 v156, v152, v156, s[6:7]
	v_fma_f32 v152, -v160, v152, v141
	v_cmp_lt_f32_e64 s[6:7], 0, v152
	s_nop 1
	v_cndmask_b32_e64 v152, v156, v160, s[6:7]
	v_mul_f32_e32 v156, 0x37800000, v152
	v_cndmask_b32_e32 v152, v152, v156, vcc
	v_cmp_class_f32_e32 vcc, v141, v221
	v_mad_i64_i32 v[176:177], s[6:7], v170, s46, v[174:175]
	s_nop 0
	v_cndmask_b32_e32 v141, v152, v141, vcc
	v_div_scale_f32 v152, s[6:7], v141, v141, 1.0
	v_rcp_f32_e32 v156, v152
	s_nop 0
	v_fma_f32 v160, -v152, v156, 1.0
	v_fmac_f32_e32 v156, v160, v156
	v_div_scale_f32 v160, vcc, 1.0, v141, 1.0
	v_mul_f32_e32 v162, v160, v156
	v_fma_f32 v164, -v152, v162, v160
	v_fmac_f32_e32 v162, v164, v156
	v_fma_f32 v152, -v152, v162, v160
	v_div_fmas_f32 v152, v152, v156, v162
	v_div_fixup_f32 v172, v152, v141, 1.0
	global_load_dword v208, v[176:177], off
	v_mad_i64_i32 v[176:177], s[6:7], v158, s46, v[174:175]
	global_load_dword v209, v[176:177], off
	v_mad_i64_i32 v[176:177], s[6:7], v159, s46, v[174:175]
	global_load_dword v210, v[176:177], off
	v_mad_i64_i32 v[176:177], s[6:7], v161, s46, v[174:175]
	global_load_dword v211, v[176:177], off
	v_mad_i64_i32 v[176:177], s[6:7], v163, s46, v[174:175]
	global_load_dword v212, v[176:177], off
	v_mad_i64_i32 v[176:177], s[6:7], v165, s46, v[174:175]
	global_load_dword v213, v[176:177], off
	v_mad_i64_i32 v[176:177], s[6:7], v167, s46, v[174:175]
	v_mad_i64_i32 v[174:175], s[6:7], v173, s46, v[174:175]
	global_load_dword v214, v[176:177], off
	global_load_dword v215, v[174:175], off
	v_lshl_add_u64 v[174:175], v[150:151], 2, s[14:15]
	s_waitcnt vmcnt(0)
	v_add_f32_e32 v141, 0, v208
	v_add_f32_e32 v141, v141, v209
	v_add_f32_e32 v141, v141, v210
	v_add_f32_e32 v141, v141, v211
	v_add_f32_e32 v141, v141, v212
	v_add_f32_e32 v141, v141, v213
	v_add_f32_e32 v141, v141, v214
	v_add_f32_e32 v141, v141, v215
	v_mov_b32_e32 v152, v141
	v_mov_b32_e32 v216, v141
	s_nop 1
	v_permlane16_swap_b32_e32 v152, v216
	s_waitcnt lgkmcnt(0)
	v_add_f32_e32 v141, v152, v216
	v_mov_b32_e32 v152, v141
	v_mov_b32_e32 v216, v141
	s_nop 1
	v_permlane32_swap_b32_e32 v152, v216
	s_waitcnt lgkmcnt(0)
; __device__ __forceinline__ void rows_rstd(const float* SS, const Unit& u, int wr, int fr, int fq, float (&rs)[2][4]) {
;     ...
;             for (int m = 0; m < 4; ++m) {
;                 const int row = u.pm * BM + ai * HALF + wr * 64 + m * 16 + fr; float s = 0.f;
; #pragma unroll
;                 for (int j = 0; j < 8; ++j) s += SS[(size_t)(fq * 8 + j) * MPAD + row];
;                 s += __shfl_xor(s, 16); s += __shfl_xor(s, 32);
;                 rs[ai][m] = 1.0f / sqrtf(s * (1.0f / 2048.0f) + RMS_EPS);
	v_add_f32_e32 v141, v152, v216
	v_fmamk_f32 v141, v141, 0x3a000000, v220
	v_cmp_gt_f32_e32 vcc, s43, v141
	v_mul_f32_e32 v152, 0x4f800000, v141
	s_nop 0
	v_cndmask_b32_e32 v141, v141, v152, vcc
	v_sqrt_f32_e32 v152, v141
	s_nop 0
	v_add_u32_e32 v156, -1, v152
	v_fma_f32 v160, -v156, v152, v141
	v_cmp_ge_f32_e64 s[6:7], 0, v160
	v_add_u32_e32 v160, 1, v152
	s_nop 0
	v_cndmask_b32_e64 v156, v152, v156, s[6:7]
	v_fma_f32 v152, -v160, v152, v141
	v_cmp_lt_f32_e64 s[6:7], 0, v152
	s_nop 1
	v_cndmask_b32_e64 v152, v156, v160, s[6:7]
	v_mul_f32_e32 v156, 0x37800000, v152
	v_cndmask_b32_e32 v152, v152, v156, vcc
	v_cmp_class_f32_e32 vcc, v141, v221
	v_mad_i64_i32 v[176:177], s[6:7], v170, s46, v[174:175]
	s_nop 0
	v_cndmask_b32_e32 v141, v152, v141, vcc
	v_div_scale_f32 v152, s[6:7], v141, v141, 1.0
	v_rcp_f32_e32 v156, v152
	s_nop 0
	v_fma_f32 v160, -v152, v156, 1.0
	v_fmac_f32_e32 v156, v160, v156
	v_div_scale_f32 v160, vcc, 1.0, v141, 1.0
	v_mul_f32_e32 v162, v160, v156
	v_fma_f32 v164, -v152, v162, v160
	v_fmac_f32_e32 v162, v164, v156
	v_fma_f32 v152, -v152, v162, v160
	v_div_fmas_f32 v152, v152, v156, v162
	v_div_fixup_f32 v166, v152, v141, 1.0
	global_load_dword v208, v[176:177], off
	v_mad_i64_i32 v[176:177], s[6:7], v158, s46, v[174:175]
	global_load_dword v209, v[176:177], off
	v_mad_i64_i32 v[176:177], s[6:7], v159, s46, v[174:175]
	global_load_dword v210, v[176:177], off
	v_mad_i64_i32 v[176:177], s[6:7], v161, s46, v[174:175]
	global_load_dword v211, v[176:177], off
	v_mad_i64_i32 v[176:177], s[6:7], v163, s46, v[174:175]
	global_load_dword v212, v[176:177], off
	v_mad_i64_i32 v[176:177], s[6:7], v165, s46, v[174:175]
	global_load_dword v213, v[176:177], off
	v_mad_i64_i32 v[176:177], s[6:7], v167, s46, v[174:175]
	v_mad_i64_i32 v[174:175], s[6:7], v173, s46, v[174:175]
	global_load_dword v214, v[176:177], off
	global_load_dword v215, v[174:175], off
	v_lshl_add_u64 v[174:175], v[148:149], 2, s[14:15]
	s_waitcnt vmcnt(0)
	v_add_f32_e32 v141, 0, v208
	v_add_f32_e32 v141, v141, v209
	v_add_f32_e32 v141, v141, v210
	v_add_f32_e32 v141, v141, v211
	v_add_f32_e32 v141, v141, v212
	v_add_f32_e32 v141, v141, v213
	v_add_f32_e32 v141, v141, v214
	v_add_f32_e32 v141, v141, v215
	v_mov_b32_e32 v152, v141
	v_mov_b32_e32 v216, v141
	s_nop 1
	v_permlane16_swap_b32_e32 v152, v216
	s_waitcnt lgkmcnt(0)
	v_add_f32_e32 v141, v152, v216
	v_mov_b32_e32 v152, v141
	v_mov_b32_e32 v216, v141
	s_nop 1
	v_permlane32_swap_b32_e32 v152, v216
	s_waitcnt lgkmcnt(0)
	v_add_f32_e32 v141, v152, v216
	v_fmamk_f32 v141, v141, 0x3a000000, v220
	v_cmp_gt_f32_e32 vcc, s43, v141
	v_mul_f32_e32 v152, 0x4f800000, v141
	s_nop 0
	v_cndmask_b32_e32 v141, v141, v152, vcc
	v_sqrt_f32_e32 v152, v141
	s_nop 0
	v_add_u32_e32 v156, -1, v152
	v_fma_f32 v160, -v156, v152, v141
	v_cmp_ge_f32_e64 s[6:7], 0, v160
	v_add_u32_e32 v160, 1, v152
	s_nop 0
	v_cndmask_b32_e64 v156, v152, v156, s[6:7]
	v_fma_f32 v152, -v160, v152, v141
	v_cmp_lt_f32_e64 s[6:7], 0, v152
	s_nop 1
	v_cndmask_b32_e64 v152, v156, v160, s[6:7]
	v_mul_f32_e32 v156, 0x37800000, v152
	v_cndmask_b32_e32 v152, v152, v156, vcc
	v_cmp_class_f32_e32 vcc, v141, v221
	v_mad_i64_i32 v[176:177], s[6:7], v170, s46, v[174:175]
	s_nop 0
	v_cndmask_b32_e32 v141, v152, v141, vcc
	v_div_scale_f32 v152, s[6:7], v141, v141, 1.0
	v_rcp_f32_e32 v156, v152
	s_nop 0
	v_fma_f32 v160, -v152, v156, 1.0
	v_fmac_f32_e32 v156, v160, v156
	v_div_scale_f32 v160, vcc, 1.0, v141, 1.0
	v_mul_f32_e32 v162, v160, v156
	v_fma_f32 v164, -v152, v162, v160
	v_fmac_f32_e32 v162, v164, v156
	v_fma_f32 v152, -v152, v162, v160
	v_div_fmas_f32 v152, v152, v156, v162
	v_div_fixup_f32 v164, v152, v141, 1.0
	global_load_dword v208, v[176:177], off
	v_mad_i64_i32 v[176:177], s[6:7], v158, s46, v[174:175]
	global_load_dword v209, v[176:177], off
	v_mad_i64_i32 v[176:177], s[6:7], v159, s46, v[174:175]
	global_load_dword v210, v[176:177], off
	v_mad_i64_i32 v[176:177], s[6:7], v161, s46, v[174:175]
	global_load_dword v211, v[176:177], off
	v_mad_i64_i32 v[176:177], s[6:7], v163, s46, v[174:175]
	global_load_dword v212, v[176:177], off
	v_mad_i64_i32 v[176:177], s[6:7], v165, s46, v[174:175]
	global_load_dword v213, v[176:177], off
	v_mad_i64_i32 v[176:177], s[6:7], v167, s46, v[174:175]
	v_mad_i64_i32 v[174:175], s[6:7], v173, s46, v[174:175]
	global_load_dword v214, v[176:177], off
	global_load_dword v215, v[174:175], off
	s_waitcnt vmcnt(0)
	v_add_f32_e32 v141, 0, v208
	v_add_f32_e32 v141, v141, v209
	v_add_f32_e32 v141, v141, v210
	v_add_f32_e32 v141, v141, v211
	v_add_f32_e32 v141, v141, v212
	v_add_f32_e32 v141, v141, v213
	v_add_f32_e32 v141, v141, v214
	v_add_f32_e32 v141, v141, v215
	v_mov_b32_e32 v152, v141
	v_mov_b32_e32 v216, v141
	s_nop 1
	v_permlane16_swap_b32_e32 v152, v216
	s_waitcnt lgkmcnt(0)
	v_add_f32_e32 v141, v152, v216
	v_mov_b32_e32 v152, v141
	v_mov_b32_e32 v216, v141
	s_nop 1
	v_permlane32_swap_b32_e32 v152, v216
	s_waitcnt lgkmcnt(0)
; __device__ __forceinline__ void rows_rstd(const float* SS, const Unit& u, int wr, int fr, int fq, float (&rs)[2][4]) {
;     ...
;             for (int m = 0; m < 4; ++m) {
;                 const int row = u.pm * BM + ai * HALF + wr * 64 + m * 16 + fr; float s = 0.f;
; #pragma unroll
;                 for (int j = 0; j < 8; ++j) s += SS[(size_t)(fq * 8 + j) * MPAD + row];
;                 s += __shfl_xor(s, 16); s += __shfl_xor(s, 32);
;                 rs[ai][m] = 1.0f / sqrtf(s * (1.0f / 2048.0f) + RMS_EPS);
	v_add_f32_e32 v141, v152, v216
	v_fmamk_f32 v141, v141, 0x3a000000, v220
	v_cmp_gt_f32_e32 vcc, s43, v141
	v_mul_f32_e32 v152, 0x4f800000, v141
	s_nop 0
	v_cndmask_b32_e32 v141, v141, v152, vcc
	v_sqrt_f32_e32 v152, v141
	s_nop 0
	v_add_u32_e32 v156, -1, v152
	v_fma_f32 v160, -v156, v152, v141
	v_cmp_ge_f32_e64 s[6:7], 0, v160
	v_add_u32_e32 v160, 1, v152
	s_nop 0
	v_cndmask_b32_e64 v156, v152, v156, s[6:7]
	v_fma_f32 v152, -v160, v152, v141
	v_cmp_lt_f32_e64 s[6:7], 0, v152
	s_nop 1
	v_cndmask_b32_e64 v152, v156, v160, s[6:7]
	v_mul_f32_e32 v156, 0x37800000, v152
	v_cndmask_b32_e32 v152, v152, v156, vcc
	v_cmp_class_f32_e32 vcc, v141, v221
	s_nop 1
	v_cndmask_b32_e32 v141, v152, v141, vcc
	v_div_scale_f32 v152, s[6:7], v141, v141, 1.0
	v_rcp_f32_e32 v156, v152
	s_nop 0
	v_fma_f32 v160, -v152, v156, 1.0
	v_fmac_f32_e32 v156, v160, v156
	v_div_scale_f32 v160, vcc, 1.0, v141, 1.0
	v_mul_f32_e32 v162, v160, v156
	v_fma_f32 v174, -v152, v162, v160
	v_fmac_f32_e32 v162, v174, v156
	v_fma_f32 v152, -v152, v162, v160
	v_lshl_add_u64 v[174:175], v[146:147], 2, s[14:15]
	v_div_fmas_f32 v152, v152, v156, v162
	v_mad_i64_i32 v[176:177], s[6:7], v170, s46, v[174:175]
	v_div_fixup_f32 v162, v152, v141, 1.0
	global_load_dword v208, v[176:177], off
	v_mad_i64_i32 v[176:177], s[6:7], v158, s46, v[174:175]
	global_load_dword v209, v[176:177], off
	v_mad_i64_i32 v[176:177], s[6:7], v159, s46, v[174:175]
	global_load_dword v210, v[176:177], off
	v_mad_i64_i32 v[176:177], s[6:7], v161, s46, v[174:175]
	global_load_dword v211, v[176:177], off
	v_mad_i64_i32 v[176:177], s[6:7], v163, s46, v[174:175]
	global_load_dword v212, v[176:177], off
	v_mad_i64_i32 v[176:177], s[6:7], v165, s46, v[174:175]
	global_load_dword v213, v[176:177], off
	v_mad_i64_i32 v[176:177], s[6:7], v167, s46, v[174:175]
	v_mad_i64_i32 v[174:175], s[6:7], v173, s46, v[174:175]
	global_load_dword v214, v[176:177], off
	global_load_dword v215, v[174:175], off
	s_waitcnt vmcnt(0)
	v_add_f32_e32 v141, 0, v208
	v_add_f32_e32 v141, v141, v209
	v_add_f32_e32 v141, v141, v210
	v_add_f32_e32 v141, v141, v211
	v_add_f32_e32 v141, v141, v212
	v_add_f32_e32 v141, v141, v213
	v_add_f32_e32 v141, v141, v214
	v_add_f32_e32 v141, v141, v215
	v_mov_b32_e32 v152, v141
	v_mov_b32_e32 v216, v141
	s_nop 1
	v_permlane16_swap_b32_e32 v152, v216
	s_waitcnt lgkmcnt(0)
	v_add_f32_e32 v141, v152, v216
	v_mov_b32_e32 v152, v141
	v_mov_b32_e32 v216, v141
	s_nop 1
	v_permlane32_swap_b32_e32 v152, v216
	s_waitcnt lgkmcnt(0)
	v_add_f32_e32 v141, v152, v216
	v_fmamk_f32 v141, v141, 0x3a000000, v220
	v_cmp_gt_f32_e32 vcc, s43, v141
	v_mul_f32_e32 v152, 0x4f800000, v141
	s_nop 0
	v_cndmask_b32_e32 v141, v141, v152, vcc
	v_sqrt_f32_e32 v152, v141
	s_nop 0
	v_add_u32_e32 v156, -1, v152
	v_fma_f32 v160, -v156, v152, v141
	v_cmp_ge_f32_e64 s[6:7], 0, v160
	v_add_u32_e32 v160, 1, v152
	s_nop 0
	v_cndmask_b32_e64 v156, v152, v156, s[6:7]
	v_fma_f32 v152, -v160, v152, v141
	v_cmp_lt_f32_e64 s[6:7], 0, v152
	s_nop 1
	v_cndmask_b32_e64 v152, v156, v160, s[6:7]
	v_mul_f32_e32 v156, 0x37800000, v152
	v_cndmask_b32_e32 v152, v152, v156, vcc
	v_cmp_class_f32_e32 vcc, v141, v221
	s_nop 1
	v_cndmask_b32_e32 v141, v152, v141, vcc
	v_div_scale_f32 v152, s[6:7], v141, v141, 1.0
	v_rcp_f32_e32 v156, v152
	s_nop 0
	v_fma_f32 v160, -v152, v156, 1.0
	v_fmac_f32_e32 v156, v160, v156
	v_div_scale_f32 v160, vcc, 1.0, v141, 1.0
	v_mul_f32_e32 v174, v160, v156
	v_fma_f32 v175, -v152, v174, v160
	v_fmac_f32_e32 v174, v175, v156
	v_fma_f32 v152, -v152, v174, v160
	v_div_fmas_f32 v152, v152, v156, v174
	v_lshl_add_u64 v[174:175], v[144:145], 2, s[14:15]
	v_mad_i64_i32 v[176:177], s[6:7], v170, s46, v[174:175]
	v_div_fixup_f32 v160, v152, v141, 1.0
	global_load_dword v208, v[176:177], off
	v_mad_i64_i32 v[176:177], s[6:7], v158, s46, v[174:175]
	global_load_dword v209, v[176:177], off
	v_mad_i64_i32 v[176:177], s[6:7], v159, s46, v[174:175]
	global_load_dword v210, v[176:177], off
	v_mad_i64_i32 v[176:177], s[6:7], v161, s46, v[174:175]
	global_load_dword v211, v[176:177], off
	v_mad_i64_i32 v[176:177], s[6:7], v163, s46, v[174:175]
	global_load_dword v212, v[176:177], off
	v_mad_i64_i32 v[176:177], s[6:7], v165, s46, v[174:175]
	global_load_dword v213, v[176:177], off
	v_mad_i64_i32 v[176:177], s[6:7], v167, s46, v[174:175]
	v_mad_i64_i32 v[174:175], s[6:7], v173, s46, v[174:175]
	global_load_dword v214, v[176:177], off
	global_load_dword v215, v[174:175], off
	s_waitcnt vmcnt(0)
	v_add_f32_e32 v141, 0, v208
	v_add_f32_e32 v141, v141, v209
	v_add_f32_e32 v141, v141, v210
	v_add_f32_e32 v141, v141, v211
	v_add_f32_e32 v141, v141, v212
	v_add_f32_e32 v141, v141, v213
	v_add_f32_e32 v141, v141, v214
	v_add_f32_e32 v141, v141, v215
	v_mov_b32_e32 v152, v141
	v_mov_b32_e32 v216, v141
	s_nop 1
	v_permlane16_swap_b32_e32 v152, v216
	s_waitcnt lgkmcnt(0)
	v_add_f32_e32 v141, v152, v216
	v_mov_b32_e32 v152, v141
	v_mov_b32_e32 v216, v141
	s_nop 1
	v_permlane32_swap_b32_e32 v152, v216
	s_waitcnt lgkmcnt(0)
; __device__ __forceinline__ void rows_rstd(const float* SS, const Unit& u, int wr, int fr, int fq, float (&rs)[2][4]) {
;     ...
;                 const int row = u.pm * BM + ai * HALF + wr * 64 + m * 16 + fr; float s = 0.f;
; #pragma unroll
;                 for (int j = 0; j < 8; ++j) s += SS[(size_t)(fq * 8 + j) * MPAD + row];
;                 s += __shfl_xor(s, 16); s += __shfl_xor(s, 32);
;                 rs[ai][m] = 1.0f / sqrtf(s * (1.0f / 2048.0f) + RMS_EPS);
	v_add_f32_e32 v141, v152, v216
	v_fmamk_f32 v141, v141, 0x3a000000, v220
	v_cmp_gt_f32_e32 vcc, s43, v141
	v_mul_f32_e32 v152, 0x4f800000, v141
	s_nop 0
	v_cndmask_b32_e32 v141, v141, v152, vcc
	v_sqrt_f32_e32 v152, v141
	s_nop 0
	v_add_u32_e32 v156, -1, v152
	v_fma_f32 v174, -v156, v152, v141
	v_cmp_ge_f32_e64 s[6:7], 0, v174
	v_add_u32_e32 v174, 1, v152
	s_nop 0
	v_cndmask_b32_e64 v156, v152, v156, s[6:7]
	v_fma_f32 v152, -v174, v152, v141
	v_cmp_lt_f32_e64 s[6:7], 0, v152
	s_nop 1
	v_cndmask_b32_e64 v152, v156, v174, s[6:7]
	v_mul_f32_e32 v156, 0x37800000, v152
	v_cndmask_b32_e32 v152, v152, v156, vcc
	v_cmp_class_f32_e32 vcc, v141, v221
	s_nop 1
	v_cndmask_b32_e32 v141, v152, v141, vcc
	v_div_scale_f32 v152, s[6:7], v141, v141, 1.0
	v_rcp_f32_e32 v156, v152
	s_nop 0
	v_fma_f32 v174, -v152, v156, 1.0
	v_fmac_f32_e32 v156, v174, v156
	v_div_scale_f32 v174, vcc, 1.0, v141, 1.0
	v_mul_f32_e32 v175, v174, v156
	v_fma_f32 v176, -v152, v175, v174
	v_fmac_f32_e32 v175, v176, v156
	v_fma_f32 v152, -v152, v175, v174
	v_div_fmas_f32 v152, v152, v156, v175
	v_lshl_add_u64 v[174:175], v[142:143], 2, s[14:15]
	v_mad_i64_i32 v[176:177], s[6:7], v170, s46, v[174:175]
	v_div_fixup_f32 v156, v152, v141, 1.0
	global_load_dword v208, v[176:177], off
	v_mad_i64_i32 v[176:177], s[6:7], v158, s46, v[174:175]
	global_load_dword v209, v[176:177], off
	v_mad_i64_i32 v[176:177], s[6:7], v159, s46, v[174:175]
	global_load_dword v210, v[176:177], off
	v_mad_i64_i32 v[176:177], s[6:7], v161, s46, v[174:175]
	global_load_dword v211, v[176:177], off
	v_mad_i64_i32 v[176:177], s[6:7], v163, s46, v[174:175]
	global_load_dword v212, v[176:177], off
	v_mad_i64_i32 v[176:177], s[6:7], v165, s46, v[174:175]
	global_load_dword v213, v[176:177], off
	v_mad_i64_i32 v[176:177], s[6:7], v167, s46, v[174:175]
	v_mad_i64_i32 v[174:175], s[6:7], v173, s46, v[174:175]
	global_load_dword v214, v[176:177], off
	global_load_dword v215, v[174:175], off
	s_waitcnt vmcnt(0)
	v_add_f32_e32 v141, 0, v208
	v_add_f32_e32 v141, v141, v209
	v_add_f32_e32 v141, v141, v210
	v_add_f32_e32 v141, v141, v211
	v_add_f32_e32 v141, v141, v212
	v_add_f32_e32 v141, v141, v213
	v_add_f32_e32 v141, v141, v214
	v_add_f32_e32 v141, v141, v215
	v_mov_b32_e32 v152, v141
	v_mov_b32_e32 v216, v141
	s_nop 1
	v_permlane16_swap_b32_e32 v152, v216
	s_waitcnt lgkmcnt(0)
	v_add_f32_e32 v141, v152, v216
	v_mov_b32_e32 v152, v141
	v_mov_b32_e32 v216, v141
	s_nop 1
	v_permlane32_swap_b32_e32 v152, v216
	s_waitcnt lgkmcnt(0)
	v_add_f32_e32 v141, v152, v216
	v_fmamk_f32 v141, v141, 0x3a000000, v220
	v_cmp_gt_f32_e32 vcc, s43, v141
	v_mul_f32_e32 v152, 0x4f800000, v141
	s_nop 0
	v_cndmask_b32_e32 v141, v141, v152, vcc
	v_sqrt_f32_e32 v152, v141
	s_nop 0
	v_add_u32_e32 v174, -1, v152
	v_fma_f32 v175, -v174, v152, v141
	v_cmp_ge_f32_e64 s[6:7], 0, v175
	v_add_u32_e32 v175, 1, v152
	s_nop 0
	v_cndmask_b32_e64 v174, v152, v174, s[6:7]
	v_fma_f32 v152, -v175, v152, v141
	v_cmp_lt_f32_e64 s[6:7], 0, v152
	s_nop 1
	v_cndmask_b32_e64 v152, v174, v175, s[6:7]
	v_mul_f32_e32 v174, 0x37800000, v152
	v_cndmask_b32_e32 v152, v152, v174, vcc
	v_cmp_class_f32_e32 vcc, v141, v221
	s_nop 1
	v_cndmask_b32_e32 v141, v152, v141, vcc
	v_div_scale_f32 v152, s[6:7], v141, v141, 1.0
	v_rcp_f32_e32 v174, v152
	s_nop 0
	v_fma_f32 v175, -v152, v174, 1.0
	v_fmac_f32_e32 v174, v175, v174
	v_div_scale_f32 v175, vcc, 1.0, v141, 1.0
	v_mul_f32_e32 v176, v175, v174
	v_fma_f32 v177, -v152, v176, v175
	v_fmac_f32_e32 v176, v177, v174
	v_fma_f32 v152, -v152, v176, v175
	v_div_fmas_f32 v152, v152, v174, v176
	v_div_fixup_f32 v152, v152, v141, 1.0
	v_ashrrev_i32_e32 v141, 31, v140
	v_lshl_add_u64 v[174:175], v[140:141], 2, s[14:15]
	v_mad_i64_i32 v[176:177], s[6:7], v170, s46, v[174:175]
	global_load_dword v208, v[176:177], off
	v_mad_i64_i32 v[176:177], s[6:7], v158, s46, v[174:175]
	global_load_dword v209, v[176:177], off
	v_mad_i64_i32 v[158:159], s[6:7], v159, s46, v[174:175]
	global_load_dword v210, v[158:159], off
	v_mad_i64_i32 v[158:159], s[6:7], v161, s46, v[174:175]
	global_load_dword v211, v[158:159], off
	v_mad_i64_i32 v[158:159], s[6:7], v163, s46, v[174:175]
	global_load_dword v212, v[158:159], off
	v_mad_i64_i32 v[158:159], s[6:7], v165, s46, v[174:175]
	global_load_dword v213, v[158:159], off
	v_mad_i64_i32 v[158:159], s[6:7], v167, s46, v[174:175]
	global_load_dword v214, v[158:159], off
	v_mad_i64_i32 v[158:159], s[6:7], v173, s46, v[174:175]
	global_load_dword v215, v[158:159], off
	s_waitcnt vmcnt(0)
	v_add_f32_e32 v141, 0, v208
	v_add_f32_e32 v141, v141, v209
	v_add_f32_e32 v141, v141, v210
	v_add_f32_e32 v141, v141, v211
	v_add_f32_e32 v141, v141, v212
	v_add_f32_e32 v141, v141, v213
	v_add_f32_e32 v141, v141, v214
	v_add_f32_e32 v141, v141, v215
	v_mov_b32_e32 v157, v141
	v_mov_b32_e32 v216, v141
	s_nop 1
	v_permlane16_swap_b32_e32 v157, v216
	s_waitcnt lgkmcnt(0)
	v_add_f32_e32 v141, v157, v216
	v_mov_b32_e32 v153, v141
	v_mov_b32_e32 v216, v141
	s_nop 1
	v_permlane32_swap_b32_e32 v153, v216
	s_waitcnt lgkmcnt(0)
	v_add_f32_e32 v141, v153, v216
	v_fmamk_f32 v141, v141, 0x3a000000, v220
	v_cmp_gt_f32_e32 vcc, s43, v141
	v_mul_f32_e32 v153, 0x4f800000, v141
	s_nop 0
	v_cndmask_b32_e32 v141, v141, v153, vcc
	v_sqrt_f32_e32 v153, v141
	s_nop 0
	v_add_u32_e32 v157, -1, v153
	v_fma_f32 v158, -v157, v153, v141
	v_cmp_ge_f32_e64 s[6:7], 0, v158
	v_add_u32_e32 v158, 1, v153
	s_nop 0
	v_cndmask_b32_e64 v157, v153, v157, s[6:7]
	v_fma_f32 v153, -v158, v153, v141
	v_cmp_lt_f32_e64 s[6:7], 0, v153
	s_nop 1
	v_cndmask_b32_e64 v153, v157, v158, s[6:7]
	v_mul_f32_e32 v157, 0x37800000, v153
	v_cndmask_b32_e32 v153, v153, v157, vcc
	v_cmp_class_f32_e32 vcc, v141, v221
	s_nop 1
	v_cndmask_b32_e32 v141, v153, v141, vcc
	v_div_scale_f32 v153, s[6:7], v141, v141, 1.0
	v_rcp_f32_e32 v157, v153
	s_mov_b64 s[6:7], 0
	v_fma_f32 v158, -v153, v157, 1.0
	v_fmac_f32_e32 v157, v158, v157
	v_div_scale_f32 v158, vcc, 1.0, v141, 1.0
	v_mul_f32_e32 v159, v158, v157
	v_fma_f32 v161, -v153, v159, v158
	v_fmac_f32_e32 v159, v161, v157
	v_fma_f32 v153, -v153, v159, v158
	v_div_fmas_f32 v153, v153, v157, v159
	v_div_fixup_f32 v158, v153, v141, 1.0

; __device__ __forceinline__ unsigned cvtpk(float lo, float hi) { unsigned r; asm volatile("v_cvt_pk_bf16_f32 %0, %1, %2" : "=v"(r) : "v"(lo), "v"(hi)); return r; }
; template <int NSL>
; __device__ __forceinline__ void phase_samp_fin(KArgs a, float scale, int gw, int NGW, int lane) {
;     ...
;     for (int it = (gw % NWAVES) * (NGW / NWAVES) + gw / NWAVES; it < MSAMP * 8; it += NGW) {
;         const int rl = it >> 3, pn = it & 7, col = pn * 256 + lane * 4;
;         f32x4 p[NSL];
; #pragma unroll
;         for (int s2 = 0; s2 < NSL; ++s2) p[s2] = *(const f32x4*)(PS + ((size_t)s2 * 128 + rl) * DM + col);
;         const size_t off = (size_t)(MPROMPT + rl) * DM + col; f32x4 x = *(const f32x4*)(X + off); f32x4 s = p[0];
; #pragma unroll
;         for (int s2 = 1; s2 < NSL; ++s2) s = s + p[s2];
;         x = x + s * scale; *(f32x4*)(X + off) = x;
;         u32x2 w; w.x = cvtpk(x[0], x[1]); w.y = cvtpk(x[2], x[3]); *(u32x2*)(XB + off) = w;
;         float ss = (x[0] * x[0] + x[1] * x[1]) + (x[2] * x[2] + x[3] * x[3]);
;         ss += __shfl_xor(ss, 1); ss += __shfl_xor(ss, 2); ss += __shfl_xor(ss, 4); ss += __shfl_xor(ss, 8);
;         if ((lane & 15) == 0) SS[(size_t)(pn * 4 + (lane >> 4)) * MPAD + MPROMPT + rl] = ss;
;     }
.LBB0_1772:
	s_ashr_i32 s12, s2, 3
	s_ashr_i32 s13, s12, 31
	s_and_b32 s18, s2, 7
	s_lshl_b64 s[14:15], s[12:13], 13
	v_lshl_or_b32 v36, s18, 8, v2
	s_add_u32 s14, s16, s14
	s_addc_u32 s15, s17, s15
	v_lshlrev_b32_e32 v0, 2, v36
	v_lshl_add_u64 v[32:33], s[14:15], 0, v[0:1]
	v_add_co_u32_e32 v8, vcc, s45, v32
	s_waitcnt lgkmcnt(0)
	global_load_dwordx4 v[4:7], v0, s[14:15]
	v_addc_co_u32_e32 v9, vcc, 0, v33, vcc
	v_add_co_u32_e32 v12, vcc, s39, v32
	global_load_dwordx4 v[8:11], v[8:9], off
	s_nop 0
	v_addc_co_u32_e32 v13, vcc, 0, v33, vcc
	v_add_co_u32_e32 v16, vcc, s47, v32
	global_load_dwordx4 v[12:15], v[12:13], off
	s_nop 0
	v_addc_co_u32_e32 v17, vcc, 0, v33, vcc
	v_add_co_u32_e32 v20, vcc, s77, v32
	global_load_dwordx4 v[16:19], v[16:17], off
	s_nop 0
	v_addc_co_u32_e32 v21, vcc, 0, v33, vcc
	v_add_co_u32_e32 v24, vcc, s37, v32
	s_lshl_b64 s[14:15], s[12:13], 11
	s_nop 0
	v_addc_co_u32_e32 v25, vcc, 0, v33, vcc
	v_add_co_u32_e32 v28, vcc, s74, v32
	global_load_dwordx4 v[20:23], v[20:21], off
	s_nop 0
	v_addc_co_u32_e32 v29, vcc, 0, v33, vcc
	s_add_u32 s14, s14, 0x1000000
	global_load_dwordx4 v[24:27], v[24:25], off
	v_add_co_u32_e32 v32, vcc, s66, v32
	s_addc_u32 s15, s15, 0
	global_load_dwordx4 v[28:31], v[28:29], off
	v_addc_co_u32_e32 v33, vcc, 0, v33, vcc
	v_or_b32_e32 v40, s14, v36
	v_mov_b32_e32 v41, s15
	global_load_dwordx4 v[32:35], v[32:33], off
	v_lshl_add_u64 v[42:43], v[40:41], 2, s[10:11]
	global_load_dwordx4 v[36:39], v[42:43], off
	s_waitcnt vmcnt(7)
	v_pk_add_f32 v[4:5], v[4:5], v[8:9]
	v_pk_add_f32 v[6:7], v[6:7], v[10:11]
	v_lshl_add_u64 v[10:11], v[40:41], 1, s[8:9]
	s_waitcnt vmcnt(6)
	v_pk_add_f32 v[4:5], v[4:5], v[12:13]
	v_pk_add_f32 v[6:7], v[6:7], v[14:15]
	s_waitcnt vmcnt(5)
	v_pk_add_f32 v[4:5], v[4:5], v[16:17]
	v_pk_add_f32 v[6:7], v[6:7], v[18:19]
	s_waitcnt vmcnt(4)
	v_pk_add_f32 v[4:5], v[4:5], v[20:21]
	v_pk_add_f32 v[6:7], v[6:7], v[22:23]
	s_waitcnt vmcnt(3)
	v_pk_add_f32 v[4:5], v[4:5], v[24:25]
	v_pk_add_f32 v[6:7], v[6:7], v[26:27]
	s_waitcnt vmcnt(2)
	v_pk_add_f32 v[4:5], v[4:5], v[28:29]
	v_pk_add_f32 v[6:7], v[6:7], v[30:31]
	s_waitcnt vmcnt(1)
	v_pk_add_f32 v[4:5], v[4:5], v[32:33]
	v_pk_add_f32 v[6:7], v[6:7], v[34:35]
	s_waitcnt vmcnt(0)
	v_pk_add_f32 v[4:5], v[36:37], v[4:5]
	v_pk_add_f32 v[6:7], v[38:39], v[6:7]
	v_mul_f32_e32 v0, v5, v5
	global_store_dwordx4 v[42:43], v[4:7], off
	v_cvt_pk_bf16_f32 v8, v4, v5
	v_fmac_f32_e32 v0, v4, v4
	v_cvt_pk_bf16_f32 v9, v6, v7
	global_store_dwordx2 v[10:11], v[8:9], off
	v_mul_f32_e32 v4, v7, v7
	v_fmac_f32_e32 v4, v6, v6
	v_and_b32_e32 v5, 64, v219
	v_add_f32_e32 v0, v0, v4
	v_xor_b32_e32 v4, 1, v219
	v_add_u32_e32 v5, 64, v5
	v_cmp_lt_i32_e32 vcc, v4, v5
	s_nop 1
	v_cndmask_b32_e32 v4, v219, v4, vcc
	v_lshlrev_b32_e32 v4, 2, v4
	s_nop 1
	v_add_f32_dpp v4, v0, v0 quad_perm:[1,0,3,2] row_mask:0xf bank_mask:0xf
	s_waitcnt lgkmcnt(0)
	v_mov_b32_e32 v0, v4
	v_xor_b32_e32 v4, 2, v219
	v_cmp_lt_i32_e32 vcc, v4, v5
	s_nop 1
	v_cndmask_b32_e32 v4, v219, v4, vcc
	v_lshlrev_b32_e32 v4, 2, v4
	s_nop 1
	v_add_f32_dpp v4, v0, v0 quad_perm:[2,3,0,1] row_mask:0xf bank_mask:0xf
	s_waitcnt lgkmcnt(0)
	v_mov_b32_e32 v0, v4
	v_xor_b32_e32 v4, 4, v219
	v_cmp_lt_i32_e32 vcc, v4, v5
	s_nop 1
	v_cndmask_b32_e32 v4, v219, v4, vcc
	v_lshlrev_b32_e32 v4, 2, v4
	s_nop 1
	v_add_f32_dpp v4, v0, v0 row_half_mirror row_mask:0xf bank_mask:0xf
	s_waitcnt lgkmcnt(0)
	v_mov_b32_e32 v0, v4
	v_xor_b32_e32 v4, 8, v219
	v_cmp_lt_i32_e32 vcc, v4, v5
	s_nop 1
	v_cndmask_b32_e32 v4, v219, v4, vcc
	v_lshlrev_b32_e32 v4, 2, v4
	s_nop 1
	v_add_f32_dpp v4, v0, v0 row_mirror row_mask:0xf bank_mask:0xf
	s_and_saveexec_b64 s[14:15], s[4:5]
	s_cbranch_execz .LBB0_1771
	s_waitcnt lgkmcnt(0)
	v_mov_b32_e32 v6, v4
	v_lshl_or_b32 v0, s18, 2, v3
	v_mul_u32_u24_e32 v0, 0x2100, v0
	v_lshlrev_b32_e32 v0, 2, v0
	v_lshl_add_u64 v[4:5], s[6:7], 0, v[0:1]
	v_lshl_add_u64 v[4:5], s[12:13], 2, v[4:5]
	v_add_co_u32_e32 v4, vcc, 0x8000, v4
	s_nop 1
	v_addc_co_u32_e32 v5, vcc, 0, v5, vcc
	global_store_dword v[4:5], v6, off
	s_branch .LBB0_1771

; __device__ __forceinline__ void rows_rstd(const float* SS, const Unit& u, int wr, int fr, int fq, float (&rs)[2][4]) {
;     if (u.pm < 32) { const float* RSTD = (const float*)((const char*)SS + SS_TO_RSTD);
; #pragma unroll
;         for (int ai = 0; ai < 2; ++ai)
; #pragma unroll
;             for (int m = 0; m < 4; ++m) rs[ai][m] = RSTD[u.pm * BM + ai * HALF + wr * 64 + m * 16 + fr];
;     } else {
; #pragma unroll
;         for (int ai = 0; ai < 2; ++ai)
; #pragma unroll
;             for (int m = 0; m < 4; ++m) {
;                 const int row = u.pm * BM + ai * HALF + wr * 64 + m * 16 + fr; float s = 0.f;
; #pragma unroll
;                 for (int j = 0; j < 8; ++j) s += SS[(size_t)(fq * 8 + j) * MPAD + row];
;                 s += __shfl_xor(s, 16); s += __shfl_xor(s, 32);
;                 rs[ai][m] = 1.0f / sqrtf(s * (1.0f / 2048.0f) + RMS_EPS);
.LBB0_1852:
	s_lshl_b32 s6, s76, 8
	v_mov_b32_e32 v140, v159
	v_mov_b32_e32 v141, v161
	s_add_i32 s6, s6, s71
	s_cmp_lt_i32 s76, 32
	v_add_u32_e32 v156, s6, v141
	v_lshlrev_b32_e32 v154, 3, v140
	v_add_u32_e32 v152, 16, v156
	v_add_u32_e32 v150, 32, v156
	v_add_u32_e32 v148, 48, v156
	v_add_u32_e32 v146, 0x80, v156
	v_add_u32_e32 v144, 0x90, v156
	v_add_u32_e32 v142, 0xa0, v156
	s_mov_b64 s[6:7], -1
	v_ashrrev_i32_e32 v157, 31, v156
	v_ashrrev_i32_e32 v155, 31, v154
	v_ashrrev_i32_e32 v153, 31, v152
	v_ashrrev_i32_e32 v151, 31, v150
	v_ashrrev_i32_e32 v149, 31, v148
	v_ashrrev_i32_e32 v147, 31, v146
	v_ashrrev_i32_e32 v145, 31, v144
	v_ashrrev_i32_e32 v143, 31, v142
	v_add_u32_e32 v140, 0xb0, v156
	s_cbranch_scc1 .LBB0_1854
	v_and_b32_e32 v158, 64, v219
	v_xor_b32_e32 v141, 16, v219
	v_add_u32_e32 v158, 64, v158
	v_cmp_lt_i32_e32 vcc, v141, v158
	v_lshl_add_u64 v[194:195], v[156:157], 2, s[14:15]
	v_mad_i64_i32 v[170:171], s[6:7], v154, s46, v[194:195]
	v_cndmask_b32_e32 v141, v219, v141, vcc
	v_lshlrev_b32_e32 v169, 2, v141
	v_xor_b32_e32 v141, 32, v219
	v_cmp_lt_i32_e32 vcc, v141, v158
	s_nop 1
	v_cndmask_b32_e32 v141, v219, v141, vcc
	v_lshlrev_b32_e32 v167, 2, v141
	global_load_dword v208, v[170:171], off
	v_or_b32_e32 v171, 1, v154
	v_mad_i64_i32 v[172:173], s[6:7], v171, s46, v[194:195]
	global_load_dword v209, v[172:173], off
	v_or_b32_e32 v172, 2, v154
	v_mad_i64_i32 v[174:175], s[6:7], v172, s46, v[194:195]
	v_or_b32_e32 v173, 3, v154
	global_load_dword v210, v[174:175], off
	v_mad_i64_i32 v[174:175], s[6:7], v173, s46, v[194:195]
	global_load_dword v211, v[174:175], off
	v_or_b32_e32 v174, 4, v154
	v_mad_i64_i32 v[176:177], s[6:7], v174, s46, v[194:195]
	v_or_b32_e32 v175, 5, v154
	global_load_dword v212, v[176:177], off
	v_mad_i64_i32 v[176:177], s[6:7], v175, s46, v[194:195]
	global_load_dword v213, v[176:177], off
	v_or_b32_e32 v176, 6, v154
	v_mad_i64_i32 v[196:197], s[6:7], v176, s46, v[194:195]
	v_or_b32_e32 v177, 7, v154
	v_mad_i64_i32 v[194:195], s[6:7], v177, s46, v[194:195]
	global_load_dword v214, v[196:197], off
	global_load_dword v215, v[194:195], off
	v_lshl_add_u64 v[194:195], v[152:153], 2, s[14:15]
	s_waitcnt vmcnt(0)
	v_add_f32_e32 v141, 0, v208
	v_add_f32_e32 v141, v141, v209
	v_add_f32_e32 v141, v141, v210
	v_add_f32_e32 v141, v141, v211
	v_add_f32_e32 v141, v141, v212
	v_add_f32_e32 v141, v141, v213
	v_add_f32_e32 v141, v141, v214
	v_add_f32_e32 v141, v141, v215
	v_mov_b32_e32 v158, v141
	v_mov_b32_e32 v216, v141
	s_nop 1
	v_permlane16_swap_b32_e32 v158, v216
	s_waitcnt lgkmcnt(0)
	v_add_f32_e32 v141, v158, v216
	v_mov_b32_e32 v158, v141
	v_mov_b32_e32 v216, v141
	s_nop 1
	v_permlane32_swap_b32_e32 v158, v216
	s_waitcnt lgkmcnt(0)
	v_add_f32_e32 v141, v158, v216
	v_fmamk_f32 v141, v141, 0x3a000000, v220
	v_cmp_gt_f32_e32 vcc, s43, v141
	v_mul_f32_e32 v158, 0x4f800000, v141
	s_nop 0
	v_cndmask_b32_e32 v141, v141, v158, vcc
	v_sqrt_f32_e32 v158, v141
	s_nop 0
	v_add_u32_e32 v160, -1, v158
	v_fma_f32 v162, -v160, v158, v141
	v_cmp_ge_f32_e64 s[6:7], 0, v162
	v_add_u32_e32 v162, 1, v158
	s_nop 0
	v_cndmask_b32_e64 v160, v158, v160, s[6:7]
	v_fma_f32 v158, -v162, v158, v141
	v_cmp_lt_f32_e64 s[6:7], 0, v158
	s_nop 1
	v_cndmask_b32_e64 v158, v160, v162, s[6:7]
	v_mul_f32_e32 v160, 0x37800000, v158
	v_cndmask_b32_e32 v158, v158, v160, vcc
	v_cmp_class_f32_e32 vcc, v141, v221
	v_mad_i64_i32 v[196:197], s[6:7], v154, s46, v[194:195]
	s_nop 0
	v_cndmask_b32_e32 v141, v158, v141, vcc
	v_div_scale_f32 v158, s[6:7], v141, v141, 1.0
	v_rcp_f32_e32 v160, v158
	s_nop 0
	v_fma_f32 v162, -v158, v160, 1.0
	v_fmac_f32_e32 v160, v162, v160
	v_div_scale_f32 v162, vcc, 1.0, v141, 1.0
	v_mul_f32_e32 v164, v162, v160
	v_fma_f32 v166, -v158, v164, v162
	v_fmac_f32_e32 v164, v166, v160
	v_fma_f32 v158, -v158, v164, v162
	v_div_fmas_f32 v158, v158, v160, v164
	v_div_fixup_f32 v158, v158, v141, 1.0
	global_load_dword v208, v[196:197], off
	v_mad_i64_i32 v[196:197], s[6:7], v171, s46, v[194:195]
	global_load_dword v209, v[196:197], off
	v_mad_i64_i32 v[196:197], s[6:7], v172, s46, v[194:195]
	global_load_dword v210, v[196:197], off
	v_mad_i64_i32 v[196:197], s[6:7], v173, s46, v[194:195]
	global_load_dword v211, v[196:197], off
	v_mad_i64_i32 v[196:197], s[6:7], v174, s46, v[194:195]
	global_load_dword v212, v[196:197], off
	v_mad_i64_i32 v[196:197], s[6:7], v175, s46, v[194:195]
	global_load_dword v213, v[196:197], off
	v_mad_i64_i32 v[196:197], s[6:7], v176, s46, v[194:195]
	v_mad_i64_i32 v[194:195], s[6:7], v177, s46, v[194:195]
	global_load_dword v214, v[196:197], off
	global_load_dword v215, v[194:195], off
	v_lshl_add_u64 v[194:195], v[150:151], 2, s[14:15]
	s_waitcnt vmcnt(0)
	v_add_f32_e32 v141, 0, v208
	v_add_f32_e32 v141, v141, v209
	v_add_f32_e32 v141, v141, v210
	v_add_f32_e32 v141, v141, v211
	v_add_f32_e32 v141, v141, v212
	v_add_f32_e32 v141, v141, v213
	v_add_f32_e32 v141, v141, v214
	v_add_f32_e32 v141, v141, v215
	v_mov_b32_e32 v160, v141
	v_mov_b32_e32 v216, v141
	s_nop 1
	v_permlane16_swap_b32_e32 v160, v216
	s_waitcnt lgkmcnt(0)
	v_add_f32_e32 v141, v160, v216
	v_mov_b32_e32 v160, v141
	v_mov_b32_e32 v216, v141
	s_nop 1
	v_permlane32_swap_b32_e32 v160, v216
	s_waitcnt lgkmcnt(0)
; __device__ __forceinline__ void rows_rstd(const float* SS, const Unit& u, int wr, int fr, int fq, float (&rs)[2][4]) {
;     ...
;                 const int row = u.pm * BM + ai * HALF + wr * 64 + m * 16 + fr; float s = 0.f;
; #pragma unroll
;                 for (int j = 0; j < 8; ++j) s += SS[(size_t)(fq * 8 + j) * MPAD + row];
;                 s += __shfl_xor(s, 16); s += __shfl_xor(s, 32);
;                 rs[ai][m] = 1.0f / sqrtf(s * (1.0f / 2048.0f) + RMS_EPS);
	v_add_f32_e32 v141, v160, v216
	v_fmamk_f32 v141, v141, 0x3a000000, v220
	v_cmp_gt_f32_e32 vcc, s43, v141
	v_mul_f32_e32 v160, 0x4f800000, v141
	s_nop 0
	v_cndmask_b32_e32 v141, v141, v160, vcc
	v_sqrt_f32_e32 v160, v141
	s_nop 0
	v_add_u32_e32 v162, -1, v160
	v_fma_f32 v164, -v162, v160, v141
	v_cmp_ge_f32_e64 s[6:7], 0, v164
	v_add_u32_e32 v164, 1, v160
	s_nop 0
	v_cndmask_b32_e64 v162, v160, v162, s[6:7]
	v_fma_f32 v160, -v164, v160, v141
	v_cmp_lt_f32_e64 s[6:7], 0, v160
	s_nop 1
	v_cndmask_b32_e64 v160, v162, v164, s[6:7]
	v_mul_f32_e32 v162, 0x37800000, v160
	v_cndmask_b32_e32 v160, v160, v162, vcc
	v_cmp_class_f32_e32 vcc, v141, v221
	v_mad_i64_i32 v[196:197], s[6:7], v154, s46, v[194:195]
	s_nop 0
	v_cndmask_b32_e32 v141, v160, v141, vcc
	v_div_scale_f32 v160, s[6:7], v141, v141, 1.0
	v_rcp_f32_e32 v162, v160
	s_nop 0
	v_fma_f32 v164, -v160, v162, 1.0
	v_fmac_f32_e32 v162, v164, v162
	v_div_scale_f32 v164, vcc, 1.0, v141, 1.0
	v_mul_f32_e32 v166, v164, v162
	v_fma_f32 v168, -v160, v166, v164
	v_fmac_f32_e32 v166, v168, v162
	v_fma_f32 v160, -v160, v166, v164
	v_div_fmas_f32 v160, v160, v162, v166
	v_div_fixup_f32 v160, v160, v141, 1.0
	global_load_dword v208, v[196:197], off
	v_mad_i64_i32 v[196:197], s[6:7], v171, s46, v[194:195]
	global_load_dword v209, v[196:197], off
	v_mad_i64_i32 v[196:197], s[6:7], v172, s46, v[194:195]
	global_load_dword v210, v[196:197], off
	v_mad_i64_i32 v[196:197], s[6:7], v173, s46, v[194:195]
	global_load_dword v211, v[196:197], off
	v_mad_i64_i32 v[196:197], s[6:7], v174, s46, v[194:195]
	global_load_dword v212, v[196:197], off
	v_mad_i64_i32 v[196:197], s[6:7], v175, s46, v[194:195]
	global_load_dword v213, v[196:197], off
	v_mad_i64_i32 v[196:197], s[6:7], v176, s46, v[194:195]
	v_mad_i64_i32 v[194:195], s[6:7], v177, s46, v[194:195]
	global_load_dword v214, v[196:197], off
	global_load_dword v215, v[194:195], off
	v_lshl_add_u64 v[194:195], v[148:149], 2, s[14:15]
	s_waitcnt vmcnt(0)
	v_add_f32_e32 v141, 0, v208
	v_add_f32_e32 v141, v141, v209
	v_add_f32_e32 v141, v141, v210
	v_add_f32_e32 v141, v141, v211
	v_add_f32_e32 v141, v141, v212
	v_add_f32_e32 v141, v141, v213
	v_add_f32_e32 v141, v141, v214
	v_add_f32_e32 v141, v141, v215
	v_mov_b32_e32 v162, v141
	v_mov_b32_e32 v216, v141
	s_nop 1
	v_permlane16_swap_b32_e32 v162, v216
	s_waitcnt lgkmcnt(0)
	v_add_f32_e32 v141, v162, v216
	v_mov_b32_e32 v162, v141
	v_mov_b32_e32 v216, v141
	s_nop 1
	v_permlane32_swap_b32_e32 v162, v216
	s_waitcnt lgkmcnt(0)
	v_add_f32_e32 v141, v162, v216
	v_fmamk_f32 v141, v141, 0x3a000000, v220
	v_cmp_gt_f32_e32 vcc, s43, v141
	v_mul_f32_e32 v162, 0x4f800000, v141
	s_nop 0
	v_cndmask_b32_e32 v141, v141, v162, vcc
	v_sqrt_f32_e32 v162, v141
	s_nop 0
	v_add_u32_e32 v164, -1, v162
	v_fma_f32 v166, -v164, v162, v141
	v_cmp_ge_f32_e64 s[6:7], 0, v166
	v_add_u32_e32 v166, 1, v162
	s_nop 0
	v_cndmask_b32_e64 v164, v162, v164, s[6:7]
	v_fma_f32 v162, -v166, v162, v141
	v_cmp_lt_f32_e64 s[6:7], 0, v162
	s_nop 1
	v_cndmask_b32_e64 v162, v164, v166, s[6:7]
	v_mul_f32_e32 v164, 0x37800000, v162
	v_cndmask_b32_e32 v162, v162, v164, vcc
	v_cmp_class_f32_e32 vcc, v141, v221
	v_mad_i64_i32 v[196:197], s[6:7], v154, s46, v[194:195]
	s_nop 0
	v_cndmask_b32_e32 v141, v162, v141, vcc
	v_div_scale_f32 v162, s[6:7], v141, v141, 1.0
	v_rcp_f32_e32 v164, v162
	s_nop 0
	v_fma_f32 v166, -v162, v164, 1.0
	v_fmac_f32_e32 v164, v166, v164
	v_div_scale_f32 v166, vcc, 1.0, v141, 1.0
	v_mul_f32_e32 v168, v166, v164
	v_fma_f32 v170, -v162, v168, v166
	v_fmac_f32_e32 v168, v170, v164
	v_fma_f32 v162, -v162, v168, v166
	v_div_fmas_f32 v162, v162, v164, v168
	v_div_fixup_f32 v162, v162, v141, 1.0
	global_load_dword v208, v[196:197], off
	v_mad_i64_i32 v[196:197], s[6:7], v171, s46, v[194:195]
	global_load_dword v209, v[196:197], off
	v_mad_i64_i32 v[196:197], s[6:7], v172, s46, v[194:195]
	global_load_dword v210, v[196:197], off
	v_mad_i64_i32 v[196:197], s[6:7], v173, s46, v[194:195]
	global_load_dword v211, v[196:197], off
	v_mad_i64_i32 v[196:197], s[6:7], v174, s46, v[194:195]
	global_load_dword v212, v[196:197], off
	v_mad_i64_i32 v[196:197], s[6:7], v175, s46, v[194:195]
	global_load_dword v213, v[196:197], off
	v_mad_i64_i32 v[196:197], s[6:7], v176, s46, v[194:195]
	v_mad_i64_i32 v[194:195], s[6:7], v177, s46, v[194:195]
	global_load_dword v214, v[196:197], off
	global_load_dword v215, v[194:195], off
	v_lshl_add_u64 v[194:195], v[146:147], 2, s[14:15]
	s_waitcnt vmcnt(0)
	v_add_f32_e32 v141, 0, v208
	v_add_f32_e32 v141, v141, v209
	v_add_f32_e32 v141, v141, v210
	v_add_f32_e32 v141, v141, v211
	v_add_f32_e32 v141, v141, v212
	v_add_f32_e32 v141, v141, v213
	v_add_f32_e32 v141, v141, v214
	v_add_f32_e32 v141, v141, v215
	v_mov_b32_e32 v164, v141
	v_mov_b32_e32 v216, v141
	s_nop 1
	v_permlane16_swap_b32_e32 v164, v216
	s_waitcnt lgkmcnt(0)
	v_add_f32_e32 v141, v164, v216
	v_mov_b32_e32 v164, v141
	v_mov_b32_e32 v216, v141
	s_nop 1
	v_permlane32_swap_b32_e32 v164, v216
	s_waitcnt lgkmcnt(0)
; __device__ __forceinline__ void rows_rstd(const float* SS, const Unit& u, int wr, int fr, int fq, float (&rs)[2][4]) {
;     ...
;                 const int row = u.pm * BM + ai * HALF + wr * 64 + m * 16 + fr; float s = 0.f;
; #pragma unroll
;                 for (int j = 0; j < 8; ++j) s += SS[(size_t)(fq * 8 + j) * MPAD + row];
;                 s += __shfl_xor(s, 16); s += __shfl_xor(s, 32);
;                 rs[ai][m] = 1.0f / sqrtf(s * (1.0f / 2048.0f) + RMS_EPS);
	v_add_f32_e32 v141, v164, v216
	v_fmamk_f32 v141, v141, 0x3a000000, v220
	v_cmp_gt_f32_e32 vcc, s43, v141
	v_mul_f32_e32 v164, 0x4f800000, v141
	s_nop 0
	v_cndmask_b32_e32 v141, v141, v164, vcc
	v_sqrt_f32_e32 v164, v141
	s_nop 0
	v_add_u32_e32 v166, -1, v164
	v_fma_f32 v168, -v166, v164, v141
	v_cmp_ge_f32_e64 s[6:7], 0, v168
	v_add_u32_e32 v168, 1, v164
	s_nop 0
	v_cndmask_b32_e64 v166, v164, v166, s[6:7]
	v_fma_f32 v164, -v168, v164, v141
	v_cmp_lt_f32_e64 s[6:7], 0, v164
	s_nop 1
	v_cndmask_b32_e64 v164, v166, v168, s[6:7]
	v_mul_f32_e32 v166, 0x37800000, v164
	v_cndmask_b32_e32 v164, v164, v166, vcc
	v_cmp_class_f32_e32 vcc, v141, v221
	v_mad_i64_i32 v[196:197], s[6:7], v154, s46, v[194:195]
	s_nop 0
	v_cndmask_b32_e32 v141, v164, v141, vcc
	v_div_scale_f32 v164, s[6:7], v141, v141, 1.0
	v_rcp_f32_e32 v166, v164
	s_nop 0
	v_fma_f32 v168, -v164, v166, 1.0
	v_fmac_f32_e32 v166, v168, v166
	v_div_scale_f32 v168, vcc, 1.0, v141, 1.0
	v_mul_f32_e32 v170, v168, v166
	v_fma_f32 v189, -v164, v170, v168
	v_fmac_f32_e32 v170, v189, v166
	v_fma_f32 v164, -v164, v170, v168
	v_div_fmas_f32 v164, v164, v166, v170
	v_div_fixup_f32 v164, v164, v141, 1.0
	global_load_dword v208, v[196:197], off
	v_mad_i64_i32 v[196:197], s[6:7], v171, s46, v[194:195]
	global_load_dword v209, v[196:197], off
	v_mad_i64_i32 v[196:197], s[6:7], v172, s46, v[194:195]
	global_load_dword v210, v[196:197], off
	v_mad_i64_i32 v[196:197], s[6:7], v173, s46, v[194:195]
	global_load_dword v211, v[196:197], off
	v_mad_i64_i32 v[196:197], s[6:7], v174, s46, v[194:195]
	global_load_dword v212, v[196:197], off
	v_mad_i64_i32 v[196:197], s[6:7], v175, s46, v[194:195]
	global_load_dword v213, v[196:197], off
	v_mad_i64_i32 v[196:197], s[6:7], v176, s46, v[194:195]
	v_mad_i64_i32 v[194:195], s[6:7], v177, s46, v[194:195]
	global_load_dword v214, v[196:197], off
	global_load_dword v215, v[194:195], off
	s_waitcnt vmcnt(0)
	v_add_f32_e32 v141, 0, v208
	v_add_f32_e32 v141, v141, v209
	v_add_f32_e32 v141, v141, v210
	v_add_f32_e32 v141, v141, v211
	v_add_f32_e32 v141, v141, v212
	v_add_f32_e32 v141, v141, v213
	v_add_f32_e32 v141, v141, v214
	v_add_f32_e32 v141, v141, v215
	v_mov_b32_e32 v166, v141
	v_mov_b32_e32 v216, v141
	s_nop 1
	v_permlane16_swap_b32_e32 v166, v216
	s_waitcnt lgkmcnt(0)
	v_add_f32_e32 v141, v166, v216
	v_mov_b32_e32 v166, v141
	v_mov_b32_e32 v216, v141
	s_nop 1
	v_permlane32_swap_b32_e32 v166, v216
	s_waitcnt lgkmcnt(0)
	v_add_f32_e32 v141, v166, v216
	v_fmamk_f32 v141, v141, 0x3a000000, v220
	v_cmp_gt_f32_e32 vcc, s43, v141
	v_mul_f32_e32 v166, 0x4f800000, v141
	s_nop 0
	v_cndmask_b32_e32 v141, v141, v166, vcc
	v_sqrt_f32_e32 v166, v141
	s_nop 0
	v_add_u32_e32 v168, -1, v166
	v_fma_f32 v170, -v168, v166, v141
	v_cmp_ge_f32_e64 s[6:7], 0, v170
	v_add_u32_e32 v170, 1, v166
	s_nop 0
	v_cndmask_b32_e64 v168, v166, v168, s[6:7]
	v_fma_f32 v166, -v170, v166, v141
	v_cmp_lt_f32_e64 s[6:7], 0, v166
	s_nop 1
	v_cndmask_b32_e64 v166, v168, v170, s[6:7]
	v_mul_f32_e32 v168, 0x37800000, v166
	v_cndmask_b32_e32 v166, v166, v168, vcc
	v_cmp_class_f32_e32 vcc, v141, v221
	s_nop 1
	v_cndmask_b32_e32 v141, v166, v141, vcc
	v_div_scale_f32 v166, s[6:7], v141, v141, 1.0
	v_rcp_f32_e32 v168, v166
	s_nop 0
	v_fma_f32 v170, -v166, v168, 1.0
	v_fmac_f32_e32 v168, v170, v168
	v_div_scale_f32 v170, vcc, 1.0, v141, 1.0
	v_mul_f32_e32 v189, v170, v168
	v_fma_f32 v194, -v166, v189, v170
	v_fmac_f32_e32 v189, v194, v168
	v_fma_f32 v166, -v166, v189, v170
	v_lshl_add_u64 v[194:195], v[144:145], 2, s[14:15]
	v_div_fmas_f32 v166, v166, v168, v189
	v_mad_i64_i32 v[196:197], s[6:7], v154, s46, v[194:195]
	v_div_fixup_f32 v166, v166, v141, 1.0
	global_load_dword v208, v[196:197], off
	v_mad_i64_i32 v[196:197], s[6:7], v171, s46, v[194:195]
	global_load_dword v209, v[196:197], off
	v_mad_i64_i32 v[196:197], s[6:7], v172, s46, v[194:195]
	global_load_dword v210, v[196:197], off
	v_mad_i64_i32 v[196:197], s[6:7], v173, s46, v[194:195]
	global_load_dword v211, v[196:197], off
	v_mad_i64_i32 v[196:197], s[6:7], v174, s46, v[194:195]
	global_load_dword v212, v[196:197], off
	v_mad_i64_i32 v[196:197], s[6:7], v175, s46, v[194:195]
	global_load_dword v213, v[196:197], off
	v_mad_i64_i32 v[196:197], s[6:7], v176, s46, v[194:195]
	v_mad_i64_i32 v[194:195], s[6:7], v177, s46, v[194:195]
	global_load_dword v214, v[196:197], off
	global_load_dword v215, v[194:195], off
	s_waitcnt vmcnt(0)
	v_add_f32_e32 v141, 0, v208
	v_add_f32_e32 v141, v141, v209
	v_add_f32_e32 v141, v141, v210
	v_add_f32_e32 v141, v141, v211
	v_add_f32_e32 v141, v141, v212
	v_add_f32_e32 v141, v141, v213
	v_add_f32_e32 v141, v141, v214
	v_add_f32_e32 v141, v141, v215
	v_mov_b32_e32 v168, v141
	v_mov_b32_e32 v216, v141
	s_nop 1
	v_permlane16_swap_b32_e32 v168, v216
	s_waitcnt lgkmcnt(0)
	v_add_f32_e32 v141, v168, v216
	v_mov_b32_e32 v168, v141
	v_mov_b32_e32 v216, v141
	s_nop 1
	v_permlane32_swap_b32_e32 v168, v216
	s_waitcnt lgkmcnt(0)
; __device__ __forceinline__ void rows_rstd(const float* SS, const Unit& u, int wr, int fr, int fq, float (&rs)[2][4]) {
;     ...
;                 const int row = u.pm * BM + ai * HALF + wr * 64 + m * 16 + fr; float s = 0.f;
; #pragma unroll
;                 for (int j = 0; j < 8; ++j) s += SS[(size_t)(fq * 8 + j) * MPAD + row];
;                 s += __shfl_xor(s, 16); s += __shfl_xor(s, 32);
;                 rs[ai][m] = 1.0f / sqrtf(s * (1.0f / 2048.0f) + RMS_EPS);
	v_add_f32_e32 v141, v168, v216
	v_fmamk_f32 v141, v141, 0x3a000000, v220
	v_cmp_gt_f32_e32 vcc, s43, v141
	v_mul_f32_e32 v168, 0x4f800000, v141
	s_nop 0
	v_cndmask_b32_e32 v141, v141, v168, vcc
	v_sqrt_f32_e32 v168, v141
	s_nop 0
	v_add_u32_e32 v170, -1, v168
	v_fma_f32 v189, -v170, v168, v141
	v_cmp_ge_f32_e64 s[6:7], 0, v189
	v_add_u32_e32 v189, 1, v168
	s_nop 0
	v_cndmask_b32_e64 v170, v168, v170, s[6:7]
	v_fma_f32 v168, -v189, v168, v141
	v_cmp_lt_f32_e64 s[6:7], 0, v168
	s_nop 1
	v_cndmask_b32_e64 v168, v170, v189, s[6:7]
	v_mul_f32_e32 v170, 0x37800000, v168
	v_cndmask_b32_e32 v168, v168, v170, vcc
	v_cmp_class_f32_e32 vcc, v141, v221
	s_nop 1
	v_cndmask_b32_e32 v141, v168, v141, vcc
	v_div_scale_f32 v168, s[6:7], v141, v141, 1.0
	v_rcp_f32_e32 v170, v168
	s_nop 0
	v_fma_f32 v189, -v168, v170, 1.0
	v_fmac_f32_e32 v170, v189, v170
	v_div_scale_f32 v189, vcc, 1.0, v141, 1.0
	v_mul_f32_e32 v194, v189, v170
	v_fma_f32 v195, -v168, v194, v189
	v_fmac_f32_e32 v194, v195, v170
	v_fma_f32 v168, -v168, v194, v189
	v_div_fmas_f32 v168, v168, v170, v194
	v_lshl_add_u64 v[194:195], v[142:143], 2, s[14:15]
	v_mad_i64_i32 v[196:197], s[6:7], v154, s46, v[194:195]
	v_div_fixup_f32 v168, v168, v141, 1.0
	global_load_dword v208, v[196:197], off
	v_mad_i64_i32 v[196:197], s[6:7], v171, s46, v[194:195]
	global_load_dword v209, v[196:197], off
	v_mad_i64_i32 v[196:197], s[6:7], v172, s46, v[194:195]
	global_load_dword v210, v[196:197], off
	v_mad_i64_i32 v[196:197], s[6:7], v173, s46, v[194:195]
	global_load_dword v211, v[196:197], off
	v_mad_i64_i32 v[196:197], s[6:7], v174, s46, v[194:195]
	global_load_dword v212, v[196:197], off
	v_mad_i64_i32 v[196:197], s[6:7], v175, s46, v[194:195]
	global_load_dword v213, v[196:197], off
	v_mad_i64_i32 v[196:197], s[6:7], v176, s46, v[194:195]
	v_mad_i64_i32 v[194:195], s[6:7], v177, s46, v[194:195]
	global_load_dword v214, v[196:197], off
	global_load_dword v215, v[194:195], off
	s_waitcnt vmcnt(0)
	v_add_f32_e32 v141, 0, v208
	v_add_f32_e32 v141, v141, v209
	v_add_f32_e32 v141, v141, v210
	v_add_f32_e32 v141, v141, v211
	v_add_f32_e32 v141, v141, v212
	v_add_f32_e32 v141, v141, v213
	v_add_f32_e32 v141, v141, v214
	v_add_f32_e32 v141, v141, v215
	v_mov_b32_e32 v170, v141
	v_mov_b32_e32 v216, v141
	s_nop 1
	v_permlane16_swap_b32_e32 v170, v216
	s_waitcnt lgkmcnt(0)
	v_add_f32_e32 v141, v170, v216
	v_mov_b32_e32 v170, v141
	v_mov_b32_e32 v216, v141
	s_nop 1
	v_permlane32_swap_b32_e32 v170, v216
	s_waitcnt lgkmcnt(0)
	v_add_f32_e32 v141, v170, v216
	v_fmamk_f32 v141, v141, 0x3a000000, v220
	v_cmp_gt_f32_e32 vcc, s43, v141
	v_mul_f32_e32 v170, 0x4f800000, v141
	s_nop 0
	v_cndmask_b32_e32 v141, v141, v170, vcc
	v_sqrt_f32_e32 v170, v141
	s_nop 0
	v_add_u32_e32 v189, -1, v170
	v_fma_f32 v194, -v189, v170, v141
	v_cmp_ge_f32_e64 s[6:7], 0, v194
	v_add_u32_e32 v194, 1, v170
	s_nop 0
	v_cndmask_b32_e64 v189, v170, v189, s[6:7]
	v_fma_f32 v170, -v194, v170, v141
	v_cmp_lt_f32_e64 s[6:7], 0, v170
	s_nop 1
	v_cndmask_b32_e64 v170, v189, v194, s[6:7]
	v_mul_f32_e32 v189, 0x37800000, v170
	v_cndmask_b32_e32 v170, v170, v189, vcc
	v_cmp_class_f32_e32 vcc, v141, v221
	s_nop 1
	v_cndmask_b32_e32 v141, v170, v141, vcc
	v_div_scale_f32 v170, s[6:7], v141, v141, 1.0
	v_rcp_f32_e32 v189, v170
	s_nop 0
	v_fma_f32 v194, -v170, v189, 1.0
	v_fmac_f32_e32 v189, v194, v189
	v_div_scale_f32 v194, vcc, 1.0, v141, 1.0
	v_mul_f32_e32 v195, v194, v189
	v_fma_f32 v196, -v170, v195, v194
	v_fmac_f32_e32 v195, v196, v189
	v_fma_f32 v170, -v170, v195, v194
	v_div_fmas_f32 v170, v170, v189, v195
	v_div_fixup_f32 v170, v170, v141, 1.0
	v_ashrrev_i32_e32 v141, 31, v140
	v_lshl_add_u64 v[194:195], v[140:141], 2, s[14:15]
	v_mad_i64_i32 v[196:197], s[6:7], v154, s46, v[194:195]
	global_load_dword v208, v[196:197], off
	v_mad_i64_i32 v[196:197], s[6:7], v171, s46, v[194:195]
	global_load_dword v209, v[196:197], off
	v_mad_i64_i32 v[196:197], s[6:7], v172, s46, v[194:195]
	global_load_dword v210, v[196:197], off
	v_mad_i64_i32 v[172:173], s[6:7], v173, s46, v[194:195]
	global_load_dword v211, v[172:173], off
	v_mad_i64_i32 v[172:173], s[6:7], v174, s46, v[194:195]
	global_load_dword v212, v[172:173], off
	v_mad_i64_i32 v[172:173], s[6:7], v175, s46, v[194:195]
	global_load_dword v213, v[172:173], off
	v_mad_i64_i32 v[172:173], s[6:7], v176, s46, v[194:195]
	global_load_dword v214, v[172:173], off
	v_mad_i64_i32 v[172:173], s[6:7], v177, s46, v[194:195]
	global_load_dword v215, v[172:173], off
	s_waitcnt vmcnt(0)
	v_add_f32_e32 v189, 0, v208
	v_add_f32_e32 v171, v189, v209
	v_add_f32_e32 v171, v171, v210
	v_add_f32_e32 v171, v171, v211
	v_add_f32_e32 v171, v171, v212
	v_add_f32_e32 v171, v171, v213
	v_add_f32_e32 v171, v171, v214
	v_add_f32_e32 v171, v171, v215
	v_mov_b32_e32 v169, v171
	v_mov_b32_e32 v216, v171
	s_nop 1
	v_permlane16_swap_b32_e32 v169, v216
	s_waitcnt lgkmcnt(0)
	v_add_f32_e32 v169, v169, v216
	v_mov_b32_e32 v167, v169
	v_mov_b32_e32 v216, v169
	s_nop 1
	v_permlane32_swap_b32_e32 v167, v216
	s_waitcnt lgkmcnt(0)
	v_add_f32_e32 v167, v167, v216
	v_fmamk_f32 v167, v167, 0x3a000000, v220
	v_cmp_gt_f32_e32 vcc, s43, v167
	v_mul_f32_e32 v169, 0x4f800000, v167
	s_nop 0
	v_cndmask_b32_e32 v167, v167, v169, vcc
	v_sqrt_f32_e32 v169, v167
	s_nop 0
	v_add_u32_e32 v171, -1, v169
	v_fma_f32 v172, -v171, v169, v167
	v_cmp_ge_f32_e64 s[6:7], 0, v172
	v_add_u32_e32 v172, 1, v169
	s_nop 0
	v_cndmask_b32_e64 v171, v169, v171, s[6:7]
	v_fma_f32 v169, -v172, v169, v167
	v_cmp_lt_f32_e64 s[6:7], 0, v169
	s_nop 1
	v_cndmask_b32_e64 v169, v171, v172, s[6:7]
	v_mul_f32_e32 v171, 0x37800000, v169
	v_cndmask_b32_e32 v169, v169, v171, vcc
	v_cmp_class_f32_e32 vcc, v167, v221
	s_nop 1
	v_cndmask_b32_e32 v167, v169, v167, vcc
	v_div_scale_f32 v169, s[6:7], v167, v167, 1.0
	v_rcp_f32_e32 v171, v169
	s_mov_b64 s[6:7], 0
	v_fma_f32 v172, -v169, v171, 1.0
	v_fmac_f32_e32 v171, v172, v171
	v_div_scale_f32 v172, vcc, 1.0, v167, 1.0
	v_mul_f32_e32 v173, v172, v171
	v_fma_f32 v174, -v169, v173, v172
	v_fmac_f32_e32 v173, v174, v171
	v_fma_f32 v169, -v169, v173, v172
	v_div_fmas_f32 v169, v169, v171, v173
	v_div_fixup_f32 v172, v169, v167, 1.0

; template <int NSL>
; __device__ __forceinline__ void phase_samp_fin(KArgs a, float scale, int gw, int NGW, int lane) {
;     ...
;     for (int it = (gw % NWAVES) * (NGW / NWAVES) + gw / NWAVES; it < MSAMP * 8; it += NGW) {
;         const int rl = it >> 3, pn = it & 7, col = pn * 256 + lane * 4;
;         f32x4 p[NSL];
; #pragma unroll
;         for (int s2 = 0; s2 < NSL; ++s2) p[s2] = *(const f32x4*)(PS + ((size_t)s2 * 128 + rl) * DM + col);
;         const size_t off = (size_t)(MPROMPT + rl) * DM + col; f32x4 x = *(const f32x4*)(X + off); f32x4 s = p[0];
.LBB0_2056:
	s_ashr_i32 s12, s2, 3
	s_ashr_i32 s13, s12, 31
	s_and_b32 s18, s2, 7
	s_lshl_b64 s[14:15], s[12:13], 13
	v_lshl_or_b32 v92, s18, 8, v2
	s_add_u32 s14, s16, s14
	s_addc_u32 s15, s17, s15
	v_lshlrev_b32_e32 v0, 2, v92
	v_lshl_add_u64 v[88:89], s[14:15], 0, v[0:1]
	v_add_co_u32_e32 v8, vcc, s45, v88
	s_waitcnt lgkmcnt(0)
	global_load_dwordx4 v[4:7], v0, s[14:15]
	v_addc_co_u32_e32 v9, vcc, 0, v89, vcc
	v_add_co_u32_e32 v12, vcc, s39, v88
	global_load_dwordx4 v[8:11], v[8:9], off
	s_nop 0
	v_addc_co_u32_e32 v13, vcc, 0, v89, vcc
	v_add_co_u32_e32 v16, vcc, s47, v88
	s_mov_b32 s14, 0x900000
	s_nop 0
	v_addc_co_u32_e32 v17, vcc, 0, v89, vcc
	v_add_co_u32_e32 v20, vcc, s77, v88
	global_load_dwordx4 v[12:15], v[12:13], off
	s_nop 0
	v_addc_co_u32_e32 v21, vcc, 0, v89, vcc
	v_add_co_u32_e32 v24, vcc, s35, v88
	global_load_dwordx4 v[16:19], v[16:17], off
	s_nop 0
	v_addc_co_u32_e32 v25, vcc, 0, v89, vcc
	v_add_co_u32_e32 v28, vcc, s74, v88
	global_load_dwordx4 v[20:23], v[20:21], off
	s_nop 0
	v_addc_co_u32_e32 v29, vcc, 0, v89, vcc
	v_add_co_u32_e32 v32, vcc, s66, v88
	global_load_dwordx4 v[24:27], v[24:25], off
	s_nop 0
	v_addc_co_u32_e32 v33, vcc, 0, v89, vcc
	v_add_co_u32_e32 v36, vcc, s37, v88
	global_load_dwordx4 v[28:31], v[28:29], off
	s_nop 0
	v_addc_co_u32_e32 v37, vcc, 0, v89, vcc
	v_add_co_u32_e32 v40, vcc, s14, v88
	s_mov_b32 s14, 0xb00000
	s_nop 0
	v_addc_co_u32_e32 v41, vcc, 0, v89, vcc
	v_add_co_u32_e32 v44, vcc, s97, v88
	global_load_dwordx4 v[32:35], v[32:33], off
	s_nop 0
	v_addc_co_u32_e32 v45, vcc, 0, v89, vcc
	v_add_co_u32_e32 v48, vcc, s14, v88
	s_mov_b32 s14, 0xd00000
	s_nop 0
	v_addc_co_u32_e32 v49, vcc, 0, v89, vcc
	v_add_co_u32_e32 v52, vcc, s56, v88
	global_load_dwordx4 v[36:39], v[36:37], off
	s_nop 0
	v_addc_co_u32_e32 v53, vcc, 0, v89, vcc
	v_add_co_u32_e32 v56, vcc, s14, v88
	s_mov_b32 s14, 0xf00000
	s_nop 0
	v_addc_co_u32_e32 v57, vcc, 0, v89, vcc
	v_add_co_u32_e32 v60, vcc, s57, v88
	global_load_dwordx4 v[40:43], v[40:41], off
	s_nop 0
	v_addc_co_u32_e32 v61, vcc, 0, v89, vcc
	v_add_co_u32_e32 v64, vcc, s14, v88
	s_mov_b32 s14, 0x1000000
	s_nop 0
	v_addc_co_u32_e32 v65, vcc, 0, v89, vcc
	v_add_co_u32_e32 v68, vcc, s14, v88
	s_mov_b32 s14, 0x1100000
	s_nop 0
	v_addc_co_u32_e32 v69, vcc, 0, v89, vcc
	v_add_co_u32_e32 v72, vcc, s14, v88
	global_load_dwordx4 v[44:47], v[44:45], off
	s_nop 0
	v_addc_co_u32_e32 v73, vcc, 0, v89, vcc
	s_mov_b32 s14, 0x1200000
	global_load_dwordx4 v[48:51], v[48:49], off
	v_add_co_u32_e32 v76, vcc, s14, v88
	global_load_dwordx4 v[52:55], v[52:53], off
	s_nop 0
	v_addc_co_u32_e32 v77, vcc, 0, v89, vcc
	s_mov_b32 s14, 0x1300000
	global_load_dwordx4 v[56:59], v[56:57], off
	v_add_co_u32_e32 v80, vcc, s14, v88
	global_load_dwordx4 v[60:63], v[60:61], off
	s_nop 0
	v_addc_co_u32_e32 v81, vcc, 0, v89, vcc
	s_mov_b32 s14, 0x1400000
	global_load_dwordx4 v[64:67], v[64:65], off
	v_add_co_u32_e32 v84, vcc, s14, v88
	global_load_dwordx4 v[68:71], v[68:69], off
	s_nop 0
	v_addc_co_u32_e32 v85, vcc, 0, v89, vcc
	s_mov_b32 s14, 0x1500000
	global_load_dwordx4 v[72:75], v[72:73], off
	v_add_co_u32_e32 v88, vcc, s14, v88
	s_lshl_b64 s[14:15], s[12:13], 11
	global_load_dwordx4 v[76:79], v[76:77], off
	s_add_u32 s14, s14, 0x1000000
	global_load_dwordx4 v[80:83], v[80:81], off
	s_addc_u32 s15, s15, 0
	global_load_dwordx4 v[84:87], v[84:85], off
	v_addc_co_u32_e32 v89, vcc, 0, v89, vcc
	v_or_b32_e32 v96, s14, v92
	v_mov_b32_e32 v97, s15
	global_load_dwordx4 v[88:91], v[88:89], off
	v_lshl_add_u64 v[98:99], v[96:97], 2, s[10:11]
	global_load_dwordx4 v[92:95], v[98:99], off
	s_waitcnt vmcnt(21)
	v_pk_add_f32 v[4:5], v[4:5], v[8:9]
	v_pk_add_f32 v[6:7], v[6:7], v[10:11]
	s_waitcnt vmcnt(20)
	v_pk_add_f32 v[4:5], v[4:5], v[12:13]
	v_pk_add_f32 v[6:7], v[6:7], v[14:15]
	s_waitcnt vmcnt(19)
; __device__ __forceinline__ unsigned cvtpk(float lo, float hi) { unsigned r; asm volatile("v_cvt_pk_bf16_f32 %0, %1, %2" : "=v"(r) : "v"(lo), "v"(hi)); return r; }
; template <int NSL>
; __device__ __forceinline__ void phase_samp_fin(KArgs a, float scale, int gw, int NGW, int lane) {
;     ...
;         const size_t off = (size_t)(MPROMPT + rl) * DM + col; f32x4 x = *(const f32x4*)(X + off); f32x4 s = p[0];
; #pragma unroll
;         for (int s2 = 1; s2 < NSL; ++s2) s = s + p[s2];
;         x = x + s * scale; *(f32x4*)(X + off) = x;
;         u32x2 w; w.x = cvtpk(x[0], x[1]); w.y = cvtpk(x[2], x[3]); *(u32x2*)(XB + off) = w;
;         float ss = (x[0] * x[0] + x[1] * x[1]) + (x[2] * x[2] + x[3] * x[3]);
;         ss += __shfl_xor(ss, 1); ss += __shfl_xor(ss, 2); ss += __shfl_xor(ss, 4); ss += __shfl_xor(ss, 8);
;         if ((lane & 15) == 0) SS[(size_t)(pn * 4 + (lane >> 4)) * MPAD + MPROMPT + rl] = ss;
;     }
	v_pk_add_f32 v[4:5], v[4:5], v[16:17]
	v_pk_add_f32 v[6:7], v[6:7], v[18:19]
	s_waitcnt vmcnt(18)
	v_pk_add_f32 v[4:5], v[4:5], v[20:21]
	v_pk_add_f32 v[6:7], v[6:7], v[22:23]
	s_waitcnt vmcnt(17)
	v_pk_add_f32 v[4:5], v[4:5], v[24:25]
	v_pk_add_f32 v[6:7], v[6:7], v[26:27]
	s_waitcnt vmcnt(16)
	v_pk_add_f32 v[4:5], v[4:5], v[28:29]
	v_pk_add_f32 v[6:7], v[6:7], v[30:31]
	s_waitcnt vmcnt(15)
	v_pk_add_f32 v[4:5], v[4:5], v[32:33]
	v_pk_add_f32 v[6:7], v[6:7], v[34:35]
	s_waitcnt vmcnt(14)
	v_pk_add_f32 v[4:5], v[4:5], v[36:37]
	v_pk_add_f32 v[6:7], v[6:7], v[38:39]
	v_lshl_add_u64 v[10:11], v[96:97], 1, s[8:9]
	s_waitcnt vmcnt(13)
	v_pk_add_f32 v[4:5], v[4:5], v[40:41]
	v_pk_add_f32 v[6:7], v[6:7], v[42:43]
	s_waitcnt vmcnt(12)
	v_pk_add_f32 v[4:5], v[4:5], v[44:45]
	v_pk_add_f32 v[6:7], v[6:7], v[46:47]
	s_waitcnt vmcnt(11)
	v_pk_add_f32 v[4:5], v[4:5], v[48:49]
	v_pk_add_f32 v[6:7], v[6:7], v[50:51]
	s_waitcnt vmcnt(10)
	v_pk_add_f32 v[4:5], v[4:5], v[52:53]
	v_pk_add_f32 v[6:7], v[6:7], v[54:55]
	s_waitcnt vmcnt(9)
	v_pk_add_f32 v[4:5], v[4:5], v[56:57]
	v_pk_add_f32 v[6:7], v[6:7], v[58:59]
	s_waitcnt vmcnt(8)
	v_pk_add_f32 v[4:5], v[4:5], v[60:61]
	v_pk_add_f32 v[6:7], v[6:7], v[62:63]
	s_waitcnt vmcnt(7)
	v_pk_add_f32 v[4:5], v[4:5], v[64:65]
	v_pk_add_f32 v[6:7], v[6:7], v[66:67]
	s_waitcnt vmcnt(6)
	v_pk_add_f32 v[4:5], v[4:5], v[68:69]
	v_pk_add_f32 v[6:7], v[6:7], v[70:71]
	s_waitcnt vmcnt(5)
	v_pk_add_f32 v[4:5], v[4:5], v[72:73]
	v_pk_add_f32 v[6:7], v[6:7], v[74:75]
	s_waitcnt vmcnt(4)
	v_pk_add_f32 v[4:5], v[4:5], v[76:77]
	v_pk_add_f32 v[6:7], v[6:7], v[78:79]
	s_waitcnt vmcnt(3)
	v_pk_add_f32 v[4:5], v[4:5], v[80:81]
	v_pk_add_f32 v[6:7], v[6:7], v[82:83]
	s_waitcnt vmcnt(2)
	v_pk_add_f32 v[4:5], v[4:5], v[84:85]
	v_pk_add_f32 v[6:7], v[6:7], v[86:87]
	s_waitcnt vmcnt(1)
	v_pk_add_f32 v[4:5], v[4:5], v[88:89]
	v_pk_add_f32 v[6:7], v[6:7], v[90:91]
	s_waitcnt vmcnt(0)
	v_pk_fma_f32 v[4:5], v[4:5], 0.5, v[92:93] op_sel_hi:[1,0,1]
	v_pk_fma_f32 v[6:7], v[6:7], 0.5, v[94:95] op_sel_hi:[1,0,1]
	v_mul_f32_e32 v0, v5, v5
	global_store_dwordx4 v[98:99], v[4:7], off
	v_cvt_pk_bf16_f32 v8, v4, v5
	v_fmac_f32_e32 v0, v4, v4
	v_cvt_pk_bf16_f32 v9, v6, v7
	global_store_dwordx2 v[10:11], v[8:9], off
	v_mul_f32_e32 v4, v7, v7
	v_fmac_f32_e32 v4, v6, v6
	v_and_b32_e32 v5, 64, v219
	v_add_f32_e32 v0, v0, v4
	v_xor_b32_e32 v4, 1, v219
	v_add_u32_e32 v5, 64, v5
	v_cmp_lt_i32_e32 vcc, v4, v5
	s_nop 1
	v_cndmask_b32_e32 v4, v219, v4, vcc
	v_lshlrev_b32_e32 v4, 2, v4
	s_nop 1
	v_add_f32_dpp v4, v0, v0 quad_perm:[1,0,3,2] row_mask:0xf bank_mask:0xf
	s_waitcnt lgkmcnt(0)
	v_mov_b32_e32 v0, v4
	v_xor_b32_e32 v4, 2, v219
	v_cmp_lt_i32_e32 vcc, v4, v5
	s_nop 1
	v_cndmask_b32_e32 v4, v219, v4, vcc
	v_lshlrev_b32_e32 v4, 2, v4
	s_nop 1
	v_add_f32_dpp v4, v0, v0 quad_perm:[2,3,0,1] row_mask:0xf bank_mask:0xf
	s_waitcnt lgkmcnt(0)
	v_mov_b32_e32 v0, v4
	v_xor_b32_e32 v4, 4, v219
	v_cmp_lt_i32_e32 vcc, v4, v5
	s_nop 1
	v_cndmask_b32_e32 v4, v219, v4, vcc
	v_lshlrev_b32_e32 v4, 2, v4
	s_nop 1
	v_add_f32_dpp v4, v0, v0 row_half_mirror row_mask:0xf bank_mask:0xf
	s_waitcnt lgkmcnt(0)
	v_mov_b32_e32 v0, v4
	v_xor_b32_e32 v4, 8, v219
	v_cmp_lt_i32_e32 vcc, v4, v5
	s_nop 1
	v_cndmask_b32_e32 v4, v219, v4, vcc
	v_lshlrev_b32_e32 v4, 2, v4
	s_nop 1
	v_add_f32_dpp v4, v0, v0 row_mirror row_mask:0xf bank_mask:0xf
	s_and_saveexec_b64 s[14:15], s[4:5]
	s_cbranch_execz .LBB0_2055
	s_waitcnt lgkmcnt(0)
	v_mov_b32_e32 v6, v4
	v_lshl_or_b32 v0, s18, 2, v3
	v_mul_u32_u24_e32 v0, 0x2100, v0
	v_lshlrev_b32_e32 v0, 2, v0
	v_lshl_add_u64 v[4:5], s[6:7], 0, v[0:1]
	v_lshl_add_u64 v[4:5], s[12:13], 2, v[4:5]
	v_add_co_u32_e32 v4, vcc, 0x8000, v4
	s_nop 1
	v_addc_co_u32_e32 v5, vcc, 0, v5, vcc
	global_store_dword v[4:5], v6, off
	s_branch .LBB0_2055

; __device__ __forceinline__ void phase_final(KArgs a, int gw, int NGW, int lane) {
;     const float* SS = (const float*)(a->ws + WS_SS); const float* g = a->in[I_LNFIN];
;     for (int r = gw; r < MREAL; r += NGW) {
;         float s = lane < 32 ? SS[(size_t)lane * MPAD + r] : 0.f; s = wave_sum(s);
;         const float rs = 1.0f / sqrtf(s * (1.0f / 2048.0f) + RMS_EPS);
;         const float* X = (const float*)(a->ws + WS_X) + (size_t)r * DM; float* o = a->out + OUT_Y + (size_t)r * DM;
; #pragma unroll
;         for (int j = 0; j < 8; ++j) { const int c = j * 256 + lane * 4; const f32x4 v = *(const f32x4*)(X + c), gg = *(const f32x4*)(g + c); *(f32x4*)(o + c) = v * rs * gg; }
;     }
.LBB0_2111:
	s_or_b64 exec, exec, s[2:3]
	v_lshl_add_u64 v[32:33], s[12:13], 0, v[0:1]
	v_add_co_u32_e32 v34, vcc, s16, v32
	s_nop 1
	v_addc_co_u32_e32 v35, vcc, 0, v33, vcc
	v_add_co_u32_e32 v32, vcc, s15, v32
	s_nop 1
	v_addc_co_u32_e32 v33, vcc, 0, v33, vcc
	global_load_dwordx4 v[96:99], v[34:35], off offset:-4096
	global_load_dwordx4 v[100:103], v[2:3], off
	global_load_dwordx4 v[104:107], v[32:33], off offset:1024
	global_load_dwordx4 v[108:111], v[2:3], off offset:1024
	global_load_dwordx4 v[112:115], v[32:33], off offset:2048
	global_load_dwordx4 v[116:119], v[2:3], off offset:2048
	global_load_dwordx4 v[120:123], v[32:33], off offset:3072
	global_load_dwordx4 v[124:127], v[2:3], off offset:3072
	global_load_dwordx4 v[128:131], v[34:35], off
	global_load_dwordx4 v[132:135], v[4:5], off
	global_load_dwordx4 v[136:139], v[34:35], off offset:1024
	global_load_dwordx4 v[140:143], v[6:7], off
	global_load_dwordx4 v[144:147], v[34:35], off offset:2048
	global_load_dwordx4 v[148:151], v[8:9], off
	global_load_dwordx4 v[152:155], v[34:35], off offset:3072
	global_load_dwordx4 v[156:159], v[10:11], off
	s_waitcnt vmcnt(16)
	s_nop 1
	v_add_f32_dpp v23, v22, v22 quad_perm:[1,0,3,2] row_mask:0xf bank_mask:0xf
	v_lshl_add_u64 v[36:37], s[6:7], 0, v[0:1]
	s_waitcnt lgkmcnt(0)
	v_mov_b32_e32 v22, v23
	s_nop 1
	v_add_f32_dpp v23, v22, v22 quad_perm:[2,3,0,1] row_mask:0xf bank_mask:0xf
	s_add_i32 s8, s8, s26
	s_add_u32 s6, s6, s10
	s_addc_u32 s7, s7, s11
	s_add_u32 s12, s12, s10
	s_waitcnt lgkmcnt(0)
	v_mov_b32_e32 v22, v23
	s_nop 1
	v_add_f32_dpp v23, v22, v22 row_half_mirror row_mask:0xf bank_mask:0xf
	s_addc_u32 s13, s13, s11
	s_cmpk_lt_i32 s8, 0x2080
	v_lshl_add_u64 v[12:13], v[12:13], 0, s[4:5]
	s_waitcnt lgkmcnt(0)
	v_mov_b32_e32 v22, v23
	s_nop 1
	v_add_f32_dpp v23, v22, v22 row_mirror row_mask:0xf bank_mask:0xf
	s_waitcnt lgkmcnt(0)
	v_mov_b32_e32 v22, v23
	v_mov_b32_e32 v23, v22
	v_mov_b32_e32 v60, v22
	s_nop 1
	v_permlane16_swap_b32_e32 v23, v60
	s_waitcnt lgkmcnt(0)
	v_add_f32_e32 v22, v23, v60
	v_mov_b32_e32 v23, v22
	v_mov_b32_e32 v60, v22
	s_nop 1
	v_permlane32_swap_b32_e32 v23, v60
	s_waitcnt lgkmcnt(0)
	v_add_f32_e32 v22, v23, v60
	v_fmamk_f32 v22, v22, 0x3a000000, v20
	v_mul_f32_e32 v23, 0x4f800000, v22
	v_cmp_gt_f32_e32 vcc, s9, v22
	s_nop 1
	v_cndmask_b32_e32 v22, v22, v23, vcc
	v_sqrt_f32_e32 v23, v22
	s_nop 0
	v_add_u32_e32 v38, -1, v23
	v_add_u32_e32 v39, 1, v23
	v_fma_f32 v40, -v38, v23, v22
	v_fma_f32 v41, -v39, v23, v22
	v_cmp_ge_f32_e64 s[2:3], 0, v40
	s_nop 1
	v_cndmask_b32_e64 v23, v23, v38, s[2:3]
	v_cmp_lt_f32_e64 s[2:3], 0, v41
	s_nop 1
	v_cndmask_b32_e64 v23, v23, v39, s[2:3]
	v_mul_f32_e32 v38, 0x37800000, v23
	v_cndmask_b32_e32 v23, v23, v38, vcc
	v_cmp_class_f32_e32 vcc, v22, v21
	s_nop 1
	v_cndmask_b32_e32 v22, v23, v22, vcc
	v_div_scale_f32 v23, s[2:3], v22, v22, 1.0
	v_rcp_f32_e32 v38, v23
	s_nop 0
	v_fma_f32 v40, -v23, v38, 1.0
	v_div_scale_f32 v39, vcc, 1.0, v22, 1.0
	v_fmac_f32_e32 v38, v40, v38
	v_mul_f32_e32 v40, v39, v38
	v_fma_f32 v41, -v23, v40, v39
	v_fmac_f32_e32 v40, v41, v38
	v_fma_f32 v23, -v23, v40, v39
	v_div_fmas_f32 v23, v23, v38, v40
	v_div_fixup_f32 v38, v23, v22, 1.0
	v_add_co_u32_e32 v30, vcc, s14, v36
	s_nop 1
	v_addc_co_u32_e32 v31, vcc, 0, v37, vcc
	s_waitcnt vmcnt(14)
	v_pk_mul_f32 v[22:23], v[96:97], v[38:39] op_sel_hi:[1,0]
	v_pk_mul_f32 v[24:25], v[98:99], v[38:39] op_sel_hi:[1,0]
	v_pk_mul_f32 v[22:23], v[100:101], v[22:23]
	v_pk_mul_f32 v[24:25], v[102:103], v[24:25]
	global_store_dwordx4 v[36:37], v[22:25], off
	s_waitcnt vmcnt(13)
	v_pk_mul_f32 v[26:27], v[104:105], v[38:39] op_sel_hi:[1,0]
	v_pk_mul_f32 v[28:29], v[106:107], v[38:39] op_sel_hi:[1,0]
	v_pk_mul_f32 v[26:27], v[108:109], v[26:27]
	v_pk_mul_f32 v[28:29], v[110:111], v[28:29]
	global_store_dwordx4 v[36:37], v[26:29], off offset:1024
	s_waitcnt vmcnt(12)
	v_pk_mul_f32 v[22:23], v[112:113], v[38:39] op_sel_hi:[1,0]
	v_pk_mul_f32 v[24:25], v[114:115], v[38:39] op_sel_hi:[1,0]
	v_pk_mul_f32 v[22:23], v[116:117], v[22:23]
	v_pk_mul_f32 v[24:25], v[118:119], v[24:25]
	global_store_dwordx4 v[36:37], v[22:25], off offset:2048
	s_waitcnt vmcnt(11)
	v_pk_mul_f32 v[26:27], v[120:121], v[38:39] op_sel_hi:[1,0]
	v_pk_mul_f32 v[28:29], v[122:123], v[38:39] op_sel_hi:[1,0]
	v_pk_mul_f32 v[26:27], v[124:125], v[26:27]
	v_pk_mul_f32 v[28:29], v[126:127], v[28:29]
	global_store_dwordx4 v[36:37], v[26:29], off offset:3072
	s_waitcnt vmcnt(10)
	v_pk_mul_f32 v[22:23], v[128:129], v[38:39] op_sel_hi:[1,0]
	v_pk_mul_f32 v[24:25], v[130:131], v[38:39] op_sel_hi:[1,0]
	v_pk_mul_f32 v[22:23], v[132:133], v[22:23]
	v_pk_mul_f32 v[24:25], v[134:135], v[24:25]
	global_store_dwordx4 v[30:31], v[22:25], off
	s_waitcnt vmcnt(9)
	v_pk_mul_f32 v[26:27], v[136:137], v[38:39] op_sel_hi:[1,0]
	v_pk_mul_f32 v[28:29], v[138:139], v[38:39] op_sel_hi:[1,0]
	v_pk_mul_f32 v[26:27], v[140:141], v[26:27]
	v_pk_mul_f32 v[28:29], v[142:143], v[28:29]
	global_store_dwordx4 v[30:31], v[26:29], off offset:1024
	s_waitcnt vmcnt(8)
	v_pk_mul_f32 v[22:23], v[144:145], v[38:39] op_sel_hi:[1,0]
	v_pk_mul_f32 v[24:25], v[146:147], v[38:39] op_sel_hi:[1,0]
	v_pk_mul_f32 v[22:23], v[148:149], v[22:23]
	v_pk_mul_f32 v[24:25], v[150:151], v[24:25]
	global_store_dwordx4 v[30:31], v[22:25], off offset:2048
	s_waitcnt vmcnt(7)
	v_pk_mul_f32 v[26:27], v[152:153], v[38:39] op_sel_hi:[1,0]
	v_pk_mul_f32 v[28:29], v[154:155], v[38:39] op_sel_hi:[1,0]
	v_pk_mul_f32 v[26:27], v[156:157], v[26:27]
	v_pk_mul_f32 v[28:29], v[158:159], v[28:29]
	global_store_dwordx4 v[30:31], v[26:29], off offset:3072
	s_cbranch_scc0 .LBB0_2114
